# GEMM mainloops: hipcc per-cluster s_setprio flips removed, one static s_setprio 1 for waves 4-7 at the stagger barrier, reset at grid barriers
# speedup vs baseline: 1.0429x; 1.0106x over previous
; __global__ void __launch_bounds__(NTHR, 2) fwd_kernel(Params p) {
;     ...
;     cg::grid_group grid = cg::this_grid();
.LBB0_156:
	v_lshrrev_b32_e32 v2, 20, v0
	v_lshrrev_b32_e32 v0, 10, v0
	s_waitcnt lgkmcnt(0)
	s_barrier
	s_setprio 0
	s_waitcnt vmcnt(0) lgkmcnt(0)
	v_or_b32_e32 v0, v0, v2
	s_movk_i32 s0, 0x3ff
	v_and_or_b32 v0, v0, s0, v1
	v_cmp_eq_u32_e32 vcc, 0, v0
	s_barrier
	s_and_saveexec_b64 s[0:1], vcc
	s_cbranch_execz .LBB0_166
	buffer_wbl2 sc1
	s_waitcnt vmcnt(0)
	s_load_dwordx2 s[2:3], s[4:5], 0x58
	v_mov_b32_e32 v2, 0
	s_mov_b64 s[6:7], exec
	v_mbcnt_lo_u32_b32 v1, s6, 0
	v_mbcnt_hi_u32_b32 v1, s7, v1
	s_waitcnt lgkmcnt(0)
	global_load_dword v0, v2, s[2:3] offset:40
	v_cmp_eq_u32_e32 vcc, 0, v1
	s_and_saveexec_b64 s[4:5], vcc
	s_cbranch_execz .LBB0_159
	s_bcnt1_i32_b64 s6, s[6:7]
	v_mov_b32_e32 v3, s6
	global_atomic_add v3, v2, v3, s[2:3] offset:32 sc0

; __device__ __forceinline__ int otid(int wv) { int t = (wv << 6) | (int)__builtin_amdgcn_mbcnt_hi(~0u, __builtin_amdgcn_mbcnt_lo(~0u, 0u)); asm volatile("" : "+v"(t)); return t; }
; __device__ __forceinline__ void grid_bar(unsigned* ctr, unsigned& target, int G, int wv) {
;     asm volatile("s_waitcnt vmcnt(0) lgkmcnt(0)" ::: "memory");
;     __syncthreads();
;     target = (unsigned)__builtin_amdgcn_readfirstlane((int)(target + (unsigned)G));
;     if (otid(wv) == 0) {
;         __builtin_amdgcn_fence(__ATOMIC_RELEASE, "agent");
;         asm volatile("s_waitcnt vmcnt(0)" ::: "memory");
;         __hip_atomic_fetch_add(ctr, 1u, __ATOMIC_RELAXED, __HIP_MEMORY_SCOPE_AGENT);
;         while (__hip_atomic_load(ctr, __ATOMIC_RELAXED, __HIP_MEMORY_SCOPE_AGENT) < target) __builtin_amdgcn_s_sleep(1);
;         __builtin_amdgcn_fence(__ATOMIC_ACQUIRE, "agent");
;         asm volatile("s_waitcnt vmcnt(0)" ::: "memory");
;     }
;     __syncthreads();
; }
.LBB0_177:
	s_or_b64 exec, exec, s[10:11]
	v_readlane_b32 s0, v254, 18
	v_readlane_b32 s1, v254, 19
	s_add_u32 s0, s0, 0x3d100000
	s_addc_u32 s1, s1, 0
	s_barrier
	s_setprio 0
	s_waitcnt vmcnt(0) lgkmcnt(0)
	v_writelane_b32 v254, s0, 30
	v_mov_b32_e32 v0, v236
	s_nop 0
	v_writelane_b32 v254, s1, 31
	s_barrier
	s_nop 0
	v_cmp_eq_u32_e32 vcc, 0, v0
	s_and_saveexec_b64 s[0:1], vcc
	s_cbranch_execz .LBB0_183
	s_mov_b64 s[2:3], exec
	buffer_wbl2 sc1
	s_waitcnt vmcnt(0)
	v_mbcnt_lo_u32_b32 v0, s2, 0
	v_mbcnt_hi_u32_b32 v0, s3, v0
	v_cmp_eq_u32_e32 vcc, 0, v0
	s_and_saveexec_b64 s[4:5], vcc
	s_cbranch_execz .LBB0_180
	s_bcnt1_i32_b64 s2, s[2:3]
	v_mov_b32_e32 v1, s2
	v_readlane_b32 s2, v254, 30
	v_mov_b32_e32 v0, 0
	v_readlane_b32 s3, v254, 31
	s_nop 4
	global_atomic_add v0, v1, s[2:3]

; __device__ __forceinline__ int otid(int wv) { int t = (wv << 6) | (int)__builtin_amdgcn_mbcnt_hi(~0u, __builtin_amdgcn_mbcnt_lo(~0u, 0u)); asm volatile("" : "+v"(t)); return t; }
;     __device__ bool next(int i, Unit& u) const { return map((long)i * G + c, u); }
; #define PG8_WAIT_V(n) asm volatile("s_waitcnt vmcnt(" #n ")" ::: "memory")
; #define PG8_BAR __builtin_amdgcn_s_barrier()
; template <class Epi, class Sched, bool AREMAP>
; __device__ __forceinline__ void gemm_phase(LAS unsigned char* lds, const Gemm g, const Sched& S, const Epi& E, int wv) {
;     const int tid = otid(wv), wid = __builtin_amdgcn_readfirstlane(tid >> 6), lane = tid & 63, wr = wid >> 2, wc = wid & 3, fr = lane & 15, fq = lane >> 4;
;     const int K = g.K, nt = K / BK;
;     unsigned voffA[2], voffB[2];
; #pragma unroll
;     for (int i = 0; i < 2; ++i) { int R, C; stage_rc(tid * 16 + i * 8192, R, C); const int Rb = Epi::PERM ? ((R & ~31) + perm32(R & 31)) : R;
;         const int Ra = AREMAP ? ((R >> 6) * 128 + (R & 63)) : R;
;         voffA[i] = (unsigned)(Ra * g.lda + C) * 2u; voffB[i] = (unsigned)(Rb * g.ldb + C) * 2u; }
;     const size_t kstep = (size_t)(BK * 2);
;     const size_t hstepA = (size_t)(AREMAP ? 64 : HALF) * g.lda * 2, hstepB = (size_t)HALF * g.ldb * 2;
;     const size_t tstepA = (size_t)BM * g.lda * 2, tstepB = (size_t)BM * g.ldb * 2;
;     const unsigned ldsw = (unsigned)wid * 1024u;
;     const int aoff = lds_byte(wr * 64 + fr, fq * 8), boff = lds_byte(wc * 32 + fr, fq * 8);
;     ...
;     Unit cur, nxt; int ui = 0;
;     if (!S.next(0, cur)) return;
;     f32x4 acc[2][2][4][2];
; #pragma unroll
;     for (int a = 0; a < 2; ++a)
; #pragma unroll
;         for (int b = 0; b < 2; ++b)
; #pragma unroll
;             for (int m = 0; m < 4; ++m)
; #pragma unroll
;                 for (int n = 0; n < 2; ++n) acc[a][b][m][n] = (f32x4){0.f, 0.f, 0.f, 0.f};
;     bf16x8 At[4][2], B0[2][2], B1[2][2];
;     ...
;     const char* cA = PG8_UA(cur); const char* cB = PG8_UB(cur);
;     PG8_STAGE(PG8_SB(0, 0), cB, voffB); PG8_STAGE(PG8_SA(0, 0), cA, voffA); PG8_STAGE(PG8_SB(0, 1), cB + hstepB, voffB); PG8_STAGE(PG8_SA(0, 1), cA + hstepA, voffA);
;     if (wr == 1) PG8_BAR;
;     PG8_WAIT_V(4); PG8_BAR;
;     PG8_STAGE(PG8_SB(1, 0), cB + kstep, voffB); PG8_STAGE(PG8_SA(1, 0), cA + kstep, voffA); PG8_STAGE(PG8_SB(1, 1), cB + hstepB + kstep, voffB);
;     PG8_WAIT_V(6); PG8_BAR;
.LBB0_192:
	v_ashrrev_i32_e32 v2, 31, v10
	v_lshrrev_b32_e32 v2, 26, v2
	v_add_u32_e32 v2, v10, v2
	v_ashrrev_i32_e32 v11, 6, v2
	v_bfe_i32 v2, v10, 27, 1
	v_lshlrev_b32_e32 v1, 4, v10
	v_lshrrev_b32_e32 v2, 22, v2
	v_add_u32_e32 v2, v1, v2
	v_and_b32_e32 v2, 0xfffffc00, v2
	v_sub_u32_e32 v2, v1, v2
	v_lshrrev_b32_e32 v3, 4, v2
	v_bitop3_b32 v3, v3, v2, 32 bitop3:0x6c
	v_ashrrev_i32_e32 v2, 31, v2
	v_lshrrev_b32_e32 v2, 26, v2
	v_add_u32_e32 v2, v3, v2
	v_ashrrev_i32_e32 v12, 6, v2
	v_lshlrev_b32_e32 v4, 3, v11
	v_mul_i32_i24_e32 v5, 64, v12
	v_and_b32_e32 v4, -16, v4
	v_sub_u32_e32 v3, v3, v5
	v_add_u32_e32 v2, v12, v4
	v_lshlrev_b32_e32 v4, 5, v11
	v_ashrrev_i16_sdwa v3, v240, sext(v3) dst_sel:DWORD dst_unused:UNUSED_PAD src0_sel:DWORD src1_sel:BYTE_0
	v_and_b32_e32 v4, 32, v4
	v_bfe_i32 v13, v3, 0, 16
	v_and_b32_e32 v6, 3, v12
	s_mov_b32 s5, 0xfffe0
	v_add_lshl_u32 v4, v4, v13, 1
	v_add_u32_e32 v1, 0x2000, v1
	v_lshlrev_b32_e32 v3, 1, v2
	v_lshrrev_b32_e32 v5, 2, v2
	v_and_or_b32 v6, v2, s5, v6
	v_lshl_add_u32 v130, v2, 12, v4
	v_ashrrev_i32_e32 v2, 31, v1
	v_lshrrev_b32_e32 v2, 22, v2
	v_add_u32_e32 v2, v1, v2
	v_ashrrev_i32_e32 v14, 10, v2
	v_mul_i32_i24_e32 v2, 0x400, v14
	v_sub_u32_e32 v1, v1, v2
	v_and_b32_e32 v3, 24, v3
	v_and_b32_e32 v5, 4, v5
	v_lshrrev_b32_e32 v2, 4, v1
	v_or3_b32 v3, v6, v5, v3
	v_bitop3_b32 v1, v2, v1, 32 bitop3:0x6c
	s_add_u32 s27, s2, 0x8e00000
	v_lshl_add_u32 v132, v3, 12, v4
	v_ashrrev_i32_e32 v3, 31, v1
	s_addc_u32 s28, s3, 0
	v_lshrrev_b32_e32 v3, 26, v3
	s_add_i32 s0, s4, s0
	v_lshlrev_b32_e32 v2, 3, v14
	v_add_u32_e32 v3, v1, v3
	s_ashr_i32 s4, s0, 31
	v_and_b32_e32 v2, -16, v2
	v_ashrrev_i32_e32 v15, 6, v3
	s_lshr_b32 s4, s4, 25
	v_add_u32_e32 v2, v15, v2
	v_and_b32_e32 v5, 3, v15
	s_add_i32 s4, s0, s4
	v_and_or_b32 v5, v2, s5, v5
	s_ashr_i32 s5, s4, 7
	s_and_b32 s4, s4, 0xff80
	s_sub_i32 s4, s0, s4
	s_bfe_i32 s0, s4, 0x80000
	s_bfe_u32 s0, s0, 0x2000d
	s_add_i32 s6, s4, s0
	s_bfe_i32 s0, s6, 0x80000
	s_and_b32 s6, s6, 0xfc
	s_sub_i32 s4, s4, s6
	s_lshl_b32 s5, s5, 2
	s_sext_i32_i16 s0, s0
	s_sext_i32_i8 s4, s4
	s_ashr_i32 s1, s25, 6
	s_lshr_b32 s0, s0, 2
	s_add_i32 s6, s5, s4
	v_and_b32_e32 v3, 0xc0, v3
	s_ashr_i32 s7, s6, 31
	s_bfe_i64 s[10:11], s[0:1], 0x100000
	v_sub_u32_e32 v1, v1, v3
	s_ashr_i32 s8, s25, 8
	s_lshl_b32 s29, s1, 10
	s_lshl_b64 s[4:5], s[6:7], 20
	s_lshl_b64 s[10:11], s[10:11], 20
	v_ashrrev_i16_sdwa v1, v240, sext(v1) dst_sel:DWORD dst_unused:UNUSED_PAD src0_sel:DWORD src1_sel:BYTE_0
	s_add_u32 s16, s2, s10
	v_lshlrev_b32_e32 v4, 5, v14
	v_bfe_i32 v16, v1, 0, 16
	v_lshlrev_b32_e32 v1, 1, v2
	v_lshrrev_b32_e32 v3, 2, v2
	s_addc_u32 s17, s3, s11
	s_add_i32 s7, s29, 0
	v_and_b32_e32 v4, 32, v4
	v_and_b32_e32 v1, 24, v1
	v_and_b32_e32 v3, 4, v3
	s_add_i32 m0, s7, 0x10000
	v_or3_b32 v1, v5, v3, v1
	v_add_lshl_u32 v3, v4, v16, 1
	global_load_lds_dwordx4 v132, s[16:17]
	s_add_i32 m0, s7, 0x12000
	v_lshl_add_u32 v136, v1, 12, v3
	s_add_u32 s18, s27, s4
	global_load_lds_dwordx4 v136, s[16:17]
	s_addc_u32 s19, s28, s5
	s_mov_b32 m0, s7
	s_add_i32 s30, s7, 0x2000
	v_lshl_add_u32 v134, v2, 12, v3
	global_load_lds_dwordx4 v130, s[18:19]
	s_mov_b32 m0, s30
	s_add_u32 s4, s16, 0x80000
	global_load_lds_dwordx4 v134, s[18:19]
	s_addc_u32 s5, s17, 0
	s_add_i32 m0, s7, 0x14000
	v_mov_b32_e32 v133, v0
	global_load_lds_dwordx4 v132, s[4:5]
	s_add_i32 m0, s7, 0x16000
	v_mov_b32_e32 v137, v0
	global_load_lds_dwordx4 v136, s[4:5]
	s_add_u32 s4, s18, 0x80000
	s_addc_u32 s5, s19, 0
	s_add_i32 s31, s7, 0x4000
	s_mov_b32 m0, s31
	s_add_i32 s34, s7, 0x6000
	global_load_lds_dwordx4 v130, s[4:5]
	s_mov_b32 m0, s34
	v_mov_b32_e32 v131, v0
	global_load_lds_dwordx4 v134, s[4:5]
	v_mov_b32_e32 v135, v0
	v_lshl_add_u64 v[8:9], s[16:17], 0, v[132:133]
	v_lshl_add_u64 v[6:7], s[16:17], 0, v[136:137]
	v_lshl_add_u64 v[4:5], s[18:19], 0, v[130:131]
	s_cmp_lg_u32 s8, 1
	v_lshl_add_u64 v[2:3], s[18:19], 0, v[134:135]
	s_cbranch_scc1 .LBB0_194
	s_barrier
	s_setprio 1

; #define PG8_STAGE(bufoff, gbase, voff) do { _Pragma("unroll") for (int _i = 0; _i < 2; ++_i) \
;         __builtin_amdgcn_global_load_lds((const unsigned*)((const char*)(gbase) + (voff)[_i]), (LAS unsigned*)(lds + (bufoff) + ldsw + _i * 8192), 16, 0, 0); } while (0)
; #define PG8_LDA(dst, b, h) do { _Pragma("unroll") for (int m = 0; m < 4; ++m) _Pragma("unroll") for (int k = 0; k < 2; ++k) dst[m][k] = *(const LAS bf16x8*)(lds + PG8_SA(b, h) + aoff + m * 2048 + k * 1024); } while (0)
; #define PG8_LDB(dst, b, h) do { _Pragma("unroll") for (int n = 0; n < 2; ++n) _Pragma("unroll") for (int k = 0; k < 2; ++k) dst[n][k] = *(const LAS bf16x8*)(lds + PG8_SB(b, h) + boff + n * 2048 + k * 1024); } while (0)
; #define PG8_MMA(ai, bj, At, Bt) do { __builtin_amdgcn_s_setprio(1); _Pragma("unroll") for (int m = 0; m < 4; ++m) _Pragma("unroll") for (int n = 0; n < 2; ++n) _Pragma("unroll") for (int k = 0; k < 2; ++k) \
;         acc[ai][bj][m][n] = __builtin_amdgcn_mfma_f32_16x16x32_bf16(Bt[n][k], At[m][k], acc[ai][bj][m][n], 0, 0, 0); __builtin_amdgcn_s_setprio(0); } while (0)
; #define PG8_WAIT_V(n) asm volatile("s_waitcnt vmcnt(" #n ")" ::: "memory")
; #define PG8_WAIT_L(n) asm volatile("s_waitcnt lgkmcnt(" #n ")" ::: "memory")
; #define PG8_BAR __builtin_amdgcn_s_barrier()
; #define PG8_SCHED __builtin_amdgcn_sched_barrier(0)
; template <class Epi, class Sched, bool AREMAP>
; __device__ __forceinline__ void gemm_phase(LAS unsigned char* lds, const Gemm g, const Sched& S, const Epi& E, int wv) {
;     ...
;             PG8_LDB(B0, 0, 0); PG8_SCHED; PG8_LDA(At, 0, 0); PG8_STAGE(PG8_SA(1, 1), a1 + hstepA, voffA);
;             PG8_WAIT_L(8); PG8_BAR; PG8_WAIT_L(0); PG8_MMA(0, 0, At, B0); PG8_BAR; PG8_SCHED;
;             PG8_LDB(B1, 0, 1); PG8_STAGE(PG8_SB(0, 0), b2, voffB);
;             PG8_BAR; PG8_WAIT_L(0); PG8_MMA(0, 1, At, B1); PG8_BAR;
;             PG8_LDA(At, 0, 1); PG8_STAGE(PG8_SA(0, 0), a2, voffA);
;             PG8_BAR; PG8_WAIT_L(0); PG8_MMA(1, 0, At, B0); PG8_BAR; PG8_SCHED;
;             PG8_STAGE(PG8_SB(0, 1), b2 + hstepB, voffB);
;             PG8_WAIT_V(6); PG8_BAR; PG8_MMA(1, 1, At, B1); PG8_BAR;
.LBB0_202:
	s_add_u32 s18, s16, 0xfff80080
	s_addc_u32 s19, s17, -1
	s_add_i32 s38, 0, 0x10000
	v_add_u32_e32 v145, s38, v142
	ds_read_b128 v[146:149], v145
	ds_read_b128 v[150:153], v145 offset:1024
	ds_read_b128 v[154:157], v145 offset:2048
	ds_read_b128 v[158:161], v145 offset:3072
	s_cmp_eq_u32 s56, 28
	s_cselect_b32 s21, s11, s19
	s_cselect_b32 s20, s47, s18
	s_cselect_b32 s19, s9, s55
	s_cselect_b32 s18, s52, s53
	v_lshl_add_u64 v[186:187], s[16:17], 0, v[140:141]
	s_add_i32 m0, s7, 0xc000
	ds_read_b128 v[162:165], v144
	ds_read_b128 v[166:169], v144 offset:1024
	ds_read_b128 v[170:173], v144 offset:2048
	ds_read_b128 v[174:177], v144 offset:3072
	ds_read_b128 v[178:181], v144 offset:4096
	ds_read_b128 v[182:185], v144 offset:5120
	ds_read_b128 v[196:199], v144 offset:6144
	ds_read_b128 v[200:203], v144 offset:7168
	global_load_lds_dwordx4 v[186:187], off
	v_lshl_add_u64 v[186:187], s[16:17], 0, v[138:139]
	s_add_i32 m0, s7, 0xe000
	s_nop 0
	global_load_lds_dwordx4 v[186:187], off
	s_waitcnt lgkmcnt(8)
	s_barrier
	s_waitcnt lgkmcnt(0)
	s_waitcnt lgkmcnt(0)
	v_mfma_f32_16x16x32_bf16 v[126:129], v[146:149], v[162:165], v[126:129]
	v_mfma_f32_16x16x32_bf16 v[122:125], v[154:157], v[162:165], v[122:125]
	v_mfma_f32_16x16x32_bf16 v[118:121], v[146:149], v[170:173], v[118:121]
	v_mfma_f32_16x16x32_bf16 v[114:117], v[154:157], v[170:173], v[114:117]
	v_mfma_f32_16x16x32_bf16 v[102:105], v[146:149], v[178:181], v[102:105]
	v_mfma_f32_16x16x32_bf16 v[98:101], v[154:157], v[178:181], v[98:101]
	v_mfma_f32_16x16x32_bf16 v[86:89], v[146:149], v[196:199], v[86:89]
	v_mfma_f32_16x16x32_bf16 v[82:85], v[154:157], v[196:199], v[82:85]
	v_mfma_f32_16x16x32_bf16 v[126:129], v[150:153], v[166:169], v[126:129]
	v_mfma_f32_16x16x32_bf16 v[122:125], v[158:161], v[166:169], v[122:125]
	v_mfma_f32_16x16x32_bf16 v[118:121], v[150:153], v[174:177], v[118:121]
	v_mfma_f32_16x16x32_bf16 v[114:117], v[158:161], v[174:177], v[114:117]
	v_mfma_f32_16x16x32_bf16 v[102:105], v[150:153], v[182:185], v[102:105]
	v_mfma_f32_16x16x32_bf16 v[98:101], v[158:161], v[182:185], v[98:101]
	v_mfma_f32_16x16x32_bf16 v[86:89], v[150:153], v[200:203], v[86:89]
	v_mfma_f32_16x16x32_bf16 v[82:85], v[158:161], v[200:203], v[82:85]
	s_barrier
	s_add_i32 s39, 0, 0x14000
	s_add_i32 s38, s38, s29
	v_add_u32_e32 v145, s39, v142
	v_lshl_add_u64 v[186:187], s[18:19], 0, v[132:133]
	s_mov_b32 m0, s38
	ds_read_b128 v[204:207], v145
	ds_read_b128 v[208:211], v145 offset:1024
	ds_read_b128 v[212:215], v145 offset:2048
	ds_read_b128 v[216:219], v145 offset:3072
	global_load_lds_dwordx4 v[186:187], off
	v_lshl_add_u64 v[192:193], s[18:19], 0, v[136:137]
	s_add_i32 m0, s38, 0x2000
	s_nop 0
	global_load_lds_dwordx4 v[192:193], off
	s_barrier
	s_waitcnt lgkmcnt(0)
	s_waitcnt lgkmcnt(0)
	v_mfma_f32_16x16x32_bf16 v[110:113], v[204:207], v[162:165], v[110:113]
	v_mfma_f32_16x16x32_bf16 v[106:109], v[212:215], v[162:165], v[106:109]
	v_mfma_f32_16x16x32_bf16 v[94:97], v[204:207], v[170:173], v[94:97]
	v_mfma_f32_16x16x32_bf16 v[90:93], v[212:215], v[170:173], v[90:93]
	v_mfma_f32_16x16x32_bf16 v[78:81], v[204:207], v[178:181], v[78:81]
	v_mfma_f32_16x16x32_bf16 v[74:77], v[212:215], v[178:181], v[74:77]
	v_mfma_f32_16x16x32_bf16 v[70:73], v[204:207], v[196:199], v[70:73]
	v_mfma_f32_16x16x32_bf16 v[66:69], v[212:215], v[196:199], v[66:69]
	v_mfma_f32_16x16x32_bf16 v[110:113], v[208:211], v[166:169], v[110:113]
	v_mfma_f32_16x16x32_bf16 v[106:109], v[216:219], v[166:169], v[106:109]
	v_mfma_f32_16x16x32_bf16 v[94:97], v[208:211], v[174:177], v[94:97]
	v_mfma_f32_16x16x32_bf16 v[90:93], v[216:219], v[174:177], v[90:93]
	v_mfma_f32_16x16x32_bf16 v[78:81], v[208:211], v[182:185], v[78:81]
	v_mfma_f32_16x16x32_bf16 v[74:77], v[216:219], v[182:185], v[74:77]
	v_mfma_f32_16x16x32_bf16 v[70:73], v[208:211], v[200:203], v[70:73]
	v_mfma_f32_16x16x32_bf16 v[66:69], v[216:219], v[200:203], v[66:69]
	s_mov_b32 m0, s7
	v_lshl_add_u64 v[194:195], s[20:21], 0, v[130:131]
	s_barrier
	ds_read_b128 v[162:165], v144 offset:16384
	ds_read_b128 v[166:169], v144 offset:17408
	ds_read_b128 v[170:173], v144 offset:18432
	ds_read_b128 v[174:177], v144 offset:19456
	ds_read_b128 v[178:181], v144 offset:20480
	ds_read_b128 v[182:185], v144 offset:21504
	ds_read_b128 v[196:199], v144 offset:22528
	ds_read_b128 v[200:203], v144 offset:23552
	global_load_lds_dwordx4 v[194:195], off
	v_lshl_add_u64 v[220:221], s[20:21], 0, v[134:135]
	s_mov_b32 m0, s30
	s_nop 0
	global_load_lds_dwordx4 v[220:221], off
	s_barrier
	s_waitcnt lgkmcnt(0)
	s_waitcnt lgkmcnt(0)
	v_mfma_f32_16x16x32_bf16 v[62:65], v[146:149], v[162:165], v[62:65]
	v_mfma_f32_16x16x32_bf16 v[58:61], v[154:157], v[162:165], v[58:61]
	v_mfma_f32_16x16x32_bf16 v[54:57], v[146:149], v[170:173], v[54:57]
	v_mfma_f32_16x16x32_bf16 v[50:53], v[154:157], v[170:173], v[50:53]
	v_mfma_f32_16x16x32_bf16 v[38:41], v[146:149], v[178:181], v[38:41]
	v_mfma_f32_16x16x32_bf16 v[34:37], v[154:157], v[178:181], v[34:37]
	v_mfma_f32_16x16x32_bf16 v[22:25], v[146:149], v[196:199], v[22:25]
	v_mfma_f32_16x16x32_bf16 v[18:21], v[154:157], v[196:199], v[18:21]
	v_mfma_f32_16x16x32_bf16 v[62:65], v[150:153], v[166:169], v[62:65]
	v_mfma_f32_16x16x32_bf16 v[58:61], v[158:161], v[166:169], v[58:61]
	v_mfma_f32_16x16x32_bf16 v[54:57], v[150:153], v[174:177], v[54:57]
	v_mfma_f32_16x16x32_bf16 v[50:53], v[158:161], v[174:177], v[50:53]
	v_mfma_f32_16x16x32_bf16 v[38:41], v[150:153], v[182:185], v[38:41]
	v_mfma_f32_16x16x32_bf16 v[34:37], v[158:161], v[182:185], v[34:37]
	v_mfma_f32_16x16x32_bf16 v[22:25], v[150:153], v[200:203], v[22:25]
	v_mfma_f32_16x16x32_bf16 v[18:21], v[158:161], v[200:203], v[18:21]
	s_barrier
; #define PG8_STAGE(bufoff, gbase, voff) do { _Pragma("unroll") for (int _i = 0; _i < 2; ++_i) \
;         __builtin_amdgcn_global_load_lds((const unsigned*)((const char*)(gbase) + (voff)[_i]), (LAS unsigned*)(lds + (bufoff) + ldsw + _i * 8192), 16, 0, 0); } while (0)
; #define PG8_LDA(dst, b, h) do { _Pragma("unroll") for (int m = 0; m < 4; ++m) _Pragma("unroll") for (int k = 0; k < 2; ++k) dst[m][k] = *(const LAS bf16x8*)(lds + PG8_SA(b, h) + aoff + m * 2048 + k * 1024); } while (0)
; #define PG8_LDB(dst, b, h) do { _Pragma("unroll") for (int n = 0; n < 2; ++n) _Pragma("unroll") for (int k = 0; k < 2; ++k) dst[n][k] = *(const LAS bf16x8*)(lds + PG8_SB(b, h) + boff + n * 2048 + k * 1024); } while (0)
; #define PG8_MMA(ai, bj, At, Bt) do { __builtin_amdgcn_s_setprio(1); _Pragma("unroll") for (int m = 0; m < 4; ++m) _Pragma("unroll") for (int n = 0; n < 2; ++n) _Pragma("unroll") for (int k = 0; k < 2; ++k) \
;         acc[ai][bj][m][n] = __builtin_amdgcn_mfma_f32_16x16x32_bf16(Bt[n][k], At[m][k], acc[ai][bj][m][n], 0, 0, 0); __builtin_amdgcn_s_setprio(0); } while (0)
; #define PG8_WAIT_V(n) asm volatile("s_waitcnt vmcnt(" #n ")" ::: "memory")
; #define PG8_WAIT_L(n) asm volatile("s_waitcnt lgkmcnt(" #n ")" ::: "memory")
; #define PG8_BAR __builtin_amdgcn_s_barrier()
; #define PG8_SCHED __builtin_amdgcn_sched_barrier(0)
; template <class Epi, class Sched, bool AREMAP>
; __device__ __forceinline__ void gemm_phase(LAS unsigned char* lds, const Gemm g, const Sched& S, const Epi& E, int wv) {
;     ...
;             PG8_LDA(At, 0, 1); PG8_STAGE(PG8_SA(0, 0), a2, voffA);
;             PG8_BAR; PG8_WAIT_L(0); PG8_MMA(1, 0, At, B0); PG8_BAR; PG8_SCHED;
;             PG8_STAGE(PG8_SB(0, 1), b2 + hstepB, voffB);
;             PG8_WAIT_V(6); PG8_BAR; PG8_MMA(1, 1, At, B1); PG8_BAR;
;             PG8_LDB(B0, 1, 0); PG8_SCHED; PG8_LDA(At, 1, 0); PG8_STAGE(PG8_SA(0, 1), a2 + hstepA, voffA);
;             PG8_WAIT_L(8); PG8_BAR; PG8_WAIT_L(0); PG8_MMA(0, 0, At, B0); PG8_BAR; PG8_SCHED;
;             PG8_LDB(B1, 1, 1); PG8_STAGE(PG8_SB(1, 0), b3, voffB);
;             PG8_BAR; PG8_WAIT_L(0); PG8_MMA(0, 1, At, B1); PG8_BAR;
;             PG8_LDA(At, 1, 1); PG8_STAGE(PG8_SA(1, 0), a3, voffA);
;             PG8_BAR; PG8_WAIT_L(0); PG8_MMA(1, 0, At, B0); PG8_BAR; PG8_SCHED;
	s_add_u32 s62, s18, 0x80000
	s_addc_u32 s63, s19, 0
	s_add_i32 s38, s39, s29
	v_lshl_add_u64 v[146:147], s[62:63], 0, v[132:133]
	s_mov_b32 m0, s38
	s_nop 0
	global_load_lds_dwordx4 v[146:147], off
	v_lshl_add_u64 v[146:147], s[62:63], 0, v[136:137]
	s_add_i32 m0, s38, 0x2000
	s_nop 0
	global_load_lds_dwordx4 v[146:147], off
	s_waitcnt vmcnt(6)
	s_barrier
	v_mfma_f32_16x16x32_bf16 v[46:49], v[204:207], v[162:165], v[46:49]
	v_mfma_f32_16x16x32_bf16 v[42:45], v[212:215], v[162:165], v[42:45]
	v_mfma_f32_16x16x32_bf16 v[30:33], v[204:207], v[170:173], v[30:33]
	v_mfma_f32_16x16x32_bf16 v[26:29], v[212:215], v[170:173], v[26:29]
	v_mfma_f32_16x16x32_bf16 v[14:17], v[204:207], v[178:181], v[14:17]
	v_mfma_f32_16x16x32_bf16 v[10:13], v[212:215], v[178:181], v[10:13]
	v_mfma_f32_16x16x32_bf16 v[6:9], v[204:207], v[196:199], v[6:9]
	v_mfma_f32_16x16x32_bf16 v[2:5], v[212:215], v[196:199], v[2:5]
	v_mfma_f32_16x16x32_bf16 v[46:49], v[208:211], v[166:169], v[46:49]
	v_mfma_f32_16x16x32_bf16 v[42:45], v[216:219], v[166:169], v[42:45]
	v_mfma_f32_16x16x32_bf16 v[30:33], v[208:211], v[174:177], v[30:33]
	v_mfma_f32_16x16x32_bf16 v[26:29], v[216:219], v[174:177], v[26:29]
	v_mfma_f32_16x16x32_bf16 v[14:17], v[208:211], v[182:185], v[14:17]
	v_mfma_f32_16x16x32_bf16 v[10:13], v[216:219], v[182:185], v[10:13]
	v_mfma_f32_16x16x32_bf16 v[6:9], v[208:211], v[200:203], v[6:9]
	v_mfma_f32_16x16x32_bf16 v[2:5], v[216:219], v[200:203], v[2:5]
	s_add_i32 s38, 0, 0x18000
	v_add_u32_e32 v145, s38, v142
	s_barrier
	ds_read_b128 v[146:149], v145
	ds_read_b128 v[150:153], v145 offset:1024
	ds_read_b128 v[154:157], v145 offset:2048
	ds_read_b128 v[158:161], v145 offset:3072
	s_add_u32 s20, s20, 0x80000
	s_addc_u32 s21, s21, 0
	s_mov_b32 m0, s31
	v_lshl_add_u64 v[204:205], s[20:21], 0, v[130:131]
	ds_read_b128 v[162:165], v144 offset:32768
	ds_read_b128 v[166:169], v144 offset:33792
	ds_read_b128 v[170:173], v144 offset:34816
	ds_read_b128 v[174:177], v144 offset:35840
	ds_read_b128 v[178:181], v144 offset:36864
	ds_read_b128 v[182:185], v144 offset:37888
	ds_read_b128 v[196:199], v144 offset:38912
	ds_read_b128 v[200:203], v144 offset:39936
	global_load_lds_dwordx4 v[204:205], off
	v_lshl_add_u64 v[204:205], s[20:21], 0, v[134:135]
	s_mov_b32 m0, s34
	s_nop 0
	global_load_lds_dwordx4 v[204:205], off
	s_waitcnt lgkmcnt(8)
	s_barrier
	s_waitcnt lgkmcnt(0)
	s_waitcnt lgkmcnt(0)
	v_mfma_f32_16x16x32_bf16 v[126:129], v[146:149], v[162:165], v[126:129]
	v_mfma_f32_16x16x32_bf16 v[122:125], v[154:157], v[162:165], v[122:125]
	v_mfma_f32_16x16x32_bf16 v[118:121], v[146:149], v[170:173], v[118:121]
	v_mfma_f32_16x16x32_bf16 v[114:117], v[154:157], v[170:173], v[114:117]
	v_mfma_f32_16x16x32_bf16 v[102:105], v[146:149], v[178:181], v[102:105]
	v_mfma_f32_16x16x32_bf16 v[98:101], v[154:157], v[178:181], v[98:101]
	v_mfma_f32_16x16x32_bf16 v[86:89], v[146:149], v[196:199], v[86:89]
	v_mfma_f32_16x16x32_bf16 v[82:85], v[154:157], v[196:199], v[82:85]
	v_mfma_f32_16x16x32_bf16 v[126:129], v[150:153], v[166:169], v[126:129]
	v_mfma_f32_16x16x32_bf16 v[122:125], v[158:161], v[166:169], v[122:125]
	v_mfma_f32_16x16x32_bf16 v[118:121], v[150:153], v[174:177], v[118:121]
	v_mfma_f32_16x16x32_bf16 v[114:117], v[158:161], v[174:177], v[114:117]
	v_mfma_f32_16x16x32_bf16 v[102:105], v[150:153], v[182:185], v[102:105]
	v_mfma_f32_16x16x32_bf16 v[98:101], v[158:161], v[182:185], v[98:101]
	v_mfma_f32_16x16x32_bf16 v[86:89], v[150:153], v[200:203], v[86:89]
	v_mfma_f32_16x16x32_bf16 v[82:85], v[158:161], v[200:203], v[82:85]
	s_barrier
	s_add_i32 s20, 0, 0x1c000
	s_add_i32 s21, s38, s29
	v_add_u32_e32 v145, s20, v142
	v_lshl_add_u64 v[186:187], v[186:187], 0, s[86:87]
	s_mov_b32 m0, s21
	ds_read_b128 v[204:207], v145
	ds_read_b128 v[208:211], v145 offset:1024
	ds_read_b128 v[212:215], v145 offset:2048
	ds_read_b128 v[216:219], v145 offset:3072
	global_load_lds_dwordx4 v[186:187], off
	v_lshl_add_u64 v[186:187], v[192:193], 0, s[86:87]
	s_add_i32 m0, s21, 0x2000
	s_nop 0
	global_load_lds_dwordx4 v[186:187], off
	s_barrier
	s_waitcnt lgkmcnt(0)
	s_waitcnt lgkmcnt(0)
	v_mfma_f32_16x16x32_bf16 v[110:113], v[204:207], v[162:165], v[110:113]
	v_mfma_f32_16x16x32_bf16 v[106:109], v[212:215], v[162:165], v[106:109]
	v_mfma_f32_16x16x32_bf16 v[94:97], v[204:207], v[170:173], v[94:97]
	v_mfma_f32_16x16x32_bf16 v[90:93], v[212:215], v[170:173], v[90:93]
	v_mfma_f32_16x16x32_bf16 v[78:81], v[204:207], v[178:181], v[78:81]
	v_mfma_f32_16x16x32_bf16 v[74:77], v[212:215], v[178:181], v[74:77]
	v_mfma_f32_16x16x32_bf16 v[70:73], v[204:207], v[196:199], v[70:73]
	v_mfma_f32_16x16x32_bf16 v[66:69], v[212:215], v[196:199], v[66:69]
	v_mfma_f32_16x16x32_bf16 v[110:113], v[208:211], v[166:169], v[110:113]
	v_mfma_f32_16x16x32_bf16 v[106:109], v[216:219], v[166:169], v[106:109]
	v_mfma_f32_16x16x32_bf16 v[94:97], v[208:211], v[174:177], v[94:97]
	v_mfma_f32_16x16x32_bf16 v[90:93], v[216:219], v[174:177], v[90:93]
	v_mfma_f32_16x16x32_bf16 v[78:81], v[208:211], v[182:185], v[78:81]
	v_mfma_f32_16x16x32_bf16 v[74:77], v[216:219], v[182:185], v[74:77]
	v_mfma_f32_16x16x32_bf16 v[70:73], v[208:211], v[200:203], v[70:73]
	v_mfma_f32_16x16x32_bf16 v[66:69], v[216:219], v[200:203], v[66:69]
	s_mov_b32 m0, s35
	v_lshl_add_u64 v[186:187], v[194:195], 0, s[86:87]
	s_barrier
	ds_read_b128 v[162:165], v144 offset:49152
	ds_read_b128 v[166:169], v144 offset:50176
	ds_read_b128 v[170:173], v144 offset:51200
	ds_read_b128 v[174:177], v144 offset:52224
	ds_read_b128 v[178:181], v144 offset:53248
	ds_read_b128 v[182:185], v144 offset:54272
	ds_read_b128 v[196:199], v144 offset:55296
	ds_read_b128 v[200:203], v144 offset:56320
	global_load_lds_dwordx4 v[186:187], off
	v_lshl_add_u64 v[186:187], v[220:221], 0, s[86:87]
	s_mov_b32 m0, s36
	s_nop 0
	global_load_lds_dwordx4 v[186:187], off
	s_barrier
; #define PG8_STAGE(bufoff, gbase, voff) do { _Pragma("unroll") for (int _i = 0; _i < 2; ++_i) \
;         __builtin_amdgcn_global_load_lds((const unsigned*)((const char*)(gbase) + (voff)[_i]), (LAS unsigned*)(lds + (bufoff) + ldsw + _i * 8192), 16, 0, 0); } while (0)
; #define PG8_LDA(dst, b, h) do { _Pragma("unroll") for (int m = 0; m < 4; ++m) _Pragma("unroll") for (int k = 0; k < 2; ++k) dst[m][k] = *(const LAS bf16x8*)(lds + PG8_SA(b, h) + aoff + m * 2048 + k * 1024); } while (0)
; #define PG8_MMA(ai, bj, At, Bt) do { __builtin_amdgcn_s_setprio(1); _Pragma("unroll") for (int m = 0; m < 4; ++m) _Pragma("unroll") for (int n = 0; n < 2; ++n) _Pragma("unroll") for (int k = 0; k < 2; ++k) \
;         acc[ai][bj][m][n] = __builtin_amdgcn_mfma_f32_16x16x32_bf16(Bt[n][k], At[m][k], acc[ai][bj][m][n], 0, 0, 0); __builtin_amdgcn_s_setprio(0); } while (0)
; #define PG8_WAIT_V(n) asm volatile("s_waitcnt vmcnt(" #n ")" ::: "memory")
; #define PG8_WAIT_L(n) asm volatile("s_waitcnt lgkmcnt(" #n ")" ::: "memory")
; #define PG8_BAR __builtin_amdgcn_s_barrier()
; #define PG8_SCHED __builtin_amdgcn_sched_barrier(0)
; template <class Epi, class Sched, bool AREMAP>
; __device__ __forceinline__ void gemm_phase(LAS unsigned char* lds, const Gemm g, const Sched& S, const Epi& E, int wv) {
;     ...
;             PG8_BAR; PG8_WAIT_L(0); PG8_MMA(0, 1, At, B1); PG8_BAR;
;             PG8_LDA(At, 1, 1); PG8_STAGE(PG8_SA(1, 0), a3, voffA);
;             PG8_BAR; PG8_WAIT_L(0); PG8_MMA(1, 0, At, B0); PG8_BAR; PG8_SCHED;
;             PG8_STAGE(PG8_SB(1, 1), b3 + hstepB, voffB);
;             PG8_WAIT_V(6); PG8_BAR; PG8_MMA(1, 1, At, B1); PG8_BAR;
	s_waitcnt lgkmcnt(0)
	s_waitcnt lgkmcnt(0)
	v_mfma_f32_16x16x32_bf16 v[62:65], v[146:149], v[162:165], v[62:65]
	v_mfma_f32_16x16x32_bf16 v[58:61], v[154:157], v[162:165], v[58:61]
	v_mfma_f32_16x16x32_bf16 v[54:57], v[146:149], v[170:173], v[54:57]
	v_mfma_f32_16x16x32_bf16 v[50:53], v[154:157], v[170:173], v[50:53]
	v_mfma_f32_16x16x32_bf16 v[38:41], v[146:149], v[178:181], v[38:41]
	v_mfma_f32_16x16x32_bf16 v[34:37], v[154:157], v[178:181], v[34:37]
	v_mfma_f32_16x16x32_bf16 v[22:25], v[146:149], v[196:199], v[22:25]
	v_mfma_f32_16x16x32_bf16 v[18:21], v[154:157], v[196:199], v[18:21]
	v_mfma_f32_16x16x32_bf16 v[62:65], v[150:153], v[166:169], v[62:65]
	v_mfma_f32_16x16x32_bf16 v[58:61], v[158:161], v[166:169], v[58:61]
	v_mfma_f32_16x16x32_bf16 v[54:57], v[150:153], v[174:177], v[54:57]
	v_mfma_f32_16x16x32_bf16 v[50:53], v[158:161], v[174:177], v[50:53]
	v_mfma_f32_16x16x32_bf16 v[38:41], v[150:153], v[182:185], v[38:41]
	v_mfma_f32_16x16x32_bf16 v[34:37], v[158:161], v[182:185], v[34:37]
	v_mfma_f32_16x16x32_bf16 v[22:25], v[150:153], v[200:203], v[22:25]
	v_mfma_f32_16x16x32_bf16 v[18:21], v[158:161], v[200:203], v[18:21]
	s_barrier
	s_add_u32 s18, s18, 0x80080
	s_addc_u32 s19, s19, 0
	s_add_i32 s20, s20, s29
	v_lshl_add_u64 v[146:147], s[18:19], 0, v[132:133]
	s_mov_b32 m0, s20
	s_nop 0
	global_load_lds_dwordx4 v[146:147], off
	v_lshl_add_u64 v[146:147], s[18:19], 0, v[136:137]
	s_add_i32 m0, s20, 0x2000
	s_nop 0
	global_load_lds_dwordx4 v[146:147], off
	s_waitcnt vmcnt(6)
	s_barrier
	v_mfma_f32_16x16x32_bf16 v[46:49], v[204:207], v[162:165], v[46:49]
	v_mfma_f32_16x16x32_bf16 v[42:45], v[212:215], v[162:165], v[42:45]
	v_mfma_f32_16x16x32_bf16 v[30:33], v[204:207], v[170:173], v[30:33]
	v_mfma_f32_16x16x32_bf16 v[26:29], v[212:215], v[170:173], v[26:29]
	v_mfma_f32_16x16x32_bf16 v[14:17], v[204:207], v[178:181], v[14:17]
	v_mfma_f32_16x16x32_bf16 v[10:13], v[212:215], v[178:181], v[10:13]
	v_mfma_f32_16x16x32_bf16 v[6:9], v[204:207], v[196:199], v[6:9]
	v_mfma_f32_16x16x32_bf16 v[2:5], v[212:215], v[196:199], v[2:5]
	v_mfma_f32_16x16x32_bf16 v[46:49], v[208:211], v[166:169], v[46:49]
	v_mfma_f32_16x16x32_bf16 v[42:45], v[216:219], v[166:169], v[42:45]
	v_mfma_f32_16x16x32_bf16 v[30:33], v[208:211], v[174:177], v[30:33]
	v_mfma_f32_16x16x32_bf16 v[26:29], v[216:219], v[174:177], v[26:29]
	v_mfma_f32_16x16x32_bf16 v[14:17], v[208:211], v[182:185], v[14:17]
	v_mfma_f32_16x16x32_bf16 v[10:13], v[216:219], v[182:185], v[10:13]
	v_mfma_f32_16x16x32_bf16 v[6:9], v[208:211], v[200:203], v[6:9]
	v_mfma_f32_16x16x32_bf16 v[2:5], v[216:219], v[200:203], v[2:5]
	s_add_i32 s56, s56, 2
	s_add_u32 s53, s53, 0x100
	s_addc_u32 s55, s55, 0
	s_add_u32 s16, s16, 0x100
	s_addc_u32 s17, s17, 0
	s_cmp_gt_u32 s56, 29
	s_barrier
	s_cbranch_scc0 .LBB0_202
; __device__ __forceinline__ unsigned cvt_pk_bf16(float lo, float hi) { f32x2_t f = {lo, hi}; bf16x2_t v = __builtin_convertvector(f, bf16x2_t); return __builtin_bit_cast(unsigned, v); }
; #define PG8_WAIT_V(n) asm volatile("s_waitcnt vmcnt(" #n ")" ::: "memory")
; #define PG8_BAR __builtin_amdgcn_s_barrier()
; template <class Epi, class Sched, bool AREMAP>
; __device__ __forceinline__ void gemm_phase(LAS unsigned char* lds, const Gemm g, const Sched& S, const Epi& E, int wv) {
;     ...
;         if (!has_next) break;
; #pragma unroll
;         for (int a = 0; a < 2; ++a)
; #pragma unroll
;             for (int b = 0; b < 2; ++b)
; #pragma unroll
;                 for (int m = 0; m < 4; ++m)
; #pragma unroll
;                     for (int n = 0; n < 2; ++n) acc[a][b][m][n] = (f32x4){0.f, 0.f, 0.f, 0.f};
;         cur = nxt; cA = nA; cB = nB; ++ui;
;     }
;     PG8_WAIT_V(0);
;     if (wr == 0) PG8_BAR;
;     PG8_BAR;
;     __device__ __forceinline__ void operator()(const f32x4 (&acc)[2][2][4][2], const Unit& u, int wr, int wc, int fr, int fq) const {
;         const int row0 = u.pm * BM + wr * 64 + fr; int colt = u.pn * BM; bf16_t* base = O;
;         if (split_cols) { const int t = colt / split_cols; base += (size_t)t * split_stride; colt -= t * split_cols; }
;         const int col0 = colt + wc * 32 + 8 * fq;
; #pragma unroll
;         for (int ai = 0; ai < 2; ++ai)
; #pragma unroll
;             for (int m = 0; m < 4; ++m) { bf16_t* rowp = base + (size_t)(row0 + ai * HALF + m * 16) * ldc + col0;
; #pragma unroll
;                 for (int bj = 0; bj < 2; ++bj) { const f32x4 v0 = acc[ai][bj][m][0], v1 = acc[ai][bj][m][1];
;                     u32x4 w; w.x = cvt_pk_bf16(v0[0], v0[1]); w.y = cvt_pk_bf16(v0[2], v0[3]); w.z = cvt_pk_bf16(v1[0], v1[1]); w.w = cvt_pk_bf16(v1[2], v1[3]);
;                     *(u32x4*)(rowp + bj * HALF) = w; } }
	v_lshl_add_u32 v146, s6, 8, v1
	v_lshl_or_b32 v148, s46, 8, v143
	v_ashrrev_i32_e32 v149, 31, v148
	v_ashrrev_i32_e32 v147, 31, v146
	v_lshl_add_u64 v[148:149], v[148:149], 1, s[4:5]
	v_lshlrev_b64 v[150:151], 14, v[146:147]
	v_lshl_add_u64 v[150:151], v[148:149], 0, v[150:151]
	s_mov_b32 s6, 0x200000
	s_mov_b64 s[16:17], 0x200000
	v_cvt_pk_bf16_f32 v62, v62, v63
	v_cvt_pk_bf16_f32 v63, v64, v65
	v_cvt_pk_bf16_f32 v64, v58, v59
	v_add_co_u32_e32 v58, vcc, s6, v150
	v_cvt_pk_bf16_f32 v70, v70, v71
	v_cvt_pk_bf16_f32 v71, v72, v73
	v_cvt_pk_bf16_f32 v72, v66, v67
	v_lshl_add_u64 v[66:67], v[150:151], 0, s[16:17]
	v_addc_co_u32_e32 v59, vcc, 0, v151, vcc
	v_cvt_pk_bf16_f32 v46, v46, v47
	v_cvt_pk_bf16_f32 v47, v48, v49
	v_cvt_pk_bf16_f32 v48, v42, v43
	v_cvt_pk_bf16_f32 v49, v44, v45
	s_mov_b32 s6, 0x240000
	global_store_dwordx4 v[66:67], v[46:49], off offset:256
	s_mov_b64 s[16:17], 0x240000
	v_cvt_pk_bf16_f32 v110, v110, v111
	v_add_co_u32_e32 v48, vcc, s6, v150
	v_cvt_pk_bf16_f32 v111, v112, v113
	v_cvt_pk_bf16_f32 v112, v106, v107
	v_or_b32_e32 v106, 16, v146
	v_lshl_add_u64 v[46:47], v[150:151], 0, s[16:17]
	v_addc_co_u32_e32 v49, vcc, 0, v151, vcc
	v_cvt_pk_bf16_f32 v30, v30, v31
	v_cvt_pk_bf16_f32 v31, v32, v33
	v_cvt_pk_bf16_f32 v32, v26, v27
	v_cvt_pk_bf16_f32 v33, v28, v29
	s_mov_b32 s6, 0x280000
	v_ashrrev_i32_e32 v107, 31, v106
	v_cvt_pk_bf16_f32 v94, v94, v95
	v_cvt_pk_bf16_f32 v95, v96, v97
	v_cvt_pk_bf16_f32 v96, v90, v91
	v_or_b32_e32 v90, 32, v146
	global_store_dwordx4 v[46:47], v[30:33], off offset:256
	s_mov_b64 s[16:17], 0x280000
	v_cvt_pk_bf16_f32 v113, v108, v109
	v_add_co_u32_e32 v32, vcc, s6, v150
	v_lshlrev_b64 v[106:107], 14, v[106:107]
	v_ashrrev_i32_e32 v91, 31, v90
	v_cvt_pk_bf16_f32 v78, v78, v79
	v_cvt_pk_bf16_f32 v79, v80, v81
	v_cvt_pk_bf16_f32 v80, v74, v75
	v_or_b32_e32 v74, 48, v146
	v_lshl_add_u64 v[30:31], v[150:151], 0, s[16:17]
	v_addc_co_u32_e32 v33, vcc, 0, v151, vcc
	v_cvt_pk_bf16_f32 v14, v14, v15
	v_cvt_pk_bf16_f32 v15, v16, v17
	v_cvt_pk_bf16_f32 v16, v10, v11
	v_cvt_pk_bf16_f32 v17, v12, v13
	global_store_dwordx4 v[150:151], v[110:113], off offset:256
	v_cvt_pk_bf16_f32 v97, v92, v93
	v_lshlrev_b64 v[90:91], 14, v[90:91]
	v_lshl_add_u64 v[110:111], v[148:149], 0, v[106:107]
	v_ashrrev_i32_e32 v75, 31, v74
	global_store_dwordx4 v[30:31], v[14:17], off offset:256
	global_store_dwordx4 v[110:111], v[94:97], off offset:256
	v_cvt_pk_bf16_f32 v81, v76, v77
	v_add_co_u32_e32 v16, vcc, s33, v150
	v_lshl_add_u64 v[94:95], v[148:149], 0, v[90:91]
	v_lshlrev_b64 v[74:75], 14, v[74:75]
	s_mov_b64 s[16:17], 0x2c0000
	v_addc_co_u32_e32 v17, vcc, 0, v151, vcc
	v_cvt_pk_bf16_f32 v126, v126, v127
	v_cvt_pk_bf16_f32 v127, v128, v129
	v_cvt_pk_bf16_f32 v128, v122, v123
	v_cvt_pk_bf16_f32 v129, v124, v125
	v_cvt_pk_bf16_f32 v106, v118, v119
	v_cvt_pk_bf16_f32 v107, v120, v121
	v_cvt_pk_bf16_f32 v108, v114, v115
	v_cvt_pk_bf16_f32 v109, v116, v117
	v_cvt_pk_bf16_f32 v90, v102, v103
	v_cvt_pk_bf16_f32 v91, v104, v105
	v_cvt_pk_bf16_f32 v92, v98, v99
	v_cvt_pk_bf16_f32 v93, v100, v101
	global_store_dwordx4 v[94:95], v[78:81], off offset:256
	v_cvt_pk_bf16_f32 v76, v82, v83
	v_cvt_pk_bf16_f32 v77, v84, v85
	v_lshl_add_u64 v[78:79], v[148:149], 0, v[74:75]
	v_cvt_pk_bf16_f32 v74, v86, v87
	v_cvt_pk_bf16_f32 v75, v88, v89
	v_cvt_pk_bf16_f32 v73, v68, v69
	v_cvt_pk_bf16_f32 v65, v60, v61
	v_cvt_pk_bf16_f32 v42, v54, v55
	v_cvt_pk_bf16_f32 v43, v56, v57
	v_cvt_pk_bf16_f32 v44, v50, v51
	v_cvt_pk_bf16_f32 v45, v52, v53
	v_cvt_pk_bf16_f32 v26, v38, v39
	v_cvt_pk_bf16_f32 v27, v40, v41
	v_cvt_pk_bf16_f32 v28, v34, v35
	v_cvt_pk_bf16_f32 v29, v36, v37
	v_lshl_add_u64 v[14:15], v[150:151], 0, s[16:17]
	v_cvt_pk_bf16_f32 v10, v22, v23
	v_cvt_pk_bf16_f32 v11, v24, v25
	v_cvt_pk_bf16_f32 v12, v18, v19
	v_cvt_pk_bf16_f32 v13, v20, v21
	v_cvt_pk_bf16_f32 v6, v6, v7
	v_cvt_pk_bf16_f32 v7, v8, v9
	v_cvt_pk_bf16_f32 v8, v2, v3
	v_cvt_pk_bf16_f32 v9, v4, v5
	s_and_b64 vcc, exec, s[0:1]
	s_mov_b32 s46, s8
	s_mov_b32 s6, s10
	s_mov_b64 s[16:17], s[14:15]
	s_mov_b64 s[18:19], s[12:13]
	s_mov_b32 s39, 0xb2a5705f
	s_mov_b32 s38, 0x42ce8ed0
	s_mov_b64 s[52:53], 0x41000
	global_store_dwordx4 v[150:151], v[126:129], off
	global_store_dwordx4 v[110:111], v[106:109], off
	global_store_dwordx4 v[94:95], v[90:93], off
	global_store_dwordx4 v[78:79], v[74:77], off
	global_store_dwordx4 v[78:79], v[70:73], off offset:256
	global_store_dwordx4 v[58:59], v[62:65], off
	global_store_dwordx4 v[48:49], v[42:45], off
	global_store_dwordx4 v[32:33], v[26:29], off
	global_store_dwordx4 v[16:17], v[10:13], off
	global_store_dwordx4 v[14:15], v[6:9], off offset:256
	s_cbranch_vccz .LBB0_195
	s_waitcnt vmcnt(0)
	s_cmpk_gt_u32 s25, 0xff
	s_cbranch_scc1 .LBB0_206
	s_barrier

; __device__ __forceinline__ int otid(int wv) { int t = (wv << 6) | (int)__builtin_amdgcn_mbcnt_hi(~0u, __builtin_amdgcn_mbcnt_lo(~0u, 0u)); asm volatile("" : "+v"(t)); return t; }
; __device__ __forceinline__ void grid_bar(unsigned* ctr, unsigned& target, int G, int wv) {
;     asm volatile("s_waitcnt vmcnt(0) lgkmcnt(0)" ::: "memory");
;     __syncthreads();
;     target = (unsigned)__builtin_amdgcn_readfirstlane((int)(target + (unsigned)G));
;     if (otid(wv) == 0) {
;         __builtin_amdgcn_fence(__ATOMIC_RELEASE, "agent");
;         asm volatile("s_waitcnt vmcnt(0)" ::: "memory");
;         __hip_atomic_fetch_add(ctr, 1u, __ATOMIC_RELAXED, __HIP_MEMORY_SCOPE_AGENT);
;         while (__hip_atomic_load(ctr, __ATOMIC_RELAXED, __HIP_MEMORY_SCOPE_AGENT) < target) __builtin_amdgcn_s_sleep(1);
;         __builtin_amdgcn_fence(__ATOMIC_ACQUIRE, "agent");
;         asm volatile("s_waitcnt vmcnt(0)" ::: "memory");
;     }
;     __syncthreads();
; }
.LBB0_207:
	s_setprio 0
	s_waitcnt vmcnt(0) lgkmcnt(0)
	v_mov_b32_e32 v1, v236
	s_waitcnt vmcnt(0) lgkmcnt(0)
	s_barrier
	s_add_i32 s73, s22, s33
	s_nop 0
	v_cmp_eq_u32_e32 vcc, 0, v1
	s_and_saveexec_b64 s[0:1], vcc
	s_cbranch_execz .LBB0_213
	s_mov_b64 s[2:3], exec
	buffer_wbl2 sc1
	s_waitcnt vmcnt(0)
	v_mbcnt_lo_u32_b32 v1, s2, 0
	v_mbcnt_hi_u32_b32 v1, s3, v1
	v_cmp_eq_u32_e32 vcc, 0, v1
	s_and_saveexec_b64 s[4:5], vcc
	s_cbranch_execz .LBB0_210
	s_bcnt1_i32_b64 s2, s[2:3]
	v_mov_b32_e32 v1, s2
	v_readlane_b32 s2, v254, 30
	v_readlane_b32 s3, v254, 31
	s_nop 4
	global_atomic_add v0, v1, s[2:3]

; __device__ __forceinline__ int otid(int wv) { int t = (wv << 6) | (int)__builtin_amdgcn_mbcnt_hi(~0u, __builtin_amdgcn_mbcnt_lo(~0u, 0u)); asm volatile("" : "+v"(t)); return t; }
; __device__ __forceinline__ void grid_bar(unsigned* ctr, unsigned& target, int G, int wv) {
;     asm volatile("s_waitcnt vmcnt(0) lgkmcnt(0)" ::: "memory");
;     __syncthreads();
;     target = (unsigned)__builtin_amdgcn_readfirstlane((int)(target + (unsigned)G));
;     if (otid(wv) == 0) {
;         __builtin_amdgcn_fence(__ATOMIC_RELEASE, "agent");
;         asm volatile("s_waitcnt vmcnt(0)" ::: "memory");
;         __hip_atomic_fetch_add(ctr, 1u, __ATOMIC_RELAXED, __HIP_MEMORY_SCOPE_AGENT);
;         while (__hip_atomic_load(ctr, __ATOMIC_RELAXED, __HIP_MEMORY_SCOPE_AGENT) < target) __builtin_amdgcn_s_sleep(1);
;         __builtin_amdgcn_fence(__ATOMIC_ACQUIRE, "agent");
;         asm volatile("s_waitcnt vmcnt(0)" ::: "memory");
;     }
;     __syncthreads();
; }
.LBB0_382:
	s_or_b64 exec, exec, s[4:5]
	s_waitcnt lgkmcnt(0)
	s_barrier
	s_setprio 0
	s_waitcnt vmcnt(0) lgkmcnt(0)
	v_mov_b32_e32 v1, v236
	s_barrier
	s_add_i32 s24, s73, s33
	s_nop 0
	v_cmp_eq_u32_e32 vcc, 0, v1
	s_and_saveexec_b64 s[0:1], vcc
	s_cbranch_execz .LBB0_388
	s_mov_b64 s[2:3], exec
	buffer_wbl2 sc1
	s_waitcnt vmcnt(0)
	s_waitcnt vmcnt(0)
	v_mbcnt_lo_u32_b32 v1, s2, 0
	v_mbcnt_hi_u32_b32 v1, s3, v1
	v_cmp_eq_u32_e32 vcc, 0, v1
	s_and_saveexec_b64 s[4:5], vcc
	s_cbranch_execz .LBB0_385
	s_bcnt1_i32_b64 s2, s[2:3]
	v_mov_b32_e32 v1, s2
	v_readlane_b32 s2, v254, 30
	v_readlane_b32 s3, v254, 31
	s_nop 4
	global_atomic_add v0, v1, s[2:3]

;     __device__ bool map(long L, Unit& u) const {
;         if (L >= nwg) return false;
;         int wgid = (int)L; { const int q = nwg / NXCD, r = nwg % NXCD, xcd = wgid % NXCD, off = wgid / NXCD; wgid = (xcd < r ? xcd * (q + 1) : r * (q + 1) + (xcd - r) * q) + off; }
;         const int nig = WGM * nN, gid = wgid / nig, fm = gid * WGM, gsz = (nM - fm) < WGM ? (nM - fm) : WGM;
; template <class Epi, class Sched, bool AREMAP>
; __device__ __forceinline__ void gemm_phase(LAS unsigned char* lds, const Gemm g, const Sched& S, const Epi& E, int wv) {
;     const int tid = otid(wv), wid = __builtin_amdgcn_readfirstlane(tid >> 6), lane = tid & 63, wr = wid >> 2, wc = wid & 3, fr = lane & 15, fq = lane >> 4;
;     const int K = g.K, nt = K / BK;
;     unsigned voffA[2], voffB[2];
; #pragma unroll
;     for (int i = 0; i < 2; ++i) { int R, C; stage_rc(tid * 16 + i * 8192, R, C); const int Rb = Epi::PERM ? ((R & ~31) + perm32(R & 31)) : R;
;         const int Ra = AREMAP ? ((R >> 6) * 128 + (R & 63)) : R;
;         voffA[i] = (unsigned)(Ra * g.lda + C) * 2u; voffB[i] = (unsigned)(Rb * g.ldb + C) * 2u; }
;     const size_t kstep = (size_t)(BK * 2);
;     const size_t hstepA = (size_t)(AREMAP ? 64 : HALF) * g.lda * 2, hstepB = (size_t)HALF * g.ldb * 2;
;     const size_t tstepA = (size_t)BM * g.lda * 2, tstepB = (size_t)BM * g.ldb * 2;
;     const unsigned ldsw = (unsigned)wid * 1024u;
;     const int aoff = lds_byte(wr * 64 + fr, fq * 8), boff = lds_byte(wc * 32 + fr, fq * 8);
;     ...
;     Unit cur, nxt; int ui = 0;
;     if (!S.next(0, cur)) return;
;     f32x4 acc[2][2][4][2];
; #pragma unroll
;     for (int a = 0; a < 2; ++a)
; #pragma unroll
;         for (int b = 0; b < 2; ++b)
; #pragma unroll
;             for (int m = 0; m < 4; ++m)
; #pragma unroll
;                 for (int n = 0; n < 2; ++n) acc[a][b][m][n] = (f32x4){0.f, 0.f, 0.f, 0.f};
;     bf16x8 At[4][2], B0[2][2], B1[2][2];
;     ...
;     const char* cA = PG8_UA(cur); const char* cB = PG8_UB(cur);
;     PG8_STAGE(PG8_SB(0, 0), cB, voffB); PG8_STAGE(PG8_SA(0, 0), cA, voffA); PG8_STAGE(PG8_SB(0, 1), cB + hstepB, voffB); PG8_STAGE(PG8_SA(0, 1), cA + hstepA, voffA);
;     if (wr == 1) PG8_BAR;
;     PG8_WAIT_V(4); PG8_BAR;
;     PG8_STAGE(PG8_SB(1, 0), cB + kstep, voffB); PG8_STAGE(PG8_SA(1, 0), cA + kstep, voffA); PG8_STAGE(PG8_SB(1, 1), cB + hstepB + kstep, voffB);
;     PG8_WAIT_V(6); PG8_BAR;
.LBB0_388:
	s_or_b64 exec, exec, s[0:1]
	v_readlane_b32 s0, v254, 18
	v_readlane_b32 s1, v254, 19
	s_mov_b32 s18, s58
	s_mov_b32 s19, s31
	v_mov_b32_e32 v16, v236
	s_barrier
	s_cmpk_gt_i32 s19, 0xbff
	v_readfirstlane_b32 s20, v16
	s_cbranch_scc1 .LBB0_402
	v_lshlrev_b32_e32 v1, 4, v16
	v_add_u32_e32 v2, 0x2000, v1
	v_ashrrev_i32_e32 v3, 31, v2
	v_lshrrev_b32_e32 v3, 22, v3
	v_add_u32_e32 v3, v2, v3
	v_ashrrev_i32_e32 v10, 10, v3
	v_mul_i32_i24_e32 v3, 0x400, v10
	v_sub_u32_e32 v2, v2, v3
	v_lshrrev_b32_e32 v3, 4, v2
	v_bitop3_b32 v2, v3, v2, 32 bitop3:0x6c
	v_ashrrev_i32_e32 v3, 31, v2
	v_lshrrev_b32_e32 v3, 26, v3
	v_add_u32_e32 v3, v2, v3
	v_lshlrev_b32_e32 v4, 3, v10
	v_ashrrev_i32_e32 v11, 6, v3
	v_and_b32_e32 v4, -16, v4
	v_add_u32_e32 v4, v11, v4
	v_and_b32_e32 v5, 3, v11
	s_mov_b32 s2, 0x1fffe0
	v_lshrrev_b32_e32 v6, 2, v4
	v_lshlrev_b32_e32 v7, 1, v4
	v_and_b32_e32 v3, 0xc0, v3
	v_and_or_b32 v5, v4, s2, v5
	v_and_b32_e32 v6, 4, v6
	v_and_b32_e32 v7, 24, v7
	v_sub_u32_e32 v2, v2, v3
	v_or3_b32 v5, v5, v6, v7
	v_lshlrev_b32_e32 v6, 5, v10
	v_ashrrev_i16_sdwa v2, v240, sext(v2) dst_sel:DWORD dst_unused:UNUSED_PAD src0_sel:DWORD src1_sel:BYTE_0
	v_and_b32_e32 v6, 32, v6
	v_bfe_i32 v12, v2, 0, 16
	v_add_lshl_u32 v2, v6, v12, 1
	v_lshl_add_u32 v130, v5, 11, v2
	v_lshl_add_u32 v132, v4, 11, v2
	v_bfe_i32 v2, v16, 27, 1
	v_lshrrev_b32_e32 v2, 22, v2
	v_add_u32_e32 v2, v1, v2
	v_and_b32_e32 v2, 0xfffffc00, v2
	v_sub_u32_e32 v1, v1, v2
	v_lshrrev_b32_e32 v2, 4, v1
	v_bitop3_b32 v2, v2, v1, 32 bitop3:0x6c
	v_ashrrev_i32_e32 v1, 31, v1
	v_lshrrev_b32_e32 v1, 26, v1
	v_add_u32_e32 v1, v2, v1
	v_ashrrev_i32_e32 v13, 6, v1
	v_ashrrev_i32_e32 v1, 31, v16
	v_lshrrev_b32_e32 v1, 26, v1
	v_add_u32_e32 v1, v16, v1
	s_add_u32 s21, s0, 0x30e00000
	v_ashrrev_i32_e32 v14, 6, v1
	s_addc_u32 s22, s1, 0
	v_lshlrev_b32_e32 v1, 3, v14
	s_add_u32 s23, s0, 0x3800000
	v_and_b32_e32 v1, -16, v1
	s_addc_u32 s25, s1, 0
	v_add_u32_e32 v1, v13, v1
	v_and_b32_e32 v3, 3, v13
	s_ashr_i32 s27, s19, 31
	v_and_or_b32 v3, v1, s2, v3
	s_lshr_b32 s2, s27, 29
	s_add_i32 s2, s19, s2
	s_ashr_i32 s3, s20, 6
	s_ashr_i32 s4, s2, 3
	s_and_b32 s2, s2, -8
	s_ashr_i32 s6, s20, 8
	s_lshl_b32 s26, s3, 10
	s_sub_i32 s2, s19, s2
	s_cmp_lt_i32 s2, 0
	s_movk_i32 s33, 0x181
	s_cselect_b32 s5, s33, 0x180
	s_mul_i32 s2, s5, s2
	s_add_i32 s2, s2, s4
	s_mul_hi_i32 s4, s2, 0x2aaaaaab
	s_lshr_b32 s5, s4, 31
	s_ashr_i32 s4, s4, 4
	s_add_i32 s4, s4, s5
	s_lshl_b32 s5, s4, 2
	s_mulk_i32 s4, 0x60
	s_sub_i32 s7, s2, s4
	s_bfe_i32 s2, s7, 0x80000
	s_lshr_b32 s8, s2, 7
	s_bfe_u32 s2, s8, 0x20006
	s_add_i32 s4, s7, s2
	s_bfe_i32 s2, s4, 0x80000
	s_and_b32 s4, s4, 0xfc
	s_sub_i32 s4, s7, s4
	s_sext_i32_i8 s4, s4
	s_add_i32 s4, s5, s4
	s_bfe_u32 s5, s8, 0x50003
	s_add_i32 s7, s7, s5
	v_lshrrev_b32_e32 v4, 2, v1
	v_lshlrev_b32_e32 v5, 1, v1
	s_bfe_i32 s5, s7, 0x80000
	v_and_b32_e32 v4, 4, v4
	v_and_b32_e32 v5, 24, v5
	s_sext_i32_i16 s2, s2
	s_sext_i32_i16 s5, s5
	v_or3_b32 v3, v3, v4, v5
	v_mul_i32_i24_e32 v5, 64, v13
	s_lshr_b32 s2, s2, 2
	s_lshr_b32 s8, s5, 5
	v_sub_u32_e32 v2, v2, v5
	s_bfe_i64 s[8:9], s[8:9], 0x100000
	s_ashr_i32 s5, s4, 31
	s_bfe_i64 s[12:13], s[2:3], 0x100000
	v_lshlrev_b32_e32 v4, 5, v14
	v_ashrrev_i16_sdwa v2, v240, sext(v2) dst_sel:DWORD dst_unused:UNUSED_PAD src0_sel:DWORD src1_sel:BYTE_0
	s_lshl_b64 s[8:9], s[8:9], 26
	s_lshl_b64 s[10:11], s[4:5], 19
	s_lshl_b64 s[12:13], s[12:13], 19
	v_and_b32_e32 v4, 32, v4
	v_bfe_i32 v15, v2, 0, 16
	s_add_u32 s14, s23, s12
	v_add_lshl_u32 v2, v4, v15, 1
	s_addc_u32 s15, s25, s13
	s_add_i32 s5, s26, 0
	v_lshl_add_u32 v134, v3, 11, v2
	s_add_i32 m0, s5, 0x10000
	v_lshl_add_u32 v136, v1, 11, v2
	global_load_lds_dwordx4 v134, s[14:15]
	s_add_i32 m0, s5, 0x12000
	s_add_u32 s7, s21, s8
	s_addc_u32 s8, s22, s9
	s_add_u32 s16, s7, s10
	global_load_lds_dwordx4 v130, s[14:15]
	s_addc_u32 s17, s8, s11
	s_mov_b32 m0, s5
	s_add_i32 s28, s5, 0x2000
	global_load_lds_dwordx4 v136, s[16:17]
	s_mov_b32 m0, s28
	s_add_u32 s8, s14, 0x40000
	global_load_lds_dwordx4 v132, s[16:17]
	s_addc_u32 s9, s15, 0
	s_add_i32 m0, s5, 0x14000
	v_mov_b32_e32 v135, v0
	global_load_lds_dwordx4 v134, s[8:9]
	s_add_i32 m0, s5, 0x16000
	v_mov_b32_e32 v131, v0
	global_load_lds_dwordx4 v130, s[8:9]
	s_add_u32 s8, s16, 0x40000
	s_addc_u32 s9, s17, 0
	s_add_i32 s29, s5, 0x4000
	s_mov_b32 m0, s29
	s_add_i32 s30, s5, 0x6000
	global_load_lds_dwordx4 v136, s[8:9]
	s_mov_b32 m0, s30
	v_mov_b32_e32 v137, v0
	global_load_lds_dwordx4 v132, s[8:9]
	v_mov_b32_e32 v133, v0
	v_lshl_add_u64 v[8:9], s[14:15], 0, v[134:135]
	v_lshl_add_u64 v[6:7], s[14:15], 0, v[130:131]
	v_lshl_add_u64 v[4:5], s[16:17], 0, v[136:137]
	s_cmp_lg_u32 s6, 1
	v_lshl_add_u64 v[2:3], s[16:17], 0, v[132:133]
	s_cbranch_scc1 .LBB0_391
	s_barrier
	s_setprio 1

; #define PG8_STAGE(bufoff, gbase, voff) do { _Pragma("unroll") for (int _i = 0; _i < 2; ++_i) \
;         __builtin_amdgcn_global_load_lds((const unsigned*)((const char*)(gbase) + (voff)[_i]), (LAS unsigned*)(lds + (bufoff) + ldsw + _i * 8192), 16, 0, 0); } while (0)
; #define PG8_LDA(dst, b, h) do { _Pragma("unroll") for (int m = 0; m < 4; ++m) _Pragma("unroll") for (int k = 0; k < 2; ++k) dst[m][k] = *(const LAS bf16x8*)(lds + PG8_SA(b, h) + aoff + m * 2048 + k * 1024); } while (0)
; #define PG8_LDB(dst, b, h) do { _Pragma("unroll") for (int n = 0; n < 2; ++n) _Pragma("unroll") for (int k = 0; k < 2; ++k) dst[n][k] = *(const LAS bf16x8*)(lds + PG8_SB(b, h) + boff + n * 2048 + k * 1024); } while (0)
; #define PG8_MMA(ai, bj, At, Bt) do { __builtin_amdgcn_s_setprio(1); _Pragma("unroll") for (int m = 0; m < 4; ++m) _Pragma("unroll") for (int n = 0; n < 2; ++n) _Pragma("unroll") for (int k = 0; k < 2; ++k) \
;         acc[ai][bj][m][n] = __builtin_amdgcn_mfma_f32_16x16x32_bf16(Bt[n][k], At[m][k], acc[ai][bj][m][n], 0, 0, 0); __builtin_amdgcn_s_setprio(0); } while (0)
; #define PG8_WAIT_V(n) asm volatile("s_waitcnt vmcnt(" #n ")" ::: "memory")
; #define PG8_WAIT_L(n) asm volatile("s_waitcnt lgkmcnt(" #n ")" ::: "memory")
; #define PG8_BAR __builtin_amdgcn_s_barrier()
; #define PG8_SCHED __builtin_amdgcn_sched_barrier(0)
; template <class Epi, class Sched, bool AREMAP>
; __device__ __forceinline__ void gemm_phase(LAS unsigned char* lds, const Gemm g, const Sched& S, const Epi& E, int wv) {
;     ...
;             PG8_LDB(B0, 0, 0); PG8_SCHED; PG8_LDA(At, 0, 0); PG8_STAGE(PG8_SA(1, 1), a1 + hstepA, voffA);
;             PG8_WAIT_L(8); PG8_BAR; PG8_WAIT_L(0); PG8_MMA(0, 0, At, B0); PG8_BAR; PG8_SCHED;
;             PG8_LDB(B1, 0, 1); PG8_STAGE(PG8_SB(0, 0), b2, voffB);
;             PG8_BAR; PG8_WAIT_L(0); PG8_MMA(0, 1, At, B1); PG8_BAR;
;             PG8_LDA(At, 0, 1); PG8_STAGE(PG8_SA(0, 0), a2, voffA);
;             PG8_BAR; PG8_WAIT_L(0); PG8_MMA(1, 0, At, B0); PG8_BAR; PG8_SCHED;
;             PG8_STAGE(PG8_SB(0, 1), b2 + hstepB, voffB);
;             PG8_WAIT_V(6); PG8_BAR; PG8_MMA(1, 1, At, B1); PG8_BAR;
.LBB0_397:
	s_add_u32 s14, s2, 0xfffc0080
	s_addc_u32 s15, s3, -1
	s_add_i32 s38, 0, 0x10000
	v_add_u32_e32 v145, s38, v142
	ds_read_b128 v[146:149], v145
	ds_read_b128 v[150:153], v145 offset:1024
	ds_read_b128 v[154:157], v145 offset:2048
	ds_read_b128 v[158:161], v145 offset:3072
	s_cmp_eq_u32 s53, 12
	s_cselect_b32 s17, s11, s15
	s_cselect_b32 s16, s10, s14
	s_cselect_b32 s15, s7, s52
	s_cselect_b32 s14, s9, s47
	v_lshl_add_u64 v[186:187], s[2:3], 0, v[140:141]
	s_add_i32 m0, s5, 0xc000
	ds_read_b128 v[162:165], v144
	ds_read_b128 v[166:169], v144 offset:1024
	ds_read_b128 v[170:173], v144 offset:2048
	ds_read_b128 v[174:177], v144 offset:3072
	ds_read_b128 v[178:181], v144 offset:4096
	ds_read_b128 v[182:185], v144 offset:5120
	ds_read_b128 v[192:195], v144 offset:6144
	ds_read_b128 v[196:199], v144 offset:7168
	global_load_lds_dwordx4 v[186:187], off
	v_lshl_add_u64 v[186:187], s[2:3], 0, v[138:139]
	s_add_i32 m0, s5, 0xe000
	s_nop 0
	global_load_lds_dwordx4 v[186:187], off
	s_waitcnt lgkmcnt(8)
	s_barrier
	s_waitcnt lgkmcnt(0)
	s_waitcnt lgkmcnt(0)
	v_mfma_f32_16x16x32_bf16 v[126:129], v[146:149], v[162:165], v[126:129]
	v_mfma_f32_16x16x32_bf16 v[122:125], v[154:157], v[162:165], v[122:125]
	v_mfma_f32_16x16x32_bf16 v[118:121], v[146:149], v[170:173], v[118:121]
	v_mfma_f32_16x16x32_bf16 v[114:117], v[154:157], v[170:173], v[114:117]
	v_mfma_f32_16x16x32_bf16 v[102:105], v[146:149], v[178:181], v[102:105]
	v_mfma_f32_16x16x32_bf16 v[98:101], v[154:157], v[178:181], v[98:101]
	v_mfma_f32_16x16x32_bf16 v[86:89], v[146:149], v[192:195], v[86:89]
	v_mfma_f32_16x16x32_bf16 v[82:85], v[154:157], v[192:195], v[82:85]
	v_mfma_f32_16x16x32_bf16 v[126:129], v[150:153], v[166:169], v[126:129]
	v_mfma_f32_16x16x32_bf16 v[122:125], v[158:161], v[166:169], v[122:125]
	v_mfma_f32_16x16x32_bf16 v[118:121], v[150:153], v[174:177], v[118:121]
	v_mfma_f32_16x16x32_bf16 v[114:117], v[158:161], v[174:177], v[114:117]
	v_mfma_f32_16x16x32_bf16 v[102:105], v[150:153], v[182:185], v[102:105]
	v_mfma_f32_16x16x32_bf16 v[98:101], v[158:161], v[182:185], v[98:101]
	v_mfma_f32_16x16x32_bf16 v[86:89], v[150:153], v[196:199], v[86:89]
	v_mfma_f32_16x16x32_bf16 v[82:85], v[158:161], v[196:199], v[82:85]
	s_barrier
	s_add_i32 s39, 0, 0x14000
	s_add_i32 s38, s38, s26
	v_add_u32_e32 v145, s39, v142
	v_lshl_add_u64 v[186:187], s[14:15], 0, v[134:135]
	s_mov_b32 m0, s38
	ds_read_b128 v[200:203], v145
	ds_read_b128 v[204:207], v145 offset:1024
	ds_read_b128 v[208:211], v145 offset:2048
	ds_read_b128 v[212:215], v145 offset:3072
	global_load_lds_dwordx4 v[186:187], off
	v_lshl_add_u64 v[216:217], s[14:15], 0, v[130:131]
	s_add_i32 m0, s38, 0x2000
	s_nop 0
	global_load_lds_dwordx4 v[216:217], off
	s_barrier
	s_waitcnt lgkmcnt(0)
	s_waitcnt lgkmcnt(0)
	v_mfma_f32_16x16x32_bf16 v[110:113], v[200:203], v[162:165], v[110:113]
	v_mfma_f32_16x16x32_bf16 v[106:109], v[208:211], v[162:165], v[106:109]
	v_mfma_f32_16x16x32_bf16 v[94:97], v[200:203], v[170:173], v[94:97]
	v_mfma_f32_16x16x32_bf16 v[90:93], v[208:211], v[170:173], v[90:93]
	v_mfma_f32_16x16x32_bf16 v[78:81], v[200:203], v[178:181], v[78:81]
	v_mfma_f32_16x16x32_bf16 v[74:77], v[208:211], v[178:181], v[74:77]
	v_mfma_f32_16x16x32_bf16 v[70:73], v[200:203], v[192:195], v[70:73]
	v_mfma_f32_16x16x32_bf16 v[66:69], v[208:211], v[192:195], v[66:69]
	v_mfma_f32_16x16x32_bf16 v[110:113], v[204:207], v[166:169], v[110:113]
	v_mfma_f32_16x16x32_bf16 v[106:109], v[212:215], v[166:169], v[106:109]
	v_mfma_f32_16x16x32_bf16 v[94:97], v[204:207], v[174:177], v[94:97]
	v_mfma_f32_16x16x32_bf16 v[90:93], v[212:215], v[174:177], v[90:93]
	v_mfma_f32_16x16x32_bf16 v[78:81], v[204:207], v[182:185], v[78:81]
	v_mfma_f32_16x16x32_bf16 v[74:77], v[212:215], v[182:185], v[74:77]
	v_mfma_f32_16x16x32_bf16 v[70:73], v[204:207], v[196:199], v[70:73]
	v_mfma_f32_16x16x32_bf16 v[66:69], v[212:215], v[196:199], v[66:69]
	s_mov_b32 m0, s5
	v_lshl_add_u64 v[218:219], s[16:17], 0, v[136:137]
	s_barrier
	ds_read_b128 v[162:165], v144 offset:16384
	ds_read_b128 v[166:169], v144 offset:17408
	ds_read_b128 v[170:173], v144 offset:18432
	ds_read_b128 v[174:177], v144 offset:19456
	ds_read_b128 v[178:181], v144 offset:20480
	ds_read_b128 v[182:185], v144 offset:21504
	ds_read_b128 v[192:195], v144 offset:22528
	ds_read_b128 v[196:199], v144 offset:23552
	global_load_lds_dwordx4 v[218:219], off
	v_lshl_add_u64 v[220:221], s[16:17], 0, v[132:133]
	s_mov_b32 m0, s28
	s_nop 0
	global_load_lds_dwordx4 v[220:221], off
	s_barrier
	s_waitcnt lgkmcnt(0)
	s_waitcnt lgkmcnt(0)
	v_mfma_f32_16x16x32_bf16 v[62:65], v[146:149], v[162:165], v[62:65]
	v_mfma_f32_16x16x32_bf16 v[58:61], v[154:157], v[162:165], v[58:61]
	v_mfma_f32_16x16x32_bf16 v[54:57], v[146:149], v[170:173], v[54:57]
	v_mfma_f32_16x16x32_bf16 v[50:53], v[154:157], v[170:173], v[50:53]
	v_mfma_f32_16x16x32_bf16 v[38:41], v[146:149], v[178:181], v[38:41]
	v_mfma_f32_16x16x32_bf16 v[34:37], v[154:157], v[178:181], v[34:37]
	v_mfma_f32_16x16x32_bf16 v[22:25], v[146:149], v[192:195], v[22:25]
	v_mfma_f32_16x16x32_bf16 v[18:21], v[154:157], v[192:195], v[18:21]
	v_mfma_f32_16x16x32_bf16 v[62:65], v[150:153], v[166:169], v[62:65]
	v_mfma_f32_16x16x32_bf16 v[58:61], v[158:161], v[166:169], v[58:61]
	v_mfma_f32_16x16x32_bf16 v[54:57], v[150:153], v[174:177], v[54:57]
	v_mfma_f32_16x16x32_bf16 v[50:53], v[158:161], v[174:177], v[50:53]
	v_mfma_f32_16x16x32_bf16 v[38:41], v[150:153], v[182:185], v[38:41]
	v_mfma_f32_16x16x32_bf16 v[34:37], v[158:161], v[182:185], v[34:37]
	v_mfma_f32_16x16x32_bf16 v[22:25], v[150:153], v[196:199], v[22:25]
	v_mfma_f32_16x16x32_bf16 v[18:21], v[158:161], v[196:199], v[18:21]
	s_barrier
; #define PG8_STAGE(bufoff, gbase, voff) do { _Pragma("unroll") for (int _i = 0; _i < 2; ++_i) \
;         __builtin_amdgcn_global_load_lds((const unsigned*)((const char*)(gbase) + (voff)[_i]), (LAS unsigned*)(lds + (bufoff) + ldsw + _i * 8192), 16, 0, 0); } while (0)
; #define PG8_LDA(dst, b, h) do { _Pragma("unroll") for (int m = 0; m < 4; ++m) _Pragma("unroll") for (int k = 0; k < 2; ++k) dst[m][k] = *(const LAS bf16x8*)(lds + PG8_SA(b, h) + aoff + m * 2048 + k * 1024); } while (0)
; #define PG8_LDB(dst, b, h) do { _Pragma("unroll") for (int n = 0; n < 2; ++n) _Pragma("unroll") for (int k = 0; k < 2; ++k) dst[n][k] = *(const LAS bf16x8*)(lds + PG8_SB(b, h) + boff + n * 2048 + k * 1024); } while (0)
; #define PG8_MMA(ai, bj, At, Bt) do { __builtin_amdgcn_s_setprio(1); _Pragma("unroll") for (int m = 0; m < 4; ++m) _Pragma("unroll") for (int n = 0; n < 2; ++n) _Pragma("unroll") for (int k = 0; k < 2; ++k) \
;         acc[ai][bj][m][n] = __builtin_amdgcn_mfma_f32_16x16x32_bf16(Bt[n][k], At[m][k], acc[ai][bj][m][n], 0, 0, 0); __builtin_amdgcn_s_setprio(0); } while (0)
; #define PG8_WAIT_V(n) asm volatile("s_waitcnt vmcnt(" #n ")" ::: "memory")
; #define PG8_WAIT_L(n) asm volatile("s_waitcnt lgkmcnt(" #n ")" ::: "memory")
; #define PG8_BAR __builtin_amdgcn_s_barrier()
; #define PG8_SCHED __builtin_amdgcn_sched_barrier(0)
; template <class Epi, class Sched, bool AREMAP>
; __device__ __forceinline__ void gemm_phase(LAS unsigned char* lds, const Gemm g, const Sched& S, const Epi& E, int wv) {
;     ...
;             PG8_LDA(At, 0, 1); PG8_STAGE(PG8_SA(0, 0), a2, voffA);
;             PG8_BAR; PG8_WAIT_L(0); PG8_MMA(1, 0, At, B0); PG8_BAR; PG8_SCHED;
;             PG8_STAGE(PG8_SB(0, 1), b2 + hstepB, voffB);
;             PG8_WAIT_V(6); PG8_BAR; PG8_MMA(1, 1, At, B1); PG8_BAR;
;             PG8_LDB(B0, 1, 0); PG8_SCHED; PG8_LDA(At, 1, 0); PG8_STAGE(PG8_SA(0, 1), a2 + hstepA, voffA);
;             PG8_WAIT_L(8); PG8_BAR; PG8_WAIT_L(0); PG8_MMA(0, 0, At, B0); PG8_BAR; PG8_SCHED;
;             PG8_LDB(B1, 1, 1); PG8_STAGE(PG8_SB(1, 0), b3, voffB);
;             PG8_BAR; PG8_WAIT_L(0); PG8_MMA(0, 1, At, B1); PG8_BAR;
;             PG8_LDA(At, 1, 1); PG8_STAGE(PG8_SA(1, 0), a3, voffA);
;             PG8_BAR; PG8_WAIT_L(0); PG8_MMA(1, 0, At, B0); PG8_BAR; PG8_SCHED;
	s_add_u32 s56, s14, 0x40000
	s_addc_u32 s57, s15, 0
	s_add_i32 s38, s39, s26
	v_lshl_add_u64 v[146:147], s[56:57], 0, v[134:135]
	s_mov_b32 m0, s38
	s_nop 0
	global_load_lds_dwordx4 v[146:147], off
	v_lshl_add_u64 v[146:147], s[56:57], 0, v[130:131]
	s_add_i32 m0, s38, 0x2000
	s_nop 0
	global_load_lds_dwordx4 v[146:147], off
	s_waitcnt vmcnt(6)
	s_barrier
	v_mfma_f32_16x16x32_bf16 v[46:49], v[200:203], v[162:165], v[46:49]
	v_mfma_f32_16x16x32_bf16 v[42:45], v[208:211], v[162:165], v[42:45]
	v_mfma_f32_16x16x32_bf16 v[30:33], v[200:203], v[170:173], v[30:33]
	v_mfma_f32_16x16x32_bf16 v[26:29], v[208:211], v[170:173], v[26:29]
	v_mfma_f32_16x16x32_bf16 v[14:17], v[200:203], v[178:181], v[14:17]
	v_mfma_f32_16x16x32_bf16 v[10:13], v[208:211], v[178:181], v[10:13]
	v_mfma_f32_16x16x32_bf16 v[6:9], v[200:203], v[192:195], v[6:9]
	v_mfma_f32_16x16x32_bf16 v[2:5], v[208:211], v[192:195], v[2:5]
	v_mfma_f32_16x16x32_bf16 v[46:49], v[204:207], v[166:169], v[46:49]
	v_mfma_f32_16x16x32_bf16 v[42:45], v[212:215], v[166:169], v[42:45]
	v_mfma_f32_16x16x32_bf16 v[30:33], v[204:207], v[174:177], v[30:33]
	v_mfma_f32_16x16x32_bf16 v[26:29], v[212:215], v[174:177], v[26:29]
	v_mfma_f32_16x16x32_bf16 v[14:17], v[204:207], v[182:185], v[14:17]
	v_mfma_f32_16x16x32_bf16 v[10:13], v[212:215], v[182:185], v[10:13]
	v_mfma_f32_16x16x32_bf16 v[6:9], v[204:207], v[196:199], v[6:9]
	v_mfma_f32_16x16x32_bf16 v[2:5], v[212:215], v[196:199], v[2:5]
	s_add_i32 s38, 0, 0x18000
	v_add_u32_e32 v145, s38, v142
	s_barrier
	ds_read_b128 v[146:149], v145
	ds_read_b128 v[150:153], v145 offset:1024
	ds_read_b128 v[154:157], v145 offset:2048
	ds_read_b128 v[158:161], v145 offset:3072
	s_add_u32 s16, s16, 0x40000
	s_addc_u32 s17, s17, 0
	s_mov_b32 m0, s29
	v_lshl_add_u64 v[200:201], s[16:17], 0, v[136:137]
	ds_read_b128 v[162:165], v144 offset:32768
	ds_read_b128 v[166:169], v144 offset:33792
	ds_read_b128 v[170:173], v144 offset:34816
	ds_read_b128 v[174:177], v144 offset:35840
	ds_read_b128 v[178:181], v144 offset:36864
	ds_read_b128 v[182:185], v144 offset:37888
	ds_read_b128 v[192:195], v144 offset:38912
	ds_read_b128 v[196:199], v144 offset:39936
	global_load_lds_dwordx4 v[200:201], off
	v_lshl_add_u64 v[200:201], s[16:17], 0, v[132:133]
	s_mov_b32 m0, s30
	s_nop 0
	global_load_lds_dwordx4 v[200:201], off
	s_waitcnt lgkmcnt(8)
	s_barrier
	s_waitcnt lgkmcnt(0)
	s_waitcnt lgkmcnt(0)
	v_mfma_f32_16x16x32_bf16 v[126:129], v[146:149], v[162:165], v[126:129]
	v_mfma_f32_16x16x32_bf16 v[122:125], v[154:157], v[162:165], v[122:125]
	v_mfma_f32_16x16x32_bf16 v[118:121], v[146:149], v[170:173], v[118:121]
	v_mfma_f32_16x16x32_bf16 v[114:117], v[154:157], v[170:173], v[114:117]
	v_mfma_f32_16x16x32_bf16 v[102:105], v[146:149], v[178:181], v[102:105]
	v_mfma_f32_16x16x32_bf16 v[98:101], v[154:157], v[178:181], v[98:101]
	v_mfma_f32_16x16x32_bf16 v[86:89], v[146:149], v[192:195], v[86:89]
	v_mfma_f32_16x16x32_bf16 v[82:85], v[154:157], v[192:195], v[82:85]
	v_mfma_f32_16x16x32_bf16 v[126:129], v[150:153], v[166:169], v[126:129]
	v_mfma_f32_16x16x32_bf16 v[122:125], v[158:161], v[166:169], v[122:125]
	v_mfma_f32_16x16x32_bf16 v[118:121], v[150:153], v[174:177], v[118:121]
	v_mfma_f32_16x16x32_bf16 v[114:117], v[158:161], v[174:177], v[114:117]
	v_mfma_f32_16x16x32_bf16 v[102:105], v[150:153], v[182:185], v[102:105]
	v_mfma_f32_16x16x32_bf16 v[98:101], v[158:161], v[182:185], v[98:101]
	v_mfma_f32_16x16x32_bf16 v[86:89], v[150:153], v[196:199], v[86:89]
	v_mfma_f32_16x16x32_bf16 v[82:85], v[158:161], v[196:199], v[82:85]
	s_barrier
	s_add_i32 s16, 0, 0x1c000
	s_add_i32 s17, s38, s26
	v_add_u32_e32 v145, s16, v142
	v_lshl_add_u64 v[186:187], v[186:187], 0, s[86:87]
	s_mov_b32 m0, s17
	ds_read_b128 v[200:203], v145
	ds_read_b128 v[204:207], v145 offset:1024
	ds_read_b128 v[208:211], v145 offset:2048
	ds_read_b128 v[212:215], v145 offset:3072
	global_load_lds_dwordx4 v[186:187], off
	v_lshl_add_u64 v[186:187], v[216:217], 0, s[86:87]
	s_add_i32 m0, s17, 0x2000
	s_nop 0
	global_load_lds_dwordx4 v[186:187], off
	s_barrier
	s_waitcnt lgkmcnt(0)
	s_waitcnt lgkmcnt(0)
	v_mfma_f32_16x16x32_bf16 v[110:113], v[200:203], v[162:165], v[110:113]
	v_mfma_f32_16x16x32_bf16 v[106:109], v[208:211], v[162:165], v[106:109]
	v_mfma_f32_16x16x32_bf16 v[94:97], v[200:203], v[170:173], v[94:97]
	v_mfma_f32_16x16x32_bf16 v[90:93], v[208:211], v[170:173], v[90:93]
	v_mfma_f32_16x16x32_bf16 v[78:81], v[200:203], v[178:181], v[78:81]
	v_mfma_f32_16x16x32_bf16 v[74:77], v[208:211], v[178:181], v[74:77]
	v_mfma_f32_16x16x32_bf16 v[70:73], v[200:203], v[192:195], v[70:73]
	v_mfma_f32_16x16x32_bf16 v[66:69], v[208:211], v[192:195], v[66:69]
	v_mfma_f32_16x16x32_bf16 v[110:113], v[204:207], v[166:169], v[110:113]
	v_mfma_f32_16x16x32_bf16 v[106:109], v[212:215], v[166:169], v[106:109]
	v_mfma_f32_16x16x32_bf16 v[94:97], v[204:207], v[174:177], v[94:97]
	v_mfma_f32_16x16x32_bf16 v[90:93], v[212:215], v[174:177], v[90:93]
	v_mfma_f32_16x16x32_bf16 v[78:81], v[204:207], v[182:185], v[78:81]
	v_mfma_f32_16x16x32_bf16 v[74:77], v[212:215], v[182:185], v[74:77]
	v_mfma_f32_16x16x32_bf16 v[70:73], v[204:207], v[196:199], v[70:73]
	v_mfma_f32_16x16x32_bf16 v[66:69], v[212:215], v[196:199], v[66:69]
	s_mov_b32 m0, s35
	v_lshl_add_u64 v[186:187], v[218:219], 0, s[86:87]
	s_barrier
	ds_read_b128 v[162:165], v144 offset:49152
	ds_read_b128 v[166:169], v144 offset:50176
	ds_read_b128 v[170:173], v144 offset:51200
	ds_read_b128 v[174:177], v144 offset:52224
	ds_read_b128 v[178:181], v144 offset:53248
	ds_read_b128 v[182:185], v144 offset:54272
	ds_read_b128 v[192:195], v144 offset:55296
	ds_read_b128 v[196:199], v144 offset:56320
	global_load_lds_dwordx4 v[186:187], off
	v_lshl_add_u64 v[186:187], v[220:221], 0, s[86:87]
	s_mov_b32 m0, s36
	s_nop 0
	global_load_lds_dwordx4 v[186:187], off
	s_barrier
; #define PG8_STAGE(bufoff, gbase, voff) do { _Pragma("unroll") for (int _i = 0; _i < 2; ++_i) \
;         __builtin_amdgcn_global_load_lds((const unsigned*)((const char*)(gbase) + (voff)[_i]), (LAS unsigned*)(lds + (bufoff) + ldsw + _i * 8192), 16, 0, 0); } while (0)
; #define PG8_LDA(dst, b, h) do { _Pragma("unroll") for (int m = 0; m < 4; ++m) _Pragma("unroll") for (int k = 0; k < 2; ++k) dst[m][k] = *(const LAS bf16x8*)(lds + PG8_SA(b, h) + aoff + m * 2048 + k * 1024); } while (0)
; #define PG8_MMA(ai, bj, At, Bt) do { __builtin_amdgcn_s_setprio(1); _Pragma("unroll") for (int m = 0; m < 4; ++m) _Pragma("unroll") for (int n = 0; n < 2; ++n) _Pragma("unroll") for (int k = 0; k < 2; ++k) \
;         acc[ai][bj][m][n] = __builtin_amdgcn_mfma_f32_16x16x32_bf16(Bt[n][k], At[m][k], acc[ai][bj][m][n], 0, 0, 0); __builtin_amdgcn_s_setprio(0); } while (0)
; #define PG8_WAIT_V(n) asm volatile("s_waitcnt vmcnt(" #n ")" ::: "memory")
; #define PG8_WAIT_L(n) asm volatile("s_waitcnt lgkmcnt(" #n ")" ::: "memory")
; #define PG8_BAR __builtin_amdgcn_s_barrier()
; #define PG8_SCHED __builtin_amdgcn_sched_barrier(0)
; template <class Epi, class Sched, bool AREMAP>
; __device__ __forceinline__ void gemm_phase(LAS unsigned char* lds, const Gemm g, const Sched& S, const Epi& E, int wv) {
;     ...
;             PG8_BAR; PG8_WAIT_L(0); PG8_MMA(0, 1, At, B1); PG8_BAR;
;             PG8_LDA(At, 1, 1); PG8_STAGE(PG8_SA(1, 0), a3, voffA);
;             PG8_BAR; PG8_WAIT_L(0); PG8_MMA(1, 0, At, B0); PG8_BAR; PG8_SCHED;
;             PG8_STAGE(PG8_SB(1, 1), b3 + hstepB, voffB);
;             PG8_WAIT_V(6); PG8_BAR; PG8_MMA(1, 1, At, B1); PG8_BAR;
	s_waitcnt lgkmcnt(0)
	s_waitcnt lgkmcnt(0)
	v_mfma_f32_16x16x32_bf16 v[62:65], v[146:149], v[162:165], v[62:65]
	v_mfma_f32_16x16x32_bf16 v[58:61], v[154:157], v[162:165], v[58:61]
	v_mfma_f32_16x16x32_bf16 v[54:57], v[146:149], v[170:173], v[54:57]
	v_mfma_f32_16x16x32_bf16 v[50:53], v[154:157], v[170:173], v[50:53]
	v_mfma_f32_16x16x32_bf16 v[38:41], v[146:149], v[178:181], v[38:41]
	v_mfma_f32_16x16x32_bf16 v[34:37], v[154:157], v[178:181], v[34:37]
	v_mfma_f32_16x16x32_bf16 v[22:25], v[146:149], v[192:195], v[22:25]
	v_mfma_f32_16x16x32_bf16 v[18:21], v[154:157], v[192:195], v[18:21]
	v_mfma_f32_16x16x32_bf16 v[62:65], v[150:153], v[166:169], v[62:65]
	v_mfma_f32_16x16x32_bf16 v[58:61], v[158:161], v[166:169], v[58:61]
	v_mfma_f32_16x16x32_bf16 v[54:57], v[150:153], v[174:177], v[54:57]
	v_mfma_f32_16x16x32_bf16 v[50:53], v[158:161], v[174:177], v[50:53]
	v_mfma_f32_16x16x32_bf16 v[38:41], v[150:153], v[182:185], v[38:41]
	v_mfma_f32_16x16x32_bf16 v[34:37], v[158:161], v[182:185], v[34:37]
	v_mfma_f32_16x16x32_bf16 v[22:25], v[150:153], v[196:199], v[22:25]
	v_mfma_f32_16x16x32_bf16 v[18:21], v[158:161], v[196:199], v[18:21]
	s_barrier
	s_add_u32 s14, s14, 0x40080
	s_addc_u32 s15, s15, 0
	s_add_i32 s16, s16, s26
	v_lshl_add_u64 v[146:147], s[14:15], 0, v[134:135]
	s_mov_b32 m0, s16
	s_nop 0
	global_load_lds_dwordx4 v[146:147], off
	v_lshl_add_u64 v[146:147], s[14:15], 0, v[130:131]
	s_add_i32 m0, s16, 0x2000
	s_nop 0
	global_load_lds_dwordx4 v[146:147], off
	s_waitcnt vmcnt(6)
	s_barrier
	v_mfma_f32_16x16x32_bf16 v[46:49], v[200:203], v[162:165], v[46:49]
	v_mfma_f32_16x16x32_bf16 v[42:45], v[208:211], v[162:165], v[42:45]
	v_mfma_f32_16x16x32_bf16 v[30:33], v[200:203], v[170:173], v[30:33]
	v_mfma_f32_16x16x32_bf16 v[26:29], v[208:211], v[170:173], v[26:29]
	v_mfma_f32_16x16x32_bf16 v[14:17], v[200:203], v[178:181], v[14:17]
	v_mfma_f32_16x16x32_bf16 v[10:13], v[208:211], v[178:181], v[10:13]
	v_mfma_f32_16x16x32_bf16 v[6:9], v[200:203], v[192:195], v[6:9]
	v_mfma_f32_16x16x32_bf16 v[2:5], v[208:211], v[192:195], v[2:5]
	v_mfma_f32_16x16x32_bf16 v[46:49], v[204:207], v[166:169], v[46:49]
	v_mfma_f32_16x16x32_bf16 v[42:45], v[212:215], v[166:169], v[42:45]
	v_mfma_f32_16x16x32_bf16 v[30:33], v[204:207], v[174:177], v[30:33]
	v_mfma_f32_16x16x32_bf16 v[26:29], v[212:215], v[174:177], v[26:29]
	v_mfma_f32_16x16x32_bf16 v[14:17], v[204:207], v[182:185], v[14:17]
	v_mfma_f32_16x16x32_bf16 v[10:13], v[212:215], v[182:185], v[10:13]
	v_mfma_f32_16x16x32_bf16 v[6:9], v[204:207], v[196:199], v[6:9]
	v_mfma_f32_16x16x32_bf16 v[2:5], v[212:215], v[196:199], v[2:5]
	s_add_i32 s53, s53, 2
	s_add_u32 s47, s47, 0x100
	s_addc_u32 s52, s52, 0
	s_add_u32 s2, s2, 0x100
	s_addc_u32 s3, s3, 0
	s_cmp_gt_u32 s53, 13
	s_barrier
	s_cbranch_scc0 .LBB0_397
; __device__ __forceinline__ unsigned cvt_pk_bf16(float lo, float hi) { f32x2_t f = {lo, hi}; bf16x2_t v = __builtin_convertvector(f, bf16x2_t); return __builtin_bit_cast(unsigned, v); }
;     __device__ __forceinline__ void operator()(const f32x4 (&acc)[2][2][4][2], const Unit& u, int wr, int wc, int fr, int fq) const {
;         const int row0 = u.pm * BM + wr * 64 + fr; int colt = u.pn * BM; bf16_t* base = O;
;         if (split_cols) { const int t = colt / split_cols; base += (size_t)t * split_stride; colt -= t * split_cols; }
;         const int col0 = colt + wc * 32 + 8 * fq;
; #pragma unroll
;         for (int ai = 0; ai < 2; ++ai)
; #pragma unroll
;             for (int m = 0; m < 4; ++m) { bf16_t* rowp = base + (size_t)(row0 + ai * HALF + m * 16) * ldc + col0;
; #pragma unroll
;                 for (int bj = 0; bj < 2; ++bj) { const f32x4 v0 = acc[ai][bj][m][0], v1 = acc[ai][bj][m][1];
;                     u32x4 w; w.x = cvt_pk_bf16(v0[0], v0[1]); w.y = cvt_pk_bf16(v0[2], v0[3]); w.z = cvt_pk_bf16(v1[0], v1[1]); w.w = cvt_pk_bf16(v1[2], v1[3]);
;                     *(u32x4*)(rowp + bj * HALF) = w; } }
	s_ashr_i32 s2, s46, 31
	s_lshr_b32 s2, s2, 29
	s_add_i32 s2, s46, s2
	s_ashr_i32 s2, s2, 3
	s_ashr_i32 s3, s2, 31
	s_lshl_b32 s7, s46, 8
	s_lshl_b64 s[14:15], s[2:3], 27
	s_add_u32 s14, s31, s14
	s_addc_u32 s15, s34, s15
	s_lshl_b32 s2, s2, 11
	s_sub_i32 s2, s7, s2
	v_lshl_add_u32 v146, s4, 8, v1
	v_or_b32_e32 v148, s2, v143
	v_ashrrev_i32_e32 v149, 31, v148
	v_ashrrev_i32_e32 v147, 31, v146
	v_lshl_add_u64 v[148:149], v[148:149], 1, s[14:15]
	v_lshlrev_b64 v[150:151], 12, v[146:147]
	v_lshl_add_u64 v[150:151], v[148:149], 0, v[150:151]
	s_mov_b64 s[2:3], 0x80000
	v_cvt_pk_bf16_f32 v70, v70, v71
	v_cvt_pk_bf16_f32 v71, v72, v73
	v_cvt_pk_bf16_f32 v72, v66, v67
	v_lshl_add_u64 v[66:67], v[150:151], 0, s[2:3]
	s_mov_b32 s2, 0x80000
	v_cvt_pk_bf16_f32 v62, v62, v63
	v_cvt_pk_bf16_f32 v63, v64, v65
	v_cvt_pk_bf16_f32 v64, v58, v59
	v_add_co_u32_e32 v58, vcc, s2, v150
	v_cvt_pk_bf16_f32 v46, v46, v47
	v_cvt_pk_bf16_f32 v47, v48, v49
	v_cvt_pk_bf16_f32 v48, v42, v43
	v_cvt_pk_bf16_f32 v49, v44, v45
	s_mov_b64 s[2:3], 0x90000
	v_addc_co_u32_e32 v59, vcc, 0, v151, vcc
	global_store_dwordx4 v[66:67], v[46:49], off offset:256
	v_cvt_pk_bf16_f32 v30, v30, v31
	v_cvt_pk_bf16_f32 v31, v32, v33
	v_lshl_add_u64 v[46:47], v[150:151], 0, s[2:3]
	s_mov_b32 s2, 0x90000
	v_add_co_u32_e32 v48, vcc, s2, v150
	v_cvt_pk_bf16_f32 v32, v26, v27
	v_cvt_pk_bf16_f32 v33, v28, v29
	s_mov_b64 s[2:3], 0xa0000
	v_cvt_pk_bf16_f32 v110, v110, v111
	v_cvt_pk_bf16_f32 v111, v112, v113
	v_cvt_pk_bf16_f32 v112, v106, v107
	v_or_b32_e32 v106, 16, v146
	v_addc_co_u32_e32 v49, vcc, 0, v151, vcc
	global_store_dwordx4 v[46:47], v[30:33], off offset:256
	v_ashrrev_i32_e32 v107, 31, v106
	v_cvt_pk_bf16_f32 v94, v94, v95
	v_lshl_add_u64 v[30:31], v[150:151], 0, s[2:3]
	s_mov_b32 s2, 0xa0000
	v_cvt_pk_bf16_f32 v95, v96, v97
	v_cvt_pk_bf16_f32 v96, v90, v91
	v_or_b32_e32 v90, 32, v146
	v_add_co_u32_e32 v32, vcc, s2, v150
	v_cvt_pk_bf16_f32 v14, v14, v15
	v_cvt_pk_bf16_f32 v15, v16, v17
	v_cvt_pk_bf16_f32 v16, v10, v11
	v_cvt_pk_bf16_f32 v17, v12, v13
	s_mov_b64 s[2:3], 0xb0000
	v_cvt_pk_bf16_f32 v113, v108, v109
	v_lshlrev_b64 v[106:107], 12, v[106:107]
	v_ashrrev_i32_e32 v91, 31, v90
	v_cvt_pk_bf16_f32 v78, v78, v79
	v_cvt_pk_bf16_f32 v79, v80, v81
	v_cvt_pk_bf16_f32 v80, v74, v75
	v_or_b32_e32 v74, 48, v146
	v_addc_co_u32_e32 v33, vcc, 0, v151, vcc
	global_store_dwordx4 v[30:31], v[14:17], off offset:256
	global_store_dwordx4 v[150:151], v[110:113], off offset:256
	v_cvt_pk_bf16_f32 v97, v92, v93
	v_lshl_add_u64 v[14:15], v[150:151], 0, s[2:3]
	s_mov_b32 s2, 0xb0000
	v_lshl_add_u64 v[110:111], v[148:149], 0, v[106:107]
	v_lshlrev_b64 v[90:91], 12, v[90:91]
	v_ashrrev_i32_e32 v75, 31, v74
	v_add_co_u32_e32 v16, vcc, s2, v150
	global_store_dwordx4 v[110:111], v[94:97], off offset:256
	v_cvt_pk_bf16_f32 v81, v76, v77
	v_lshlrev_b64 v[74:75], 12, v[74:75]
	v_lshl_add_u64 v[94:95], v[148:149], 0, v[90:91]
	v_addc_co_u32_e32 v17, vcc, 0, v151, vcc
	v_cvt_pk_bf16_f32 v126, v126, v127
	v_cvt_pk_bf16_f32 v127, v128, v129
	v_cvt_pk_bf16_f32 v128, v122, v123
	v_cvt_pk_bf16_f32 v129, v124, v125
	v_cvt_pk_bf16_f32 v106, v118, v119
	v_cvt_pk_bf16_f32 v107, v120, v121
	v_cvt_pk_bf16_f32 v108, v114, v115
	v_cvt_pk_bf16_f32 v109, v116, v117
	v_cvt_pk_bf16_f32 v90, v102, v103
	v_cvt_pk_bf16_f32 v91, v104, v105
	v_cvt_pk_bf16_f32 v92, v98, v99
	v_cvt_pk_bf16_f32 v93, v100, v101
	global_store_dwordx4 v[94:95], v[78:81], off offset:256
	v_cvt_pk_bf16_f32 v76, v82, v83
	v_cvt_pk_bf16_f32 v77, v84, v85
	v_lshl_add_u64 v[78:79], v[148:149], 0, v[74:75]
	v_cvt_pk_bf16_f32 v74, v86, v87
	v_cvt_pk_bf16_f32 v75, v88, v89
	v_cvt_pk_bf16_f32 v73, v68, v69
	v_cvt_pk_bf16_f32 v65, v60, v61
	v_cvt_pk_bf16_f32 v42, v54, v55
	v_cvt_pk_bf16_f32 v43, v56, v57
	v_cvt_pk_bf16_f32 v44, v50, v51
	v_cvt_pk_bf16_f32 v45, v52, v53
	v_cvt_pk_bf16_f32 v26, v38, v39
	v_cvt_pk_bf16_f32 v27, v40, v41
	v_cvt_pk_bf16_f32 v28, v34, v35
	v_cvt_pk_bf16_f32 v29, v36, v37
	v_cvt_pk_bf16_f32 v10, v22, v23
	v_cvt_pk_bf16_f32 v11, v24, v25
	v_cvt_pk_bf16_f32 v12, v18, v19
	v_cvt_pk_bf16_f32 v13, v20, v21
	v_cvt_pk_bf16_f32 v6, v6, v7
	v_cvt_pk_bf16_f32 v7, v8, v9
	v_cvt_pk_bf16_f32 v8, v2, v3
	v_cvt_pk_bf16_f32 v9, v4, v5
	s_and_b64 vcc, exec, s[0:1]
	s_mov_b32 s46, s6
	s_mov_b32 s4, s8
	s_mov_b64 s[14:15], s[12:13]
	s_mov_b64 s[16:17], s[10:11]
	s_mov_b32 s39, 0xb2a5705f
	global_store_dwordx4 v[150:151], v[126:129], off
	global_store_dwordx4 v[110:111], v[106:109], off
	global_store_dwordx4 v[94:95], v[90:93], off
	global_store_dwordx4 v[78:79], v[74:77], off
	global_store_dwordx4 v[78:79], v[70:73], off offset:256
	global_store_dwordx4 v[58:59], v[62:65], off
	global_store_dwordx4 v[48:49], v[42:45], off
	global_store_dwordx4 v[32:33], v[26:29], off
	global_store_dwordx4 v[16:17], v[10:13], off
	global_store_dwordx4 v[14:15], v[6:9], off offset:256
	s_cbranch_vccz .LBB0_392
	s_waitcnt vmcnt(0)
	s_cmpk_gt_u32 s20, 0xff
	v_readlane_b32 s31, v254, 22
	v_readlane_b32 s33, v254, 23
	s_mov_b32 s41, 0xe020
	s_cbranch_scc1 .LBB0_401
	s_barrier

; __device__ __forceinline__ int otid(int wv) { int t = (wv << 6) | (int)__builtin_amdgcn_mbcnt_hi(~0u, __builtin_amdgcn_mbcnt_lo(~0u, 0u)); asm volatile("" : "+v"(t)); return t; }
; __device__ __forceinline__ void grid_bar(unsigned* ctr, unsigned& target, int G, int wv) {
;     asm volatile("s_waitcnt vmcnt(0) lgkmcnt(0)" ::: "memory");
;     __syncthreads();
;     target = (unsigned)__builtin_amdgcn_readfirstlane((int)(target + (unsigned)G));
;     if (otid(wv) == 0) {
;         __builtin_amdgcn_fence(__ATOMIC_RELEASE, "agent");
;         asm volatile("s_waitcnt vmcnt(0)" ::: "memory");
;         __hip_atomic_fetch_add(ctr, 1u, __ATOMIC_RELAXED, __HIP_MEMORY_SCOPE_AGENT);
;         while (__hip_atomic_load(ctr, __ATOMIC_RELAXED, __HIP_MEMORY_SCOPE_AGENT) < target) __builtin_amdgcn_s_sleep(1);
;         __builtin_amdgcn_fence(__ATOMIC_ACQUIRE, "agent");
;         asm volatile("s_waitcnt vmcnt(0)" ::: "memory");
;     }
;     __syncthreads();
; }
.LBB0_402:
	s_setprio 0
	s_waitcnt vmcnt(0) lgkmcnt(0)
	v_mov_b32_e32 v1, v236
	s_waitcnt vmcnt(0) lgkmcnt(0)
	s_barrier
	s_add_i32 s24, s24, s33
	s_nop 0
	v_cmp_eq_u32_e32 vcc, 0, v1
	s_and_saveexec_b64 s[0:1], vcc
	s_cbranch_execz .LBB0_408
	s_mov_b64 s[2:3], exec
	buffer_wbl2 sc1
	s_waitcnt vmcnt(0)
	v_mbcnt_lo_u32_b32 v1, s2, 0
	v_mbcnt_hi_u32_b32 v1, s3, v1
	v_cmp_eq_u32_e32 vcc, 0, v1
	s_and_saveexec_b64 s[4:5], vcc
	s_cbranch_execz .LBB0_405
	s_bcnt1_i32_b64 s2, s[2:3]
	v_mov_b32_e32 v1, s2
	v_readlane_b32 s2, v254, 30
	v_readlane_b32 s3, v254, 31
	s_nop 4
	global_atomic_add v0, v1, s[2:3]

; __device__ __forceinline__ int otid(int wv) { int t = (wv << 6) | (int)__builtin_amdgcn_mbcnt_hi(~0u, __builtin_amdgcn_mbcnt_lo(~0u, 0u)); asm volatile("" : "+v"(t)); return t; }
;     __device__ bool next(int i, Unit& u) const { return map((long)i * G + c, u); }
; #define PG8_WAIT_V(n) asm volatile("s_waitcnt vmcnt(" #n ")" ::: "memory")
; #define PG8_BAR __builtin_amdgcn_s_barrier()
; template <class Epi, class Sched, bool AREMAP>
; __device__ __forceinline__ void gemm_phase(LAS unsigned char* lds, const Gemm g, const Sched& S, const Epi& E, int wv) {
;     const int tid = otid(wv), wid = __builtin_amdgcn_readfirstlane(tid >> 6), lane = tid & 63, wr = wid >> 2, wc = wid & 3, fr = lane & 15, fq = lane >> 4;
;     const int K = g.K, nt = K / BK;
;     unsigned voffA[2], voffB[2];
; #pragma unroll
;     for (int i = 0; i < 2; ++i) { int R, C; stage_rc(tid * 16 + i * 8192, R, C); const int Rb = Epi::PERM ? ((R & ~31) + perm32(R & 31)) : R;
;         const int Ra = AREMAP ? ((R >> 6) * 128 + (R & 63)) : R;
;         voffA[i] = (unsigned)(Ra * g.lda + C) * 2u; voffB[i] = (unsigned)(Rb * g.ldb + C) * 2u; }
;     const size_t kstep = (size_t)(BK * 2);
;     const size_t hstepA = (size_t)(AREMAP ? 64 : HALF) * g.lda * 2, hstepB = (size_t)HALF * g.ldb * 2;
;     const size_t tstepA = (size_t)BM * g.lda * 2, tstepB = (size_t)BM * g.ldb * 2;
;     const unsigned ldsw = (unsigned)wid * 1024u;
;     const int aoff = lds_byte(wr * 64 + fr, fq * 8), boff = lds_byte(wc * 32 + fr, fq * 8);
;     ...
;     Unit cur, nxt; int ui = 0;
;     if (!S.next(0, cur)) return;
;     f32x4 acc[2][2][4][2];
; #pragma unroll
;     for (int a = 0; a < 2; ++a)
; #pragma unroll
;         for (int b = 0; b < 2; ++b)
; #pragma unroll
;             for (int m = 0; m < 4; ++m)
; #pragma unroll
;                 for (int n = 0; n < 2; ++n) acc[a][b][m][n] = (f32x4){0.f, 0.f, 0.f, 0.f};
;     bf16x8 At[4][2], B0[2][2], B1[2][2];
;     ...
;     const char* cA = PG8_UA(cur); const char* cB = PG8_UB(cur);
;     PG8_STAGE(PG8_SB(0, 0), cB, voffB); PG8_STAGE(PG8_SA(0, 0), cA, voffA); PG8_STAGE(PG8_SB(0, 1), cB + hstepB, voffB); PG8_STAGE(PG8_SA(0, 1), cA + hstepA, voffA);
;     if (wr == 1) PG8_BAR;
;     PG8_WAIT_V(4); PG8_BAR;
;     PG8_STAGE(PG8_SB(1, 0), cB + kstep, voffB); PG8_STAGE(PG8_SA(1, 0), cA + kstep, voffA); PG8_STAGE(PG8_SB(1, 1), cB + hstepB + kstep, voffB);
;     PG8_WAIT_V(6); PG8_BAR;
.LBB0_414:
	s_andn2_b64 vcc, exec, s[8:9]
	s_cbranch_vccnz .LBB0_528
	v_ashrrev_i32_e32 v2, 31, v13
	v_lshrrev_b32_e32 v2, 26, v2
	v_add_u32_e32 v2, v13, v2
	v_ashrrev_i32_e32 v10, 6, v2
	v_bfe_i32 v2, v13, 27, 1
	v_lshlrev_b32_e32 v1, 4, v13
	v_lshrrev_b32_e32 v2, 22, v2
	v_add_u32_e32 v2, v1, v2
	v_and_b32_e32 v2, 0xfffffc00, v2
	v_sub_u32_e32 v2, v1, v2
	v_lshrrev_b32_e32 v3, 4, v2
	v_bitop3_b32 v3, v3, v2, 32 bitop3:0x6c
	v_ashrrev_i32_e32 v2, 31, v2
	v_lshrrev_b32_e32 v2, 26, v2
	v_add_u32_e32 v2, v3, v2
	v_ashrrev_i32_e32 v11, 6, v2
	v_lshlrev_b32_e32 v4, 3, v10
	v_mul_i32_i24_e32 v5, 64, v11
	v_and_b32_e32 v4, -16, v4
	v_sub_u32_e32 v3, v3, v5
	v_add_u32_e32 v2, v11, v4
	v_lshlrev_b32_e32 v4, 5, v10
	v_ashrrev_i16_sdwa v3, v240, sext(v3) dst_sel:DWORD dst_unused:UNUSED_PAD src0_sel:DWORD src1_sel:BYTE_0
	v_and_b32_e32 v4, 32, v4
	v_bfe_i32 v12, v3, 0, 16
	v_and_b32_e32 v6, 3, v11
	s_mov_b32 s3, 0xfffe0
	v_add_lshl_u32 v4, v4, v12, 1
	v_add_u32_e32 v1, 0x2000, v1
	v_lshlrev_b32_e32 v3, 1, v2
	v_lshrrev_b32_e32 v5, 2, v2
	v_and_or_b32 v6, v2, s3, v6
	v_lshl_add_u32 v162, v2, 12, v4
	v_ashrrev_i32_e32 v2, 31, v1
	v_lshrrev_b32_e32 v2, 22, v2
	v_add_u32_e32 v2, v1, v2
	v_ashrrev_i32_e32 v14, 10, v2
	v_mul_i32_i24_e32 v2, 0x400, v14
	v_sub_u32_e32 v1, v1, v2
	v_and_b32_e32 v3, 24, v3
	v_and_b32_e32 v5, 4, v5
	v_lshrrev_b32_e32 v2, 4, v1
	v_or3_b32 v3, v6, v5, v3
	v_bitop3_b32 v1, v2, v1, 32 bitop3:0x6c
	v_lshl_add_u32 v164, v3, 12, v4
	v_ashrrev_i32_e32 v3, 31, v1
	v_lshrrev_b32_e32 v3, 26, v3
	s_add_u32 s28, s0, 0x8e00000
	v_lshlrev_b32_e32 v2, 3, v14
	v_add_u32_e32 v3, v1, v3
	s_addc_u32 s29, s1, 0
	v_and_b32_e32 v2, -16, v2
	v_ashrrev_i32_e32 v15, 6, v3
	s_add_u32 s30, s0, 0x2000000
	v_add_u32_e32 v2, v15, v2
	v_and_b32_e32 v5, 3, v15
	s_addc_u32 s31, s1, 0
	v_and_b32_e32 v3, 0xc0, v3
	v_and_or_b32 v5, v2, s3, v5
	s_ashr_i32 s11, s27, 6
	s_ashr_i32 s3, s2, 31
	s_ashr_i32 s5, s4, 31
	s_ashr_i32 s10, s27, 8
	v_sub_u32_e32 v1, v1, v3
	s_lshl_b32 s34, s11, 10
	s_lshl_b64 s[8:9], s[2:3], 20
	s_lshl_b64 s[12:13], s[4:5], 20
	v_ashrrev_i16_sdwa v1, v240, sext(v1) dst_sel:DWORD dst_unused:UNUSED_PAD src0_sel:DWORD src1_sel:BYTE_0
	s_add_u32 s18, s30, s12
	v_lshlrev_b32_e32 v4, 5, v14
	v_bfe_i32 v16, v1, 0, 16
	v_lshlrev_b32_e32 v1, 1, v2
	v_lshrrev_b32_e32 v3, 2, v2
	s_addc_u32 s19, s31, s13
	s_add_i32 s35, s34, 0
	v_and_b32_e32 v4, 32, v4
	v_and_b32_e32 v1, 24, v1
	v_and_b32_e32 v3, 4, v3
	s_add_i32 m0, s35, 0x10000
	v_or3_b32 v1, v5, v3, v1
	v_add_lshl_u32 v3, v4, v16, 1
	global_load_lds_dwordx4 v164, s[18:19]
	s_add_i32 m0, s35, 0x12000
	v_lshl_add_u32 v168, v1, 12, v3
	s_add_u32 s20, s28, s8
	global_load_lds_dwordx4 v168, s[18:19]
	s_addc_u32 s21, s29, s9
	s_mov_b32 m0, s35
	s_add_i32 s41, s35, 0x2000
	v_lshl_add_u32 v166, v2, 12, v3
	global_load_lds_dwordx4 v162, s[20:21]
	s_mov_b32 m0, s41
	s_add_u32 s8, s18, 0x80000
	global_load_lds_dwordx4 v166, s[20:21]
	s_addc_u32 s9, s19, 0
	s_add_i32 m0, s35, 0x14000
	v_mov_b32_e32 v165, v0
	global_load_lds_dwordx4 v164, s[8:9]
	s_add_i32 m0, s35, 0x16000
	v_mov_b32_e32 v169, v0
	global_load_lds_dwordx4 v168, s[8:9]
	s_add_u32 s8, s20, 0x80000
	s_addc_u32 s9, s21, 0
	s_add_i32 s52, s35, 0x4000
	s_mov_b32 m0, s52
	s_add_i32 s53, s35, 0x6000
	global_load_lds_dwordx4 v162, s[8:9]
	s_mov_b32 m0, s53
	v_mov_b32_e32 v163, v0
	global_load_lds_dwordx4 v166, s[8:9]
	v_mov_b32_e32 v167, v0
	v_lshl_add_u64 v[8:9], s[18:19], 0, v[164:165]
	v_lshl_add_u64 v[6:7], s[18:19], 0, v[168:169]
	v_lshl_add_u64 v[4:5], s[20:21], 0, v[162:163]
	s_cmp_lg_u32 s10, 1
	v_lshl_add_u64 v[2:3], s[20:21], 0, v[166:167]
	s_cbranch_scc1 .LBB0_417
	s_barrier
	s_setprio 1

; #define PG8_STAGE(bufoff, gbase, voff) do { _Pragma("unroll") for (int _i = 0; _i < 2; ++_i) \
;         __builtin_amdgcn_global_load_lds((const unsigned*)((const char*)(gbase) + (voff)[_i]), (LAS unsigned*)(lds + (bufoff) + ldsw + _i * 8192), 16, 0, 0); } while (0)
; #define PG8_LDA(dst, b, h) do { _Pragma("unroll") for (int m = 0; m < 4; ++m) _Pragma("unroll") for (int k = 0; k < 2; ++k) dst[m][k] = *(const LAS bf16x8*)(lds + PG8_SA(b, h) + aoff + m * 2048 + k * 1024); } while (0)
; #define PG8_LDB(dst, b, h) do { _Pragma("unroll") for (int n = 0; n < 2; ++n) _Pragma("unroll") for (int k = 0; k < 2; ++k) dst[n][k] = *(const LAS bf16x8*)(lds + PG8_SB(b, h) + boff + n * 2048 + k * 1024); } while (0)
; #define PG8_MMA(ai, bj, At, Bt) do { __builtin_amdgcn_s_setprio(1); _Pragma("unroll") for (int m = 0; m < 4; ++m) _Pragma("unroll") for (int n = 0; n < 2; ++n) _Pragma("unroll") for (int k = 0; k < 2; ++k) \
;         acc[ai][bj][m][n] = __builtin_amdgcn_mfma_f32_16x16x32_bf16(Bt[n][k], At[m][k], acc[ai][bj][m][n], 0, 0, 0); __builtin_amdgcn_s_setprio(0); } while (0)
; #define PG8_WAIT_V(n) asm volatile("s_waitcnt vmcnt(" #n ")" ::: "memory")
; #define PG8_WAIT_L(n) asm volatile("s_waitcnt lgkmcnt(" #n ")" ::: "memory")
; #define PG8_BAR __builtin_amdgcn_s_barrier()
; #define PG8_SCHED __builtin_amdgcn_sched_barrier(0)
; template <class Epi, class Sched, bool AREMAP>
; __device__ __forceinline__ void gemm_phase(LAS unsigned char* lds, const Gemm g, const Sched& S, const Epi& E, int wv) {
;     ...
;             PG8_LDB(B0, 0, 0); PG8_SCHED; PG8_LDA(At, 0, 0); PG8_STAGE(PG8_SA(1, 1), a1 + hstepA, voffA);
;             PG8_WAIT_L(8); PG8_BAR; PG8_WAIT_L(0); PG8_MMA(0, 0, At, B0); PG8_BAR; PG8_SCHED;
;             PG8_LDB(B1, 0, 1); PG8_STAGE(PG8_SB(0, 0), b2, voffB);
;             PG8_BAR; PG8_WAIT_L(0); PG8_MMA(0, 1, At, B1); PG8_BAR;
;             PG8_LDA(At, 0, 1); PG8_STAGE(PG8_SA(0, 0), a2, voffA);
;             PG8_BAR; PG8_WAIT_L(0); PG8_MMA(1, 0, At, B0); PG8_BAR; PG8_SCHED;
;             PG8_STAGE(PG8_SB(0, 1), b2 + hstepB, voffB);
;             PG8_WAIT_V(6); PG8_BAR; PG8_MMA(1, 1, At, B1); PG8_BAR;
.LBB0_426:
	s_add_u32 s20, s18, 0xfff80080
	s_addc_u32 s21, s19, -1
	s_add_i32 s38, 0, 0x10000
	v_add_u32_e32 v142, s38, v186
	ds_read_b128 v[130:133], v142
	ds_read_b128 v[134:137], v142 offset:1024
	ds_read_b128 v[138:141], v142 offset:2048
	ds_read_b128 v[142:145], v142 offset:3072
	s_cmp_eq_u32 s46, 28
	s_cselect_b32 s23, s3, s21
	s_cselect_b32 s22, s5, s20
	s_cselect_b32 s21, s11, s37
	s_cselect_b32 s20, s13, s36
	v_lshl_add_u64 v[198:199], s[18:19], 0, v[172:173]
	s_add_i32 m0, s35, 0xc000
	ds_read_b128 v[146:149], v196
	ds_read_b128 v[150:153], v196 offset:1024
	ds_read_b128 v[154:157], v196 offset:2048
	ds_read_b128 v[158:161], v196 offset:3072
	ds_read_b128 v[174:177], v196 offset:4096
	ds_read_b128 v[178:181], v196 offset:5120
	ds_read_b128 v[182:185], v196 offset:6144
	ds_read_b128 v[192:195], v196 offset:7168
	global_load_lds_dwordx4 v[198:199], off
	v_lshl_add_u64 v[198:199], s[18:19], 0, v[170:171]
	s_add_i32 m0, s35, 0xe000
	s_nop 0
	global_load_lds_dwordx4 v[198:199], off
	s_waitcnt lgkmcnt(8)
	s_barrier
	s_waitcnt lgkmcnt(0)
	s_waitcnt lgkmcnt(0)
	v_mfma_f32_16x16x32_bf16 v[126:129], v[130:133], v[146:149], v[126:129]
	v_mfma_f32_16x16x32_bf16 v[122:125], v[138:141], v[146:149], v[122:125]
	v_mfma_f32_16x16x32_bf16 v[110:113], v[130:133], v[154:157], v[110:113]
	v_mfma_f32_16x16x32_bf16 v[106:109], v[138:141], v[154:157], v[106:109]
	v_mfma_f32_16x16x32_bf16 v[94:97], v[130:133], v[174:177], v[94:97]
	v_mfma_f32_16x16x32_bf16 v[90:93], v[138:141], v[174:177], v[90:93]
	v_mfma_f32_16x16x32_bf16 v[78:81], v[130:133], v[182:185], v[78:81]
	v_mfma_f32_16x16x32_bf16 v[74:77], v[138:141], v[182:185], v[74:77]
	v_mfma_f32_16x16x32_bf16 v[126:129], v[134:137], v[150:153], v[126:129]
	v_mfma_f32_16x16x32_bf16 v[122:125], v[142:145], v[150:153], v[122:125]
	v_mfma_f32_16x16x32_bf16 v[110:113], v[134:137], v[158:161], v[110:113]
	v_mfma_f32_16x16x32_bf16 v[106:109], v[142:145], v[158:161], v[106:109]
	v_mfma_f32_16x16x32_bf16 v[94:97], v[134:137], v[178:181], v[94:97]
	v_mfma_f32_16x16x32_bf16 v[90:93], v[142:145], v[178:181], v[90:93]
	v_mfma_f32_16x16x32_bf16 v[78:81], v[134:137], v[192:195], v[78:81]
	v_mfma_f32_16x16x32_bf16 v[74:77], v[142:145], v[192:195], v[74:77]
	s_barrier
	s_add_i32 s39, 0, 0x14000
	s_add_i32 s38, s38, s34
	v_add_u32_e32 v197, s39, v186
	v_lshl_add_u64 v[214:215], s[20:21], 0, v[164:165]
	s_mov_b32 m0, s38
	ds_read_b128 v[198:201], v197
	ds_read_b128 v[202:205], v197 offset:1024
	ds_read_b128 v[206:209], v197 offset:2048
	ds_read_b128 v[210:213], v197 offset:3072
	global_load_lds_dwordx4 v[214:215], off
	v_lshl_add_u64 v[216:217], s[20:21], 0, v[168:169]
	s_add_i32 m0, s38, 0x2000
	s_nop 0
	global_load_lds_dwordx4 v[216:217], off
	s_barrier
	s_waitcnt lgkmcnt(0)
	s_waitcnt lgkmcnt(0)
	v_mfma_f32_16x16x32_bf16 v[118:121], v[198:201], v[146:149], v[118:121]
	v_mfma_f32_16x16x32_bf16 v[114:117], v[206:209], v[146:149], v[114:117]
	v_mfma_f32_16x16x32_bf16 v[102:105], v[198:201], v[154:157], v[102:105]
	v_mfma_f32_16x16x32_bf16 v[98:101], v[206:209], v[154:157], v[98:101]
	v_mfma_f32_16x16x32_bf16 v[86:89], v[198:201], v[174:177], v[86:89]
	v_mfma_f32_16x16x32_bf16 v[82:85], v[206:209], v[174:177], v[82:85]
	v_mfma_f32_16x16x32_bf16 v[70:73], v[198:201], v[182:185], v[70:73]
	v_mfma_f32_16x16x32_bf16 v[66:69], v[206:209], v[182:185], v[66:69]
	v_mfma_f32_16x16x32_bf16 v[118:121], v[202:205], v[150:153], v[118:121]
	v_mfma_f32_16x16x32_bf16 v[114:117], v[210:213], v[150:153], v[114:117]
	v_mfma_f32_16x16x32_bf16 v[102:105], v[202:205], v[158:161], v[102:105]
	v_mfma_f32_16x16x32_bf16 v[98:101], v[210:213], v[158:161], v[98:101]
	v_mfma_f32_16x16x32_bf16 v[86:89], v[202:205], v[178:181], v[86:89]
	v_mfma_f32_16x16x32_bf16 v[82:85], v[210:213], v[178:181], v[82:85]
	v_mfma_f32_16x16x32_bf16 v[70:73], v[202:205], v[192:195], v[70:73]
	v_mfma_f32_16x16x32_bf16 v[66:69], v[210:213], v[192:195], v[66:69]
	s_mov_b32 m0, s35
	v_lshl_add_u64 v[218:219], s[22:23], 0, v[162:163]
	s_barrier
	ds_read_b128 v[146:149], v196 offset:16384
	ds_read_b128 v[150:153], v196 offset:17408
	ds_read_b128 v[154:157], v196 offset:18432
	ds_read_b128 v[158:161], v196 offset:19456
	ds_read_b128 v[174:177], v196 offset:20480
	ds_read_b128 v[178:181], v196 offset:21504
	ds_read_b128 v[182:185], v196 offset:22528
	ds_read_b128 v[192:195], v196 offset:23552
	global_load_lds_dwordx4 v[218:219], off
	v_lshl_add_u64 v[220:221], s[22:23], 0, v[166:167]
	s_mov_b32 m0, s41
	s_nop 0
	global_load_lds_dwordx4 v[220:221], off
	s_barrier
	s_waitcnt lgkmcnt(0)
	s_waitcnt lgkmcnt(0)
	v_mfma_f32_16x16x32_bf16 v[62:65], v[130:133], v[146:149], v[62:65]
	v_mfma_f32_16x16x32_bf16 v[58:61], v[138:141], v[146:149], v[58:61]
	v_mfma_f32_16x16x32_bf16 v[46:49], v[130:133], v[154:157], v[46:49]
	v_mfma_f32_16x16x32_bf16 v[42:45], v[138:141], v[154:157], v[42:45]
	v_mfma_f32_16x16x32_bf16 v[30:33], v[130:133], v[174:177], v[30:33]
	v_mfma_f32_16x16x32_bf16 v[26:29], v[138:141], v[174:177], v[26:29]
	v_mfma_f32_16x16x32_bf16 v[14:17], v[130:133], v[182:185], v[14:17]
	v_mfma_f32_16x16x32_bf16 v[10:13], v[138:141], v[182:185], v[10:13]
	v_mfma_f32_16x16x32_bf16 v[62:65], v[134:137], v[150:153], v[62:65]
	v_mfma_f32_16x16x32_bf16 v[58:61], v[142:145], v[150:153], v[58:61]
	v_mfma_f32_16x16x32_bf16 v[46:49], v[134:137], v[158:161], v[46:49]
	v_mfma_f32_16x16x32_bf16 v[42:45], v[142:145], v[158:161], v[42:45]
	v_mfma_f32_16x16x32_bf16 v[30:33], v[134:137], v[178:181], v[30:33]
	v_mfma_f32_16x16x32_bf16 v[26:29], v[142:145], v[178:181], v[26:29]
	v_mfma_f32_16x16x32_bf16 v[14:17], v[134:137], v[192:195], v[14:17]
	v_mfma_f32_16x16x32_bf16 v[10:13], v[142:145], v[192:195], v[10:13]
	s_barrier
; #define PG8_STAGE(bufoff, gbase, voff) do { _Pragma("unroll") for (int _i = 0; _i < 2; ++_i) \
;         __builtin_amdgcn_global_load_lds((const unsigned*)((const char*)(gbase) + (voff)[_i]), (LAS unsigned*)(lds + (bufoff) + ldsw + _i * 8192), 16, 0, 0); } while (0)
; #define PG8_LDA(dst, b, h) do { _Pragma("unroll") for (int m = 0; m < 4; ++m) _Pragma("unroll") for (int k = 0; k < 2; ++k) dst[m][k] = *(const LAS bf16x8*)(lds + PG8_SA(b, h) + aoff + m * 2048 + k * 1024); } while (0)
; #define PG8_LDB(dst, b, h) do { _Pragma("unroll") for (int n = 0; n < 2; ++n) _Pragma("unroll") for (int k = 0; k < 2; ++k) dst[n][k] = *(const LAS bf16x8*)(lds + PG8_SB(b, h) + boff + n * 2048 + k * 1024); } while (0)
; #define PG8_MMA(ai, bj, At, Bt) do { __builtin_amdgcn_s_setprio(1); _Pragma("unroll") for (int m = 0; m < 4; ++m) _Pragma("unroll") for (int n = 0; n < 2; ++n) _Pragma("unroll") for (int k = 0; k < 2; ++k) \
;         acc[ai][bj][m][n] = __builtin_amdgcn_mfma_f32_16x16x32_bf16(Bt[n][k], At[m][k], acc[ai][bj][m][n], 0, 0, 0); __builtin_amdgcn_s_setprio(0); } while (0)
; #define PG8_WAIT_V(n) asm volatile("s_waitcnt vmcnt(" #n ")" ::: "memory")
; #define PG8_WAIT_L(n) asm volatile("s_waitcnt lgkmcnt(" #n ")" ::: "memory")
; #define PG8_BAR __builtin_amdgcn_s_barrier()
; #define PG8_SCHED __builtin_amdgcn_sched_barrier(0)
; template <class Epi, class Sched, bool AREMAP>
; __device__ __forceinline__ void gemm_phase(LAS unsigned char* lds, const Gemm g, const Sched& S, const Epi& E, int wv) {
;     ...
;             PG8_LDA(At, 0, 1); PG8_STAGE(PG8_SA(0, 0), a2, voffA);
;             PG8_BAR; PG8_WAIT_L(0); PG8_MMA(1, 0, At, B0); PG8_BAR; PG8_SCHED;
;             PG8_STAGE(PG8_SB(0, 1), b2 + hstepB, voffB);
;             PG8_WAIT_V(6); PG8_BAR; PG8_MMA(1, 1, At, B1); PG8_BAR;
;             PG8_LDB(B0, 1, 0); PG8_SCHED; PG8_LDA(At, 1, 0); PG8_STAGE(PG8_SA(0, 1), a2 + hstepA, voffA);
;             PG8_WAIT_L(8); PG8_BAR; PG8_WAIT_L(0); PG8_MMA(0, 0, At, B0); PG8_BAR; PG8_SCHED;
;             PG8_LDB(B1, 1, 1); PG8_STAGE(PG8_SB(1, 0), b3, voffB);
;             PG8_BAR; PG8_WAIT_L(0); PG8_MMA(0, 1, At, B1); PG8_BAR;
;             PG8_LDA(At, 1, 1); PG8_STAGE(PG8_SA(1, 0), a3, voffA);
;             PG8_BAR; PG8_WAIT_L(0); PG8_MMA(1, 0, At, B0); PG8_BAR; PG8_SCHED;
	s_add_u32 s66, s20, 0x80000
	s_addc_u32 s67, s21, 0
	s_add_i32 s38, s39, s34
	v_lshl_add_u64 v[130:131], s[66:67], 0, v[164:165]
	s_mov_b32 m0, s38
	s_nop 0
	global_load_lds_dwordx4 v[130:131], off
	v_lshl_add_u64 v[130:131], s[66:67], 0, v[168:169]
	s_add_i32 m0, s38, 0x2000
	s_nop 0
	global_load_lds_dwordx4 v[130:131], off
	s_waitcnt vmcnt(6)
	s_barrier
	v_mfma_f32_16x16x32_bf16 v[54:57], v[198:201], v[146:149], v[54:57]
	v_mfma_f32_16x16x32_bf16 v[50:53], v[206:209], v[146:149], v[50:53]
	v_mfma_f32_16x16x32_bf16 v[38:41], v[198:201], v[154:157], v[38:41]
	v_mfma_f32_16x16x32_bf16 v[34:37], v[206:209], v[154:157], v[34:37]
	v_mfma_f32_16x16x32_bf16 v[22:25], v[198:201], v[174:177], v[22:25]
	v_mfma_f32_16x16x32_bf16 v[18:21], v[206:209], v[174:177], v[18:21]
	v_mfma_f32_16x16x32_bf16 v[6:9], v[198:201], v[182:185], v[6:9]
	v_mfma_f32_16x16x32_bf16 v[2:5], v[206:209], v[182:185], v[2:5]
	v_mfma_f32_16x16x32_bf16 v[54:57], v[202:205], v[150:153], v[54:57]
	v_mfma_f32_16x16x32_bf16 v[50:53], v[210:213], v[150:153], v[50:53]
	v_mfma_f32_16x16x32_bf16 v[38:41], v[202:205], v[158:161], v[38:41]
	v_mfma_f32_16x16x32_bf16 v[34:37], v[210:213], v[158:161], v[34:37]
	v_mfma_f32_16x16x32_bf16 v[22:25], v[202:205], v[178:181], v[22:25]
	v_mfma_f32_16x16x32_bf16 v[18:21], v[210:213], v[178:181], v[18:21]
	v_mfma_f32_16x16x32_bf16 v[6:9], v[202:205], v[192:195], v[6:9]
	v_mfma_f32_16x16x32_bf16 v[2:5], v[210:213], v[192:195], v[2:5]
	s_add_i32 s38, 0, 0x18000
	v_add_u32_e32 v142, s38, v186
	s_barrier
	ds_read_b128 v[130:133], v142
	ds_read_b128 v[134:137], v142 offset:1024
	ds_read_b128 v[138:141], v142 offset:2048
	ds_read_b128 v[142:145], v142 offset:3072
	s_add_u32 s22, s22, 0x80000
	s_addc_u32 s23, s23, 0
	s_mov_b32 m0, s52
	v_lshl_add_u64 v[198:199], s[22:23], 0, v[162:163]
	ds_read_b128 v[146:149], v196 offset:32768
	ds_read_b128 v[150:153], v196 offset:33792
	ds_read_b128 v[154:157], v196 offset:34816
	ds_read_b128 v[158:161], v196 offset:35840
	ds_read_b128 v[174:177], v196 offset:36864
	ds_read_b128 v[178:181], v196 offset:37888
	ds_read_b128 v[182:185], v196 offset:38912
	ds_read_b128 v[192:195], v196 offset:39936
	global_load_lds_dwordx4 v[198:199], off
	v_lshl_add_u64 v[198:199], s[22:23], 0, v[166:167]
	s_mov_b32 m0, s53
	s_nop 0
	global_load_lds_dwordx4 v[198:199], off
	s_waitcnt lgkmcnt(8)
	s_barrier
	s_waitcnt lgkmcnt(0)
	s_waitcnt lgkmcnt(0)
	v_mfma_f32_16x16x32_bf16 v[126:129], v[130:133], v[146:149], v[126:129]
	v_mfma_f32_16x16x32_bf16 v[122:125], v[138:141], v[146:149], v[122:125]
	v_mfma_f32_16x16x32_bf16 v[110:113], v[130:133], v[154:157], v[110:113]
	v_mfma_f32_16x16x32_bf16 v[106:109], v[138:141], v[154:157], v[106:109]
	v_mfma_f32_16x16x32_bf16 v[94:97], v[130:133], v[174:177], v[94:97]
	v_mfma_f32_16x16x32_bf16 v[90:93], v[138:141], v[174:177], v[90:93]
	v_mfma_f32_16x16x32_bf16 v[78:81], v[130:133], v[182:185], v[78:81]
	v_mfma_f32_16x16x32_bf16 v[74:77], v[138:141], v[182:185], v[74:77]
	v_mfma_f32_16x16x32_bf16 v[126:129], v[134:137], v[150:153], v[126:129]
	v_mfma_f32_16x16x32_bf16 v[122:125], v[142:145], v[150:153], v[122:125]
	v_mfma_f32_16x16x32_bf16 v[110:113], v[134:137], v[158:161], v[110:113]
	v_mfma_f32_16x16x32_bf16 v[106:109], v[142:145], v[158:161], v[106:109]
	v_mfma_f32_16x16x32_bf16 v[94:97], v[134:137], v[178:181], v[94:97]
	v_mfma_f32_16x16x32_bf16 v[90:93], v[142:145], v[178:181], v[90:93]
	v_mfma_f32_16x16x32_bf16 v[78:81], v[134:137], v[192:195], v[78:81]
	v_mfma_f32_16x16x32_bf16 v[74:77], v[142:145], v[192:195], v[74:77]
	s_barrier
	s_add_i32 s22, 0, 0x1c000
	s_add_i32 s23, s38, s34
	v_add_u32_e32 v197, s22, v186
	v_lshl_add_u64 v[214:215], v[214:215], 0, s[86:87]
	s_mov_b32 m0, s23
	ds_read_b128 v[198:201], v197
	ds_read_b128 v[202:205], v197 offset:1024
	ds_read_b128 v[206:209], v197 offset:2048
	ds_read_b128 v[210:213], v197 offset:3072
	global_load_lds_dwordx4 v[214:215], off
	v_lshl_add_u64 v[214:215], v[216:217], 0, s[86:87]
	s_add_i32 m0, s23, 0x2000
	s_nop 0
	global_load_lds_dwordx4 v[214:215], off
	s_barrier
	s_waitcnt lgkmcnt(0)
	s_waitcnt lgkmcnt(0)
	v_mfma_f32_16x16x32_bf16 v[118:121], v[198:201], v[146:149], v[118:121]
	v_mfma_f32_16x16x32_bf16 v[114:117], v[206:209], v[146:149], v[114:117]
	v_mfma_f32_16x16x32_bf16 v[102:105], v[198:201], v[154:157], v[102:105]
	v_mfma_f32_16x16x32_bf16 v[98:101], v[206:209], v[154:157], v[98:101]
	v_mfma_f32_16x16x32_bf16 v[86:89], v[198:201], v[174:177], v[86:89]
	v_mfma_f32_16x16x32_bf16 v[82:85], v[206:209], v[174:177], v[82:85]
	v_mfma_f32_16x16x32_bf16 v[70:73], v[198:201], v[182:185], v[70:73]
	v_mfma_f32_16x16x32_bf16 v[66:69], v[206:209], v[182:185], v[66:69]
	v_mfma_f32_16x16x32_bf16 v[118:121], v[202:205], v[150:153], v[118:121]
	v_mfma_f32_16x16x32_bf16 v[114:117], v[210:213], v[150:153], v[114:117]
	v_mfma_f32_16x16x32_bf16 v[102:105], v[202:205], v[158:161], v[102:105]
	v_mfma_f32_16x16x32_bf16 v[98:101], v[210:213], v[158:161], v[98:101]
	v_mfma_f32_16x16x32_bf16 v[86:89], v[202:205], v[178:181], v[86:89]
	v_mfma_f32_16x16x32_bf16 v[82:85], v[210:213], v[178:181], v[82:85]
	v_mfma_f32_16x16x32_bf16 v[70:73], v[202:205], v[192:195], v[70:73]
	v_mfma_f32_16x16x32_bf16 v[66:69], v[210:213], v[192:195], v[66:69]
	s_mov_b32 m0, s57
	v_lshl_add_u64 v[214:215], v[218:219], 0, s[86:87]
	s_barrier
; __device__ __forceinline__ int otid(int wv) { int t = (wv << 6) | (int)__builtin_amdgcn_mbcnt_hi(~0u, __builtin_amdgcn_mbcnt_lo(~0u, 0u)); asm volatile("" : "+v"(t)); return t; }
; #define PG8_STAGE(bufoff, gbase, voff) do { _Pragma("unroll") for (int _i = 0; _i < 2; ++_i) \
;         __builtin_amdgcn_global_load_lds((const unsigned*)((const char*)(gbase) + (voff)[_i]), (LAS unsigned*)(lds + (bufoff) + ldsw + _i * 8192), 16, 0, 0); } while (0)
; #define PG8_LDA(dst, b, h) do { _Pragma("unroll") for (int m = 0; m < 4; ++m) _Pragma("unroll") for (int k = 0; k < 2; ++k) dst[m][k] = *(const LAS bf16x8*)(lds + PG8_SA(b, h) + aoff + m * 2048 + k * 1024); } while (0)
; #define PG8_LDB(dst, b, h) do { _Pragma("unroll") for (int n = 0; n < 2; ++n) _Pragma("unroll") for (int k = 0; k < 2; ++k) dst[n][k] = *(const LAS bf16x8*)(lds + PG8_SB(b, h) + boff + n * 2048 + k * 1024); } while (0)
; #define PG8_BAR __builtin_amdgcn_s_barrier()
; template <class Epi, class Sched, bool AREMAP>
; __device__ __forceinline__ void gemm_phase(LAS unsigned char* lds, const Gemm g, const Sched& S, const Epi& E, int wv) {
;     ...
;             PG8_LDB(B1, 1, 1); PG8_STAGE(PG8_SB(1, 0), b3, voffB);
;             PG8_BAR; PG8_WAIT_L(0); PG8_MMA(0, 1, At, B1); PG8_BAR;
;             PG8_LDA(At, 1, 1); PG8_STAGE(PG8_SA(1, 0), a3, voffA);
;             PG8_BAR; PG8_WAIT_L(0); PG8_MMA(1, 0, At, B0); PG8_BAR; PG8_SCHED;
;             PG8_STAGE(PG8_SB(1, 1), b3 + hstepB, voffB);
;             PG8_WAIT_V(6); PG8_BAR; PG8_MMA(1, 1, At, B1); PG8_BAR;
;     __device__ __forceinline__ void operator()(const f32x4 (&acc)[2][2][4][2], const Unit& u, int wr, int wc, int fr, int fq) const {
;         const int b = u.pn >> 3, pn8 = u.pn & 7;
;         const int row0 = u.pm * BM + wr * 64 + fr, col0 = pn8 * BM + wc * 32 + 8 * fq;
;         const bf16_t* yb = YB + (size_t)b * NTOK * DM;
;         u32x4* sc = (u32x4*)scratch + otid(wv);
; #pragma unroll
;         for (int ai = 0; ai < 2; ++ai)
; #pragma unroll
;             for (int mp = 0; mp < 2; ++mp) {
;                 u32x4 y[2][2], pr[2][2];
; #pragma unroll
;                 for (int mm = 0; mm < 2; ++mm)
; #pragma unroll
;                     for (int bj = 0; bj < 2; ++bj) { const int m = mp * 2 + mm; const size_t off = (size_t)(row0 + ai * HALF + m * 16) * DM + col0;
;                         y[mm][bj] = *(const u32x4*)(yb + off + bj * HALF);
	ds_read_b128 v[146:149], v196 offset:49152
	ds_read_b128 v[150:153], v196 offset:50176
	ds_read_b128 v[154:157], v196 offset:51200
	ds_read_b128 v[158:161], v196 offset:52224
	ds_read_b128 v[174:177], v196 offset:53248
	ds_read_b128 v[178:181], v196 offset:54272
	ds_read_b128 v[182:185], v196 offset:55296
	ds_read_b128 v[192:195], v196 offset:56320
	global_load_lds_dwordx4 v[214:215], off
	v_lshl_add_u64 v[214:215], v[220:221], 0, s[86:87]
	s_mov_b32 m0, s62
	s_nop 0
	global_load_lds_dwordx4 v[214:215], off
	s_barrier
	s_waitcnt lgkmcnt(0)
	s_waitcnt lgkmcnt(0)
	v_mfma_f32_16x16x32_bf16 v[62:65], v[130:133], v[146:149], v[62:65]
	v_mfma_f32_16x16x32_bf16 v[58:61], v[138:141], v[146:149], v[58:61]
	v_mfma_f32_16x16x32_bf16 v[46:49], v[130:133], v[154:157], v[46:49]
	v_mfma_f32_16x16x32_bf16 v[42:45], v[138:141], v[154:157], v[42:45]
	v_mfma_f32_16x16x32_bf16 v[30:33], v[130:133], v[174:177], v[30:33]
	v_mfma_f32_16x16x32_bf16 v[26:29], v[138:141], v[174:177], v[26:29]
	v_mfma_f32_16x16x32_bf16 v[14:17], v[130:133], v[182:185], v[14:17]
	v_mfma_f32_16x16x32_bf16 v[10:13], v[138:141], v[182:185], v[10:13]
	v_mfma_f32_16x16x32_bf16 v[62:65], v[134:137], v[150:153], v[62:65]
	v_mfma_f32_16x16x32_bf16 v[58:61], v[142:145], v[150:153], v[58:61]
	v_mfma_f32_16x16x32_bf16 v[46:49], v[134:137], v[158:161], v[46:49]
	v_mfma_f32_16x16x32_bf16 v[42:45], v[142:145], v[158:161], v[42:45]
	v_mfma_f32_16x16x32_bf16 v[30:33], v[134:137], v[178:181], v[30:33]
	v_mfma_f32_16x16x32_bf16 v[26:29], v[142:145], v[178:181], v[26:29]
	v_mfma_f32_16x16x32_bf16 v[14:17], v[134:137], v[192:195], v[14:17]
	v_mfma_f32_16x16x32_bf16 v[10:13], v[142:145], v[192:195], v[10:13]
	s_barrier
	s_add_u32 s20, s20, 0x80080
	s_addc_u32 s21, s21, 0
	s_add_i32 s22, s22, s34
	v_lshl_add_u64 v[130:131], s[20:21], 0, v[164:165]
	s_mov_b32 m0, s22
	s_nop 0
	global_load_lds_dwordx4 v[130:131], off
	v_lshl_add_u64 v[130:131], s[20:21], 0, v[168:169]
	s_add_i32 m0, s22, 0x2000
	s_nop 0
	global_load_lds_dwordx4 v[130:131], off
	s_waitcnt vmcnt(6)
	s_barrier
	v_mfma_f32_16x16x32_bf16 v[54:57], v[198:201], v[146:149], v[54:57]
	v_mfma_f32_16x16x32_bf16 v[50:53], v[206:209], v[146:149], v[50:53]
	v_mfma_f32_16x16x32_bf16 v[38:41], v[198:201], v[154:157], v[38:41]
	v_mfma_f32_16x16x32_bf16 v[34:37], v[206:209], v[154:157], v[34:37]
	v_mfma_f32_16x16x32_bf16 v[22:25], v[198:201], v[174:177], v[22:25]
	v_mfma_f32_16x16x32_bf16 v[18:21], v[206:209], v[174:177], v[18:21]
	v_mfma_f32_16x16x32_bf16 v[6:9], v[198:201], v[182:185], v[6:9]
	v_mfma_f32_16x16x32_bf16 v[2:5], v[206:209], v[182:185], v[2:5]
	v_mfma_f32_16x16x32_bf16 v[54:57], v[202:205], v[150:153], v[54:57]
	v_mfma_f32_16x16x32_bf16 v[50:53], v[210:213], v[150:153], v[50:53]
	v_mfma_f32_16x16x32_bf16 v[38:41], v[202:205], v[158:161], v[38:41]
	v_mfma_f32_16x16x32_bf16 v[34:37], v[210:213], v[158:161], v[34:37]
	v_mfma_f32_16x16x32_bf16 v[22:25], v[202:205], v[178:181], v[22:25]
	v_mfma_f32_16x16x32_bf16 v[18:21], v[210:213], v[178:181], v[18:21]
	v_mfma_f32_16x16x32_bf16 v[6:9], v[202:205], v[192:195], v[6:9]
	v_mfma_f32_16x16x32_bf16 v[2:5], v[210:213], v[192:195], v[2:5]
	s_add_i32 s46, s46, 2
	s_add_u32 s36, s36, 0x100
	s_addc_u32 s37, s37, 0
	s_add_u32 s18, s18, 0x100
	s_addc_u32 s19, s19, 0
	s_cmp_gt_u32 s46, 29
	s_barrier
	s_cbranch_scc0 .LBB0_426
	s_ashr_i32 s18, s4, 3
	v_lshl_add_u32 v178, s2, 8, v1
	s_lshl_b32 s2, s4, 8
	s_and_b32 s2, s2, 0x700
	s_ashr_i32 s19, s18, 31
	v_or_b32_e32 v132, s2, v187
	s_lshl_b64 s[2:3], s[18:19], 27
	s_add_u32 s2, s55, s2
	s_addc_u32 s3, s56, s3
	v_mov_b32_e32 v130, v236
	v_lshlrev_b32_e32 v176, 1, v132
	v_mov_b32_e32 v177, v0
	v_ashrrev_i32_e32 v179, 31, v178
	v_lshl_add_u64 v[180:181], s[2:3], 0, v[176:177]
	v_ashrrev_i32_e32 v131, 31, v130
	v_lshlrev_b64 v[184:185], 12, v[178:179]
	v_lshl_add_u64 v[174:175], v[130:131], 4, s[6:7]
	v_lshl_add_u64 v[130:131], v[180:181], 0, v[184:185]
	v_mov_b64_e32 v[250:251], v[130:131]
	s_mov_b32 s20, 0x20000
	s_mov_b32 s21, 0
	v_lshl_add_u64 v[252:253], v[250:251], 0, s[20:21]
	global_load_dwordx4 v[198:201], v[252:253], off
	global_load_dwordx4 v[202:205], v[252:253], off offset:256
	s_mov_b32 s20, 0x30000
	v_lshl_add_u64 v[252:253], v[250:251], 0, s[20:21]
	global_load_dwordx4 v[206:209], v[252:253], off
	global_load_dwordx4 v[210:213], v[252:253], off offset:256
	global_load_dwordx4 v[154:157], v[130:131], off
	s_cmp_gt_i32 s18, 0
	s_cselect_b64 s[2:3], -1, 0
	s_cmp_lt_i32 s18, 1
	s_cbranch_scc1 .LBB0_429
	global_load_dwordx4 v[158:161], v[174:175], off
	s_branch .LBB0_430

; __device__ __forceinline__ int otid(int wv) { int t = (wv << 6) | (int)__builtin_amdgcn_mbcnt_hi(~0u, __builtin_amdgcn_mbcnt_lo(~0u, 0u)); asm volatile("" : "+v"(t)); return t; }
; __device__ __forceinline__ void grid_bar(unsigned* ctr, unsigned& target, int G, int wv) {
;     asm volatile("s_waitcnt vmcnt(0) lgkmcnt(0)" ::: "memory");
;     __syncthreads();
;     target = (unsigned)__builtin_amdgcn_readfirstlane((int)(target + (unsigned)G));
;     if (otid(wv) == 0) {
;         __builtin_amdgcn_fence(__ATOMIC_RELEASE, "agent");
;         asm volatile("s_waitcnt vmcnt(0)" ::: "memory");
;         __hip_atomic_fetch_add(ctr, 1u, __ATOMIC_RELAXED, __HIP_MEMORY_SCOPE_AGENT);
;         while (__hip_atomic_load(ctr, __ATOMIC_RELAXED, __HIP_MEMORY_SCOPE_AGENT) < target) __builtin_amdgcn_s_sleep(1);
;         __builtin_amdgcn_fence(__ATOMIC_ACQUIRE, "agent");
;         asm volatile("s_waitcnt vmcnt(0)" ::: "memory");
;     }
;     __syncthreads();
; }
.LBB0_528:
	s_setprio 0
	s_waitcnt vmcnt(0) lgkmcnt(0)
	v_mov_b32_e32 v1, v236
	s_waitcnt lgkmcnt(0)
	s_barrier
	s_add_i32 s10, s24, s33
	s_nop 0
	v_cmp_eq_u32_e32 vcc, 0, v1
	s_and_saveexec_b64 s[0:1], vcc
	s_cbranch_execz .LBB0_534
	s_mov_b64 s[2:3], exec
	buffer_wbl2 sc1
	s_waitcnt vmcnt(0)
	s_waitcnt vmcnt(0)
	v_mbcnt_lo_u32_b32 v1, s2, 0
	v_mbcnt_hi_u32_b32 v1, s3, v1
	v_cmp_eq_u32_e32 vcc, 0, v1
	s_and_saveexec_b64 s[4:5], vcc
	s_cbranch_execz .LBB0_531
	s_bcnt1_i32_b64 s2, s[2:3]
	v_mov_b32_e32 v1, s2
	v_readlane_b32 s2, v254, 30
	v_readlane_b32 s3, v254, 31
	s_nop 4
	global_atomic_add v0, v1, s[2:3]

; __device__ __forceinline__ int otid(int wv) { int t = (wv << 6) | (int)__builtin_amdgcn_mbcnt_hi(~0u, __builtin_amdgcn_mbcnt_lo(~0u, 0u)); asm volatile("" : "+v"(t)); return t; }
;     __device__ bool next(int i, Unit& u) const { return map((long)i * G + c, u); }
; #define PG8_WAIT_V(n) asm volatile("s_waitcnt vmcnt(" #n ")" ::: "memory")
; #define PG8_BAR __builtin_amdgcn_s_barrier()
; template <class Epi, class Sched, bool AREMAP>
; __device__ __forceinline__ void gemm_phase(LAS unsigned char* lds, const Gemm g, const Sched& S, const Epi& E, int wv) {
;     const int tid = otid(wv), wid = __builtin_amdgcn_readfirstlane(tid >> 6), lane = tid & 63, wr = wid >> 2, wc = wid & 3, fr = lane & 15, fq = lane >> 4;
;     const int K = g.K, nt = K / BK;
;     unsigned voffA[2], voffB[2];
; #pragma unroll
;     for (int i = 0; i < 2; ++i) { int R, C; stage_rc(tid * 16 + i * 8192, R, C); const int Rb = Epi::PERM ? ((R & ~31) + perm32(R & 31)) : R;
;         const int Ra = AREMAP ? ((R >> 6) * 128 + (R & 63)) : R;
;         voffA[i] = (unsigned)(Ra * g.lda + C) * 2u; voffB[i] = (unsigned)(Rb * g.ldb + C) * 2u; }
;     const size_t kstep = (size_t)(BK * 2);
;     const size_t hstepA = (size_t)(AREMAP ? 64 : HALF) * g.lda * 2, hstepB = (size_t)HALF * g.ldb * 2;
;     const size_t tstepA = (size_t)BM * g.lda * 2, tstepB = (size_t)BM * g.ldb * 2;
;     const unsigned ldsw = (unsigned)wid * 1024u;
;     const int aoff = lds_byte(wr * 64 + fr, fq * 8), boff = lds_byte(wc * 32 + fr, fq * 8);
;     ...
;     Unit cur, nxt; int ui = 0;
;     if (!S.next(0, cur)) return;
;     f32x4 acc[2][2][4][2];
; #pragma unroll
;     for (int a = 0; a < 2; ++a)
; #pragma unroll
;         for (int b = 0; b < 2; ++b)
; #pragma unroll
;             for (int m = 0; m < 4; ++m)
; #pragma unroll
;                 for (int n = 0; n < 2; ++n) acc[a][b][m][n] = (f32x4){0.f, 0.f, 0.f, 0.f};
;     bf16x8 At[4][2], B0[2][2], B1[2][2];
;     ...
;     const char* cA = PG8_UA(cur); const char* cB = PG8_UB(cur);
;     PG8_STAGE(PG8_SB(0, 0), cB, voffB); PG8_STAGE(PG8_SA(0, 0), cA, voffA); PG8_STAGE(PG8_SB(0, 1), cB + hstepB, voffB); PG8_STAGE(PG8_SA(0, 1), cA + hstepA, voffA);
;     if (wr == 1) PG8_BAR;
;     PG8_WAIT_V(4); PG8_BAR;
;     PG8_STAGE(PG8_SB(1, 0), cB + kstep, voffB); PG8_STAGE(PG8_SA(1, 0), cA + kstep, voffA); PG8_STAGE(PG8_SB(1, 1), cB + hstepB + kstep, voffB);
;     PG8_WAIT_V(6); PG8_BAR;
.LBB0_540:
	v_writelane_b32 v255, s34, 31
	s_andn2_b64 vcc, exec, s[2:3]
	s_nop 0
	v_writelane_b32 v255, s35, 32
	s_cbranch_vccnz .LBB0_590
	v_bfe_i32 v3, v13, 27, 1
	v_lshlrev_b32_e32 v2, 4, v13
	v_lshrrev_b32_e32 v3, 22, v3
	v_add_u32_e32 v3, v2, v3
	v_and_b32_e32 v3, 0xfffffc00, v3
	v_ashrrev_i32_e32 v1, 31, v13
	v_sub_u32_e32 v3, v2, v3
	v_lshrrev_b32_e32 v1, 26, v1
	v_lshrrev_b32_e32 v4, 4, v3
	v_add_u32_e32 v1, v13, v1
	v_bitop3_b32 v4, v4, v3, 32 bitop3:0x6c
	v_ashrrev_i32_e32 v3, 31, v3
	v_ashrrev_i32_e32 v1, 6, v1
	v_lshrrev_b32_e32 v3, 26, v3
	v_lshlrev_b32_e32 v5, 3, v1
	v_add_u32_e32 v3, v4, v3
	v_and_b32_e32 v5, 0xffff0, v5
	v_ashrrev_i32_e32 v10, 6, v3
	v_add_u32_e32 v3, v10, v5
	v_lshlrev_b32_e32 v5, 5, v1
	v_and_b32_e32 v11, 32, v5
	v_mul_i32_i24_e32 v5, 64, v10
	v_sub_u32_e32 v4, v4, v5
	v_ashrrev_i16_sdwa v4, v240, sext(v4) dst_sel:DWORD dst_unused:UNUSED_PAD src0_sel:DWORD src1_sel:BYTE_0
	v_bfe_i32 v12, v4, 0, 16
	v_lshl_or_b32 v3, v3, 11, v11
	v_add_u32_e32 v2, 0x2000, v2
	v_add_lshl_u32 v196, v3, v12, 1
	v_ashrrev_i32_e32 v3, 31, v2
	v_lshrrev_b32_e32 v3, 22, v3
	v_add_u32_e32 v3, v2, v3
	v_ashrrev_i32_e32 v14, 10, v3
	v_mul_i32_i24_e32 v3, 0x400, v14
	v_sub_u32_e32 v2, v2, v3
	s_add_u32 s41, s0, 0x28e00000
	v_lshrrev_b32_e32 v3, 4, v2
	s_addc_u32 s46, s1, 0
	v_bitop3_b32 v2, v3, v2, 32 bitop3:0x6c
	s_add_u32 s47, s0, 0x4400000
	v_ashrrev_i32_e32 v4, 31, v2
	s_addc_u32 s52, s1, 0
	v_lshrrev_b32_e32 v4, 26, v4
	s_ashr_i32 s1, s37, 6
	s_ashr_i32 s29, s28, 31
	s_ashr_i32 s31, s30, 31
	s_ashr_i32 s0, s37, 8
	v_add_u32_e32 v4, v2, v4
	s_lshl_b32 s53, s1, 10
	s_lshl_b64 s[2:3], s[28:29], 20
	s_lshl_b64 s[18:19], s[30:31], 20
	v_lshlrev_b32_e32 v3, 3, v14
	v_ashrrev_i32_e32 v15, 6, v4
	v_and_b32_e32 v4, 0xc0, v4
	s_add_u32 s34, s47, s18
	v_and_b32_e32 v3, 0xffff0, v3
	v_lshlrev_b32_e32 v5, 5, v14
	v_sub_u32_e32 v2, v2, v4
	s_addc_u32 s35, s52, s19
	s_add_i32 s29, s53, 0
	v_add_u32_e32 v3, v15, v3
	v_and_b32_e32 v16, 32, v5
	v_ashrrev_i16_sdwa v2, v240, sext(v2) dst_sel:DWORD dst_unused:UNUSED_PAD src0_sel:DWORD src1_sel:BYTE_0
	s_add_i32 m0, s29, 0x10000
	v_bfe_i32 v17, v2, 0, 16
	v_lshl_or_b32 v2, v3, 11, v16
	global_load_lds_dwordx4 v196, s[34:35]
	s_add_i32 m0, s29, 0x12000
	v_add_lshl_u32 v198, v2, v17, 1
	s_add_u32 s2, s41, s2
	global_load_lds_dwordx4 v198, s[34:35]
	s_addc_u32 s3, s46, s3
	s_mov_b32 m0, s29
	s_add_i32 s31, s29, 0x2000
	global_load_lds_dwordx4 v196, s[2:3]
	s_mov_b32 m0, s31
	s_add_u32 s18, s34, 0x80000
	global_load_lds_dwordx4 v198, s[2:3]
	s_addc_u32 s19, s35, 0
	s_add_i32 m0, s29, 0x14000
	v_mov_b32_e32 v197, v0
	global_load_lds_dwordx4 v196, s[18:19]
	s_add_i32 m0, s29, 0x16000
	v_mov_b32_e32 v199, v0
	global_load_lds_dwordx4 v198, s[18:19]
	s_add_u32 s18, s2, 0x80000
	s_addc_u32 s19, s3, 0
	s_add_i32 s55, s29, 0x4000
	s_mov_b32 m0, s55
	s_add_i32 s56, s29, 0x6000
	global_load_lds_dwordx4 v196, s[18:19]
	s_mov_b32 m0, s56
	v_lshl_add_u64 v[8:9], s[34:35], 0, v[196:197]
	global_load_lds_dwordx4 v198, s[18:19]
	v_lshl_add_u64 v[6:7], s[34:35], 0, v[198:199]
	v_lshl_add_u64 v[4:5], s[2:3], 0, v[196:197]
	s_cmp_lg_u32 s0, 1
	v_lshl_add_u64 v[2:3], s[2:3], 0, v[198:199]
	s_mov_b32 s33, 1.0
	s_cbranch_scc1 .LBB0_543
	s_barrier
	s_setprio 1

; #define PG8_STAGE(bufoff, gbase, voff) do { _Pragma("unroll") for (int _i = 0; _i < 2; ++_i) \
;         __builtin_amdgcn_global_load_lds((const unsigned*)((const char*)(gbase) + (voff)[_i]), (LAS unsigned*)(lds + (bufoff) + ldsw + _i * 8192), 16, 0, 0); } while (0)
; #define PG8_LDA(dst, b, h) do { _Pragma("unroll") for (int m = 0; m < 4; ++m) _Pragma("unroll") for (int k = 0; k < 2; ++k) dst[m][k] = *(const LAS bf16x8*)(lds + PG8_SA(b, h) + aoff + m * 2048 + k * 1024); } while (0)
; #define PG8_LDB(dst, b, h) do { _Pragma("unroll") for (int n = 0; n < 2; ++n) _Pragma("unroll") for (int k = 0; k < 2; ++k) dst[n][k] = *(const LAS bf16x8*)(lds + PG8_SB(b, h) + boff + n * 2048 + k * 1024); } while (0)
; #define PG8_MMA(ai, bj, At, Bt) do { __builtin_amdgcn_s_setprio(1); _Pragma("unroll") for (int m = 0; m < 4; ++m) _Pragma("unroll") for (int n = 0; n < 2; ++n) _Pragma("unroll") for (int k = 0; k < 2; ++k) \
;         acc[ai][bj][m][n] = __builtin_amdgcn_mfma_f32_16x16x32_bf16(Bt[n][k], At[m][k], acc[ai][bj][m][n], 0, 0, 0); __builtin_amdgcn_s_setprio(0); } while (0)
; #define PG8_WAIT_V(n) asm volatile("s_waitcnt vmcnt(" #n ")" ::: "memory")
; #define PG8_WAIT_L(n) asm volatile("s_waitcnt lgkmcnt(" #n ")" ::: "memory")
; #define PG8_BAR __builtin_amdgcn_s_barrier()
; #define PG8_SCHED __builtin_amdgcn_sched_barrier(0)
; template <class Epi, class Sched, bool AREMAP>
; __device__ __forceinline__ void gemm_phase(LAS unsigned char* lds, const Gemm g, const Sched& S, const Epi& E, int wv) {
;     ...
;             PG8_LDB(B0, 0, 0); PG8_SCHED; PG8_LDA(At, 0, 0); PG8_STAGE(PG8_SA(1, 1), a1 + hstepA, voffA);
;             PG8_WAIT_L(8); PG8_BAR; PG8_WAIT_L(0); PG8_MMA(0, 0, At, B0); PG8_BAR; PG8_SCHED;
;             PG8_LDB(B1, 0, 1); PG8_STAGE(PG8_SB(0, 0), b2, voffB);
;             PG8_BAR; PG8_WAIT_L(0); PG8_MMA(0, 1, At, B1); PG8_BAR;
;             PG8_LDA(At, 0, 1); PG8_STAGE(PG8_SA(0, 0), a2, voffA);
;             PG8_BAR; PG8_WAIT_L(0); PG8_MMA(1, 0, At, B0); PG8_BAR; PG8_SCHED;
;             PG8_STAGE(PG8_SB(0, 1), b2 + hstepB, voffB);
;             PG8_WAIT_V(6); PG8_BAR; PG8_MMA(1, 1, At, B1); PG8_BAR;
.LBB0_552:
	s_add_u32 s34, s2, 0x100
	s_addc_u32 s35, s3, 0
	s_add_i32 s38, 0, 0x10000
	v_add_u32_e32 v1, s38, v250
	ds_read_b128 v[130:133], v1
	ds_read_b128 v[134:137], v1 offset:1024
	ds_read_b128 v[138:141], v1 offset:2048
	ds_read_b128 v[142:145], v1 offset:3072
	s_cmp_eq_u32 s76, 28
	s_cselect_b32 s67, s23, s35
	s_cselect_b32 s66, s72, s34
	s_cselect_b32 s63, s21, s75
	s_cselect_b32 s62, s73, s74
	v_lshl_add_u64 v[178:179], s[2:3], 0, v[202:203]
	s_add_i32 m0, s29, 0xc000
	ds_read_b128 v[146:149], v252
	ds_read_b128 v[150:153], v252 offset:1024
	ds_read_b128 v[154:157], v252 offset:2048
	ds_read_b128 v[158:161], v252 offset:3072
	ds_read_b128 v[162:165], v252 offset:4096
	ds_read_b128 v[166:169], v252 offset:5120
	ds_read_b128 v[170:173], v252 offset:6144
	ds_read_b128 v[174:177], v252 offset:7168
	global_load_lds_dwordx4 v[178:179], off
	v_lshl_add_u64 v[178:179], s[2:3], 0, v[200:201]
	s_add_i32 m0, s29, 0xe000
	s_nop 0
	global_load_lds_dwordx4 v[178:179], off
	s_waitcnt lgkmcnt(8)
	s_barrier
	s_waitcnt lgkmcnt(0)
	s_waitcnt lgkmcnt(0)
	v_mfma_f32_16x16x32_bf16 v[126:129], v[130:133], v[146:149], v[126:129]
	v_mfma_f32_16x16x32_bf16 v[110:113], v[138:141], v[146:149], v[110:113]
	v_mfma_f32_16x16x32_bf16 v[122:125], v[130:133], v[154:157], v[122:125]
	v_mfma_f32_16x16x32_bf16 v[106:109], v[138:141], v[154:157], v[106:109]
	v_mfma_f32_16x16x32_bf16 v[118:121], v[130:133], v[162:165], v[118:121]
	v_mfma_f32_16x16x32_bf16 v[102:105], v[138:141], v[162:165], v[102:105]
	v_mfma_f32_16x16x32_bf16 v[114:117], v[130:133], v[170:173], v[114:117]
	v_mfma_f32_16x16x32_bf16 v[98:101], v[138:141], v[170:173], v[98:101]
	v_mfma_f32_16x16x32_bf16 v[126:129], v[134:137], v[150:153], v[126:129]
	v_mfma_f32_16x16x32_bf16 v[110:113], v[142:145], v[150:153], v[110:113]
	v_mfma_f32_16x16x32_bf16 v[122:125], v[134:137], v[158:161], v[122:125]
	v_mfma_f32_16x16x32_bf16 v[106:109], v[142:145], v[158:161], v[106:109]
	v_mfma_f32_16x16x32_bf16 v[118:121], v[134:137], v[166:169], v[118:121]
	v_mfma_f32_16x16x32_bf16 v[102:105], v[142:145], v[166:169], v[102:105]
	v_mfma_f32_16x16x32_bf16 v[114:117], v[134:137], v[174:177], v[114:117]
	v_mfma_f32_16x16x32_bf16 v[98:101], v[142:145], v[174:177], v[98:101]
	s_barrier
	s_add_i32 s39, 0, 0x14000
	s_add_i32 s2, s38, s53
	v_add_u32_e32 v1, s39, v250
	v_lshl_add_u64 v[186:187], s[62:63], 0, v[196:197]
	s_mov_b32 m0, s2
	ds_read_b128 v[178:181], v1
	ds_read_b128 v[182:185], v1 offset:1024
	ds_read_b128 v[192:195], v1 offset:2048
	ds_read_b128 v[204:207], v1 offset:3072
	global_load_lds_dwordx4 v[186:187], off
	v_lshl_add_u64 v[208:209], s[62:63], 0, v[198:199]
	s_add_i32 m0, s2, 0x2000
	s_nop 0
	global_load_lds_dwordx4 v[208:209], off
	s_barrier
	s_waitcnt lgkmcnt(0)
	s_waitcnt lgkmcnt(0)
	v_mfma_f32_16x16x32_bf16 v[94:97], v[178:181], v[146:149], v[94:97]
	v_mfma_f32_16x16x32_bf16 v[78:81], v[192:195], v[146:149], v[78:81]
	v_mfma_f32_16x16x32_bf16 v[90:93], v[178:181], v[154:157], v[90:93]
	v_mfma_f32_16x16x32_bf16 v[74:77], v[192:195], v[154:157], v[74:77]
	v_mfma_f32_16x16x32_bf16 v[86:89], v[178:181], v[162:165], v[86:89]
	v_mfma_f32_16x16x32_bf16 v[70:73], v[192:195], v[162:165], v[70:73]
	v_mfma_f32_16x16x32_bf16 v[82:85], v[178:181], v[170:173], v[82:85]
	v_mfma_f32_16x16x32_bf16 v[66:69], v[192:195], v[170:173], v[66:69]
	v_mfma_f32_16x16x32_bf16 v[94:97], v[182:185], v[150:153], v[94:97]
	v_mfma_f32_16x16x32_bf16 v[78:81], v[204:207], v[150:153], v[78:81]
	v_mfma_f32_16x16x32_bf16 v[90:93], v[182:185], v[158:161], v[90:93]
	v_mfma_f32_16x16x32_bf16 v[74:77], v[204:207], v[158:161], v[74:77]
	v_mfma_f32_16x16x32_bf16 v[86:89], v[182:185], v[166:169], v[86:89]
	v_mfma_f32_16x16x32_bf16 v[70:73], v[204:207], v[166:169], v[70:73]
	v_mfma_f32_16x16x32_bf16 v[82:85], v[182:185], v[174:177], v[82:85]
	v_mfma_f32_16x16x32_bf16 v[66:69], v[204:207], v[174:177], v[66:69]
	s_mov_b32 m0, s29
	v_lshl_add_u64 v[210:211], s[66:67], 0, v[196:197]
	s_barrier
	ds_read_b128 v[146:149], v252 offset:16384
	ds_read_b128 v[150:153], v252 offset:17408
	ds_read_b128 v[154:157], v252 offset:18432
	ds_read_b128 v[158:161], v252 offset:19456
	ds_read_b128 v[162:165], v252 offset:20480
	ds_read_b128 v[166:169], v252 offset:21504
	ds_read_b128 v[170:173], v252 offset:22528
	ds_read_b128 v[174:177], v252 offset:23552
	global_load_lds_dwordx4 v[210:211], off
	v_lshl_add_u64 v[212:213], s[66:67], 0, v[198:199]
	s_mov_b32 m0, s31
	s_nop 0
	global_load_lds_dwordx4 v[212:213], off
	s_barrier
	s_waitcnt lgkmcnt(0)
	s_waitcnt lgkmcnt(0)
	v_mfma_f32_16x16x32_bf16 v[62:65], v[130:133], v[146:149], v[62:65]
	v_mfma_f32_16x16x32_bf16 v[46:49], v[138:141], v[146:149], v[46:49]
	v_mfma_f32_16x16x32_bf16 v[58:61], v[130:133], v[154:157], v[58:61]
	v_mfma_f32_16x16x32_bf16 v[42:45], v[138:141], v[154:157], v[42:45]
	v_mfma_f32_16x16x32_bf16 v[54:57], v[130:133], v[162:165], v[54:57]
	v_mfma_f32_16x16x32_bf16 v[38:41], v[138:141], v[162:165], v[38:41]
	v_mfma_f32_16x16x32_bf16 v[50:53], v[130:133], v[170:173], v[50:53]
	v_mfma_f32_16x16x32_bf16 v[34:37], v[138:141], v[170:173], v[34:37]
	v_mfma_f32_16x16x32_bf16 v[62:65], v[134:137], v[150:153], v[62:65]
	v_mfma_f32_16x16x32_bf16 v[46:49], v[142:145], v[150:153], v[46:49]
	v_mfma_f32_16x16x32_bf16 v[58:61], v[134:137], v[158:161], v[58:61]
	v_mfma_f32_16x16x32_bf16 v[42:45], v[142:145], v[158:161], v[42:45]
	v_mfma_f32_16x16x32_bf16 v[54:57], v[134:137], v[166:169], v[54:57]
	v_mfma_f32_16x16x32_bf16 v[38:41], v[142:145], v[166:169], v[38:41]
	v_mfma_f32_16x16x32_bf16 v[50:53], v[134:137], v[174:177], v[50:53]
	v_mfma_f32_16x16x32_bf16 v[34:37], v[142:145], v[174:177], v[34:37]
	s_barrier
; #define PG8_STAGE(bufoff, gbase, voff) do { _Pragma("unroll") for (int _i = 0; _i < 2; ++_i) \
;         __builtin_amdgcn_global_load_lds((const unsigned*)((const char*)(gbase) + (voff)[_i]), (LAS unsigned*)(lds + (bufoff) + ldsw + _i * 8192), 16, 0, 0); } while (0)
; #define PG8_LDA(dst, b, h) do { _Pragma("unroll") for (int m = 0; m < 4; ++m) _Pragma("unroll") for (int k = 0; k < 2; ++k) dst[m][k] = *(const LAS bf16x8*)(lds + PG8_SA(b, h) + aoff + m * 2048 + k * 1024); } while (0)
; #define PG8_LDB(dst, b, h) do { _Pragma("unroll") for (int n = 0; n < 2; ++n) _Pragma("unroll") for (int k = 0; k < 2; ++k) dst[n][k] = *(const LAS bf16x8*)(lds + PG8_SB(b, h) + boff + n * 2048 + k * 1024); } while (0)
; #define PG8_MMA(ai, bj, At, Bt) do { __builtin_amdgcn_s_setprio(1); _Pragma("unroll") for (int m = 0; m < 4; ++m) _Pragma("unroll") for (int n = 0; n < 2; ++n) _Pragma("unroll") for (int k = 0; k < 2; ++k) \
;         acc[ai][bj][m][n] = __builtin_amdgcn_mfma_f32_16x16x32_bf16(Bt[n][k], At[m][k], acc[ai][bj][m][n], 0, 0, 0); __builtin_amdgcn_s_setprio(0); } while (0)
; #define PG8_WAIT_V(n) asm volatile("s_waitcnt vmcnt(" #n ")" ::: "memory")
; #define PG8_WAIT_L(n) asm volatile("s_waitcnt lgkmcnt(" #n ")" ::: "memory")
; #define PG8_BAR __builtin_amdgcn_s_barrier()
; #define PG8_SCHED __builtin_amdgcn_sched_barrier(0)
; template <class Epi, class Sched, bool AREMAP>
; __device__ __forceinline__ void gemm_phase(LAS unsigned char* lds, const Gemm g, const Sched& S, const Epi& E, int wv) {
;     ...
;             PG8_LDA(At, 0, 1); PG8_STAGE(PG8_SA(0, 0), a2, voffA);
;             PG8_BAR; PG8_WAIT_L(0); PG8_MMA(1, 0, At, B0); PG8_BAR; PG8_SCHED;
;             PG8_STAGE(PG8_SB(0, 1), b2 + hstepB, voffB);
;             PG8_WAIT_V(6); PG8_BAR; PG8_MMA(1, 1, At, B1); PG8_BAR;
;             PG8_LDB(B0, 1, 0); PG8_SCHED; PG8_LDA(At, 1, 0); PG8_STAGE(PG8_SA(0, 1), a2 + hstepA, voffA);
;             PG8_WAIT_L(8); PG8_BAR; PG8_WAIT_L(0); PG8_MMA(0, 0, At, B0); PG8_BAR; PG8_SCHED;
;             PG8_LDB(B1, 1, 1); PG8_STAGE(PG8_SB(1, 0), b3, voffB);
;             PG8_BAR; PG8_WAIT_L(0); PG8_MMA(0, 1, At, B1); PG8_BAR;
;             PG8_LDA(At, 1, 1); PG8_STAGE(PG8_SA(1, 0), a3, voffA);
;             PG8_BAR; PG8_WAIT_L(0); PG8_MMA(1, 0, At, B0); PG8_BAR; PG8_SCHED;
	s_add_u32 s2, s62, 0x80000
	s_addc_u32 s3, s63, 0
	s_add_i32 s38, s39, s53
	v_lshl_add_u64 v[130:131], s[2:3], 0, v[196:197]
	s_mov_b32 m0, s38
	s_nop 0
	global_load_lds_dwordx4 v[130:131], off
	v_lshl_add_u64 v[130:131], s[2:3], 0, v[198:199]
	s_add_i32 m0, s38, 0x2000
	s_nop 0
	global_load_lds_dwordx4 v[130:131], off
	s_waitcnt vmcnt(6)
	s_barrier
	v_mfma_f32_16x16x32_bf16 v[30:33], v[178:181], v[146:149], v[30:33]
	v_mfma_f32_16x16x32_bf16 v[14:17], v[192:195], v[146:149], v[14:17]
	v_mfma_f32_16x16x32_bf16 v[26:29], v[178:181], v[154:157], v[26:29]
	v_mfma_f32_16x16x32_bf16 v[10:13], v[192:195], v[154:157], v[10:13]
	v_mfma_f32_16x16x32_bf16 v[22:25], v[178:181], v[162:165], v[22:25]
	v_mfma_f32_16x16x32_bf16 v[6:9], v[192:195], v[162:165], v[6:9]
	v_mfma_f32_16x16x32_bf16 v[18:21], v[178:181], v[170:173], v[18:21]
	v_mfma_f32_16x16x32_bf16 v[2:5], v[192:195], v[170:173], v[2:5]
	v_mfma_f32_16x16x32_bf16 v[30:33], v[182:185], v[150:153], v[30:33]
	v_mfma_f32_16x16x32_bf16 v[14:17], v[204:207], v[150:153], v[14:17]
	v_mfma_f32_16x16x32_bf16 v[26:29], v[182:185], v[158:161], v[26:29]
	v_mfma_f32_16x16x32_bf16 v[10:13], v[204:207], v[158:161], v[10:13]
	v_mfma_f32_16x16x32_bf16 v[22:25], v[182:185], v[166:169], v[22:25]
	v_mfma_f32_16x16x32_bf16 v[6:9], v[204:207], v[166:169], v[6:9]
	v_mfma_f32_16x16x32_bf16 v[18:21], v[182:185], v[174:177], v[18:21]
	v_mfma_f32_16x16x32_bf16 v[2:5], v[204:207], v[174:177], v[2:5]
	s_add_i32 s38, 0, 0x18000
	v_add_u32_e32 v1, s38, v250
	s_barrier
	ds_read_b128 v[130:133], v1
	ds_read_b128 v[134:137], v1 offset:1024
	ds_read_b128 v[138:141], v1 offset:2048
	ds_read_b128 v[142:145], v1 offset:3072
	s_add_u32 s2, s66, 0x80000
	s_addc_u32 s3, s67, 0
	s_mov_b32 m0, s55
	v_lshl_add_u64 v[178:179], s[2:3], 0, v[196:197]
	ds_read_b128 v[146:149], v252 offset:32768
	ds_read_b128 v[150:153], v252 offset:33792
	ds_read_b128 v[154:157], v252 offset:34816
	ds_read_b128 v[158:161], v252 offset:35840
	ds_read_b128 v[162:165], v252 offset:36864
	ds_read_b128 v[166:169], v252 offset:37888
	ds_read_b128 v[170:173], v252 offset:38912
	ds_read_b128 v[174:177], v252 offset:39936
	global_load_lds_dwordx4 v[178:179], off
	v_lshl_add_u64 v[178:179], s[2:3], 0, v[198:199]
	s_mov_b32 m0, s56
	s_nop 0
	global_load_lds_dwordx4 v[178:179], off
	s_waitcnt lgkmcnt(8)
	s_barrier
	s_waitcnt lgkmcnt(0)
	s_waitcnt lgkmcnt(0)
	v_mfma_f32_16x16x32_bf16 v[126:129], v[130:133], v[146:149], v[126:129]
	v_mfma_f32_16x16x32_bf16 v[110:113], v[138:141], v[146:149], v[110:113]
	v_mfma_f32_16x16x32_bf16 v[122:125], v[130:133], v[154:157], v[122:125]
	v_mfma_f32_16x16x32_bf16 v[106:109], v[138:141], v[154:157], v[106:109]
	v_mfma_f32_16x16x32_bf16 v[118:121], v[130:133], v[162:165], v[118:121]
	v_mfma_f32_16x16x32_bf16 v[102:105], v[138:141], v[162:165], v[102:105]
	v_mfma_f32_16x16x32_bf16 v[114:117], v[130:133], v[170:173], v[114:117]
	v_mfma_f32_16x16x32_bf16 v[98:101], v[138:141], v[170:173], v[98:101]
	v_mfma_f32_16x16x32_bf16 v[126:129], v[134:137], v[150:153], v[126:129]
	v_mfma_f32_16x16x32_bf16 v[110:113], v[142:145], v[150:153], v[110:113]
	v_mfma_f32_16x16x32_bf16 v[122:125], v[134:137], v[158:161], v[122:125]
	v_mfma_f32_16x16x32_bf16 v[106:109], v[142:145], v[158:161], v[106:109]
	v_mfma_f32_16x16x32_bf16 v[118:121], v[134:137], v[166:169], v[118:121]
	v_mfma_f32_16x16x32_bf16 v[102:105], v[142:145], v[166:169], v[102:105]
	v_mfma_f32_16x16x32_bf16 v[114:117], v[134:137], v[174:177], v[114:117]
	v_mfma_f32_16x16x32_bf16 v[98:101], v[142:145], v[174:177], v[98:101]
	s_barrier
	s_add_i32 s39, 0, 0x1c000
	s_add_i32 s2, s38, s53
	v_add_u32_e32 v1, s39, v250
	v_lshl_add_u64 v[186:187], v[186:187], 0, s[86:87]
	s_mov_b32 m0, s2
	ds_read_b128 v[178:181], v1
	ds_read_b128 v[182:185], v1 offset:1024
	ds_read_b128 v[192:195], v1 offset:2048
	ds_read_b128 v[204:207], v1 offset:3072
	global_load_lds_dwordx4 v[186:187], off
	v_lshl_add_u64 v[186:187], v[208:209], 0, s[86:87]
	s_add_i32 m0, s2, 0x2000
	s_nop 0
	global_load_lds_dwordx4 v[186:187], off
	s_barrier
; #define PG8_STAGE(bufoff, gbase, voff) do { _Pragma("unroll") for (int _i = 0; _i < 2; ++_i) \
;         __builtin_amdgcn_global_load_lds((const unsigned*)((const char*)(gbase) + (voff)[_i]), (LAS unsigned*)(lds + (bufoff) + ldsw + _i * 8192), 16, 0, 0); } while (0)
; #define PG8_LDA(dst, b, h) do { _Pragma("unroll") for (int m = 0; m < 4; ++m) _Pragma("unroll") for (int k = 0; k < 2; ++k) dst[m][k] = *(const LAS bf16x8*)(lds + PG8_SA(b, h) + aoff + m * 2048 + k * 1024); } while (0)
; #define PG8_MMA(ai, bj, At, Bt) do { __builtin_amdgcn_s_setprio(1); _Pragma("unroll") for (int m = 0; m < 4; ++m) _Pragma("unroll") for (int n = 0; n < 2; ++n) _Pragma("unroll") for (int k = 0; k < 2; ++k) \
;         acc[ai][bj][m][n] = __builtin_amdgcn_mfma_f32_16x16x32_bf16(Bt[n][k], At[m][k], acc[ai][bj][m][n], 0, 0, 0); __builtin_amdgcn_s_setprio(0); } while (0)
; #define PG8_WAIT_V(n) asm volatile("s_waitcnt vmcnt(" #n ")" ::: "memory")
; #define PG8_WAIT_L(n) asm volatile("s_waitcnt lgkmcnt(" #n ")" ::: "memory")
; #define PG8_BAR __builtin_amdgcn_s_barrier()
; #define PG8_SCHED __builtin_amdgcn_sched_barrier(0)
; template <class Epi, class Sched, bool AREMAP>
; __device__ __forceinline__ void gemm_phase(LAS unsigned char* lds, const Gemm g, const Sched& S, const Epi& E, int wv) {
;     ...
;             PG8_BAR; PG8_WAIT_L(0); PG8_MMA(0, 1, At, B1); PG8_BAR;
;             PG8_LDA(At, 1, 1); PG8_STAGE(PG8_SA(1, 0), a3, voffA);
;             PG8_BAR; PG8_WAIT_L(0); PG8_MMA(1, 0, At, B0); PG8_BAR; PG8_SCHED;
;             PG8_STAGE(PG8_SB(1, 1), b3 + hstepB, voffB);
;             PG8_WAIT_V(6); PG8_BAR; PG8_MMA(1, 1, At, B1); PG8_BAR;
;     __device__ __forceinline__ void operator()(const f32x4 (&acc)[2][2][4][2], const Unit& u, int wr, int wc, int fr, int fq) const {
;         const int row0 = u.pm * BM + wr * 64 + fr, col0 = u.pn * BM + wc * 32 + 4 * fq;
;         const float* gv = gate + (size_t)(u.pm >> 3) * 12288 + col0;
; #pragma unroll
;         for (int ai = 0; ai < 2; ++ai) {
;             float mu[4], rs[4];
; #pragma unroll
;             for (int m = 0; m < 4; ++m) { mu[m] = 0.f; rs[m] = 1.f;
;                 if (stats) { const float* sp = stats + (size_t)(row0 + ai * HALF + m * 16) * 2; mu[m] = sp[0]; rs[m] = sp[1]; } }
	s_waitcnt lgkmcnt(0)
	s_waitcnt lgkmcnt(0)
	v_mfma_f32_16x16x32_bf16 v[94:97], v[178:181], v[146:149], v[94:97]
	v_mfma_f32_16x16x32_bf16 v[78:81], v[192:195], v[146:149], v[78:81]
	v_mfma_f32_16x16x32_bf16 v[90:93], v[178:181], v[154:157], v[90:93]
	v_mfma_f32_16x16x32_bf16 v[74:77], v[192:195], v[154:157], v[74:77]
	v_mfma_f32_16x16x32_bf16 v[86:89], v[178:181], v[162:165], v[86:89]
	v_mfma_f32_16x16x32_bf16 v[70:73], v[192:195], v[162:165], v[70:73]
	v_mfma_f32_16x16x32_bf16 v[82:85], v[178:181], v[170:173], v[82:85]
	v_mfma_f32_16x16x32_bf16 v[66:69], v[192:195], v[170:173], v[66:69]
	v_mfma_f32_16x16x32_bf16 v[94:97], v[182:185], v[150:153], v[94:97]
	v_mfma_f32_16x16x32_bf16 v[78:81], v[204:207], v[150:153], v[78:81]
	v_mfma_f32_16x16x32_bf16 v[90:93], v[182:185], v[158:161], v[90:93]
	v_mfma_f32_16x16x32_bf16 v[74:77], v[204:207], v[158:161], v[74:77]
	v_mfma_f32_16x16x32_bf16 v[86:89], v[182:185], v[166:169], v[86:89]
	v_mfma_f32_16x16x32_bf16 v[70:73], v[204:207], v[166:169], v[70:73]
	v_mfma_f32_16x16x32_bf16 v[82:85], v[182:185], v[174:177], v[82:85]
	v_mfma_f32_16x16x32_bf16 v[66:69], v[204:207], v[174:177], v[66:69]
	s_mov_b32 m0, s57
	v_lshl_add_u64 v[186:187], v[210:211], 0, s[86:87]
	s_barrier
	ds_read_b128 v[146:149], v252 offset:49152
	ds_read_b128 v[150:153], v252 offset:50176
	ds_read_b128 v[154:157], v252 offset:51200
	ds_read_b128 v[158:161], v252 offset:52224
	ds_read_b128 v[162:165], v252 offset:53248
	ds_read_b128 v[166:169], v252 offset:54272
	ds_read_b128 v[170:173], v252 offset:55296
	ds_read_b128 v[174:177], v252 offset:56320
	global_load_lds_dwordx4 v[186:187], off
	v_lshl_add_u64 v[186:187], v[212:213], 0, s[86:87]
	s_mov_b32 m0, s65
	s_nop 0
	global_load_lds_dwordx4 v[186:187], off
	s_barrier
	s_waitcnt lgkmcnt(0)
	s_waitcnt lgkmcnt(0)
	v_mfma_f32_16x16x32_bf16 v[62:65], v[130:133], v[146:149], v[62:65]
	v_mfma_f32_16x16x32_bf16 v[46:49], v[138:141], v[146:149], v[46:49]
	v_mfma_f32_16x16x32_bf16 v[58:61], v[130:133], v[154:157], v[58:61]
	v_mfma_f32_16x16x32_bf16 v[42:45], v[138:141], v[154:157], v[42:45]
	v_mfma_f32_16x16x32_bf16 v[54:57], v[130:133], v[162:165], v[54:57]
	v_mfma_f32_16x16x32_bf16 v[38:41], v[138:141], v[162:165], v[38:41]
	v_mfma_f32_16x16x32_bf16 v[50:53], v[130:133], v[170:173], v[50:53]
	v_mfma_f32_16x16x32_bf16 v[34:37], v[138:141], v[170:173], v[34:37]
	v_mfma_f32_16x16x32_bf16 v[62:65], v[134:137], v[150:153], v[62:65]
	v_mfma_f32_16x16x32_bf16 v[46:49], v[142:145], v[150:153], v[46:49]
	v_mfma_f32_16x16x32_bf16 v[58:61], v[134:137], v[158:161], v[58:61]
	v_mfma_f32_16x16x32_bf16 v[42:45], v[142:145], v[158:161], v[42:45]
	v_mfma_f32_16x16x32_bf16 v[54:57], v[134:137], v[166:169], v[54:57]
	v_mfma_f32_16x16x32_bf16 v[38:41], v[142:145], v[166:169], v[38:41]
	v_mfma_f32_16x16x32_bf16 v[50:53], v[134:137], v[174:177], v[50:53]
	v_mfma_f32_16x16x32_bf16 v[34:37], v[142:145], v[174:177], v[34:37]
	s_barrier
	s_add_u32 s2, s62, 0x80080
	s_addc_u32 s3, s63, 0
	s_add_i32 s38, s39, s53
	v_lshl_add_u64 v[130:131], s[2:3], 0, v[196:197]
	s_mov_b32 m0, s38
	s_nop 0
	global_load_lds_dwordx4 v[130:131], off
	v_lshl_add_u64 v[130:131], s[2:3], 0, v[198:199]
	s_add_i32 m0, s38, 0x2000
	s_nop 0
	global_load_lds_dwordx4 v[130:131], off
	s_waitcnt vmcnt(6)
	s_barrier
	v_mfma_f32_16x16x32_bf16 v[30:33], v[178:181], v[146:149], v[30:33]
	v_mfma_f32_16x16x32_bf16 v[14:17], v[192:195], v[146:149], v[14:17]
	v_mfma_f32_16x16x32_bf16 v[26:29], v[178:181], v[154:157], v[26:29]
	v_mfma_f32_16x16x32_bf16 v[10:13], v[192:195], v[154:157], v[10:13]
	v_mfma_f32_16x16x32_bf16 v[22:25], v[178:181], v[162:165], v[22:25]
	v_mfma_f32_16x16x32_bf16 v[6:9], v[192:195], v[162:165], v[6:9]
	v_mfma_f32_16x16x32_bf16 v[18:21], v[178:181], v[170:173], v[18:21]
	v_mfma_f32_16x16x32_bf16 v[2:5], v[192:195], v[170:173], v[2:5]
	v_mfma_f32_16x16x32_bf16 v[30:33], v[182:185], v[150:153], v[30:33]
	v_mfma_f32_16x16x32_bf16 v[14:17], v[204:207], v[150:153], v[14:17]
	v_mfma_f32_16x16x32_bf16 v[26:29], v[182:185], v[158:161], v[26:29]
	v_mfma_f32_16x16x32_bf16 v[10:13], v[204:207], v[158:161], v[10:13]
	v_mfma_f32_16x16x32_bf16 v[22:25], v[182:185], v[166:169], v[22:25]
	v_mfma_f32_16x16x32_bf16 v[6:9], v[204:207], v[166:169], v[6:9]
	v_mfma_f32_16x16x32_bf16 v[18:21], v[182:185], v[174:177], v[18:21]
	v_mfma_f32_16x16x32_bf16 v[2:5], v[204:207], v[174:177], v[2:5]
	s_add_i32 s76, s76, 2
	s_add_u32 s74, s74, 0x100
	s_addc_u32 s75, s75, 0
	s_cmp_gt_u32 s76, 29
	s_mov_b64 s[2:3], s[34:35]
	s_barrier
	s_cbranch_scc0 .LBB0_552
	v_lshl_add_u32 v212, s28, 8, v249
	v_cndmask_b32_e64 v1, 0, 1, s[18:19]
	v_mov_b32_e32 v216, 1.0
	v_cmp_ne_u32_e64 s[2:3], 1, v1
	s_andn2_b64 vcc, exec, s[18:19]
	v_ashrrev_i32_e32 v213, 31, v212
	s_cbranch_vccnz .LBB0_556
	v_lshl_add_u64 v[130:131], v[212:213], 3, s[12:13]
	global_load_dwordx2 v[134:135], v[130:131], off
	v_or_b32_e32 v140, 16, v212
	s_and_b64 vcc, exec, s[2:3]
	v_ashrrev_i32_e32 v141, 31, v140
	s_cbranch_vccnz .LBB0_557

; __device__ __forceinline__ int otid(int wv) { int t = (wv << 6) | (int)__builtin_amdgcn_mbcnt_hi(~0u, __builtin_amdgcn_mbcnt_lo(~0u, 0u)); asm volatile("" : "+v"(t)); return t; }
; __device__ __forceinline__ void grid_bar(unsigned* ctr, unsigned& target, int G, int wv) {
;     asm volatile("s_waitcnt vmcnt(0) lgkmcnt(0)" ::: "memory");
;     __syncthreads();
;     target = (unsigned)__builtin_amdgcn_readfirstlane((int)(target + (unsigned)G));
;     if (otid(wv) == 0) {
;         __builtin_amdgcn_fence(__ATOMIC_RELEASE, "agent");
;         asm volatile("s_waitcnt vmcnt(0)" ::: "memory");
;         __hip_atomic_fetch_add(ctr, 1u, __ATOMIC_RELAXED, __HIP_MEMORY_SCOPE_AGENT);
;         while (__hip_atomic_load(ctr, __ATOMIC_RELAXED, __HIP_MEMORY_SCOPE_AGENT) < target) __builtin_amdgcn_s_sleep(1);
;         __builtin_amdgcn_fence(__ATOMIC_ACQUIRE, "agent");
;         asm volatile("s_waitcnt vmcnt(0)" ::: "memory");
;     }
;     __syncthreads();
; }
.LBB0_590:
	s_setprio 0
	s_waitcnt vmcnt(0) lgkmcnt(0)
	v_mov_b32_e32 v1, v236
	s_waitcnt lgkmcnt(0)
	s_barrier
	s_add_i32 s10, s10, s33
	s_nop 0
	v_cmp_eq_u32_e32 vcc, 0, v1
	s_and_saveexec_b64 s[0:1], vcc
	s_cbranch_execz .LBB0_596
	s_mov_b64 s[2:3], exec
	buffer_wbl2 sc1
	s_waitcnt vmcnt(0)
	s_waitcnt vmcnt(0)
	v_mbcnt_lo_u32_b32 v1, s2, 0
	v_mbcnt_hi_u32_b32 v1, s3, v1
	v_cmp_eq_u32_e32 vcc, 0, v1
	s_and_saveexec_b64 s[4:5], vcc
	s_cbranch_execz .LBB0_593
	s_bcnt1_i32_b64 s2, s[2:3]
	v_mov_b32_e32 v1, s2
	v_readlane_b32 s2, v254, 30
	v_readlane_b32 s3, v254, 31
	s_nop 4
	global_atomic_add v0, v1, s[2:3]

; __device__ __forceinline__ int otid(int wv) { int t = (wv << 6) | (int)__builtin_amdgcn_mbcnt_hi(~0u, __builtin_amdgcn_mbcnt_lo(~0u, 0u)); asm volatile("" : "+v"(t)); return t; }
; __device__ __forceinline__ void grid_bar(unsigned* ctr, unsigned& target, int G, int wv) {
;     asm volatile("s_waitcnt vmcnt(0) lgkmcnt(0)" ::: "memory");
;     __syncthreads();
;     target = (unsigned)__builtin_amdgcn_readfirstlane((int)(target + (unsigned)G));
;     if (otid(wv) == 0) {
;         __builtin_amdgcn_fence(__ATOMIC_RELEASE, "agent");
;         asm volatile("s_waitcnt vmcnt(0)" ::: "memory");
;         __hip_atomic_fetch_add(ctr, 1u, __ATOMIC_RELAXED, __HIP_MEMORY_SCOPE_AGENT);
;         while (__hip_atomic_load(ctr, __ATOMIC_RELAXED, __HIP_MEMORY_SCOPE_AGENT) < target) __builtin_amdgcn_s_sleep(1);
;         __builtin_amdgcn_fence(__ATOMIC_ACQUIRE, "agent");
;         asm volatile("s_waitcnt vmcnt(0)" ::: "memory");
;     }
;     __syncthreads();
; }
.LBB0_605:
	s_or_b64 exec, exec, s[4:5]
	s_waitcnt lgkmcnt(0)
	s_barrier
	s_setprio 0
	s_waitcnt vmcnt(0) lgkmcnt(0)
	v_mov_b32_e32 v1, v236
	s_barrier
	s_add_i32 s20, s10, s33
	s_nop 0
	v_cmp_eq_u32_e32 vcc, 0, v1
	s_and_saveexec_b64 s[0:1], vcc
	s_cbranch_execz .LBB0_611
	s_mov_b64 s[2:3], exec
	buffer_wbl2 sc1
	s_waitcnt vmcnt(0)
	s_waitcnt vmcnt(0)
	v_mbcnt_lo_u32_b32 v1, s2, 0
	v_mbcnt_hi_u32_b32 v1, s3, v1
	v_cmp_eq_u32_e32 vcc, 0, v1
	s_and_saveexec_b64 s[4:5], vcc
	s_cbranch_execz .LBB0_608
	s_bcnt1_i32_b64 s2, s[2:3]
	v_mov_b32_e32 v1, s2
	v_readlane_b32 s2, v254, 30
	v_readlane_b32 s3, v254, 31
	s_nop 4
	global_atomic_add v0, v1, s[2:3]

; __device__ __forceinline__ int otid(int wv) { int t = (wv << 6) | (int)__builtin_amdgcn_mbcnt_hi(~0u, __builtin_amdgcn_mbcnt_lo(~0u, 0u)); asm volatile("" : "+v"(t)); return t; }
;     __device__ bool next(int i, Unit& u) const { return map((long)i * G + c, u); }
; #define PG8_WAIT_V(n) asm volatile("s_waitcnt vmcnt(" #n ")" ::: "memory")
; #define PG8_BAR __builtin_amdgcn_s_barrier()
; template <class Epi, class Sched, bool AREMAP>
; __device__ __forceinline__ void gemm_phase(LAS unsigned char* lds, const Gemm g, const Sched& S, const Epi& E, int wv) {
;     const int tid = otid(wv), wid = __builtin_amdgcn_readfirstlane(tid >> 6), lane = tid & 63, wr = wid >> 2, wc = wid & 3, fr = lane & 15, fq = lane >> 4;
;     const int K = g.K, nt = K / BK;
;     unsigned voffA[2], voffB[2];
; #pragma unroll
;     for (int i = 0; i < 2; ++i) { int R, C; stage_rc(tid * 16 + i * 8192, R, C); const int Rb = Epi::PERM ? ((R & ~31) + perm32(R & 31)) : R;
;         const int Ra = AREMAP ? ((R >> 6) * 128 + (R & 63)) : R;
;         voffA[i] = (unsigned)(Ra * g.lda + C) * 2u; voffB[i] = (unsigned)(Rb * g.ldb + C) * 2u; }
;     const size_t kstep = (size_t)(BK * 2);
;     const size_t hstepA = (size_t)(AREMAP ? 64 : HALF) * g.lda * 2, hstepB = (size_t)HALF * g.ldb * 2;
;     const size_t tstepA = (size_t)BM * g.lda * 2, tstepB = (size_t)BM * g.ldb * 2;
;     const unsigned ldsw = (unsigned)wid * 1024u;
;     const int aoff = lds_byte(wr * 64 + fr, fq * 8), boff = lds_byte(wc * 32 + fr, fq * 8);
;     ...
;     Unit cur, nxt; int ui = 0;
;     if (!S.next(0, cur)) return;
;     f32x4 acc[2][2][4][2];
; #pragma unroll
;     for (int a = 0; a < 2; ++a)
; #pragma unroll
;         for (int b = 0; b < 2; ++b)
; #pragma unroll
;             for (int m = 0; m < 4; ++m)
; #pragma unroll
;                 for (int n = 0; n < 2; ++n) acc[a][b][m][n] = (f32x4){0.f, 0.f, 0.f, 0.f};
;     bf16x8 At[4][2], B0[2][2], B1[2][2];
;     ...
;     const char* cA = PG8_UA(cur); const char* cB = PG8_UB(cur);
;     PG8_STAGE(PG8_SB(0, 0), cB, voffB); PG8_STAGE(PG8_SA(0, 0), cA, voffA); PG8_STAGE(PG8_SB(0, 1), cB + hstepB, voffB); PG8_STAGE(PG8_SA(0, 1), cA + hstepA, voffA);
;     if (wr == 1) PG8_BAR;
;     PG8_WAIT_V(4); PG8_BAR;
;     PG8_STAGE(PG8_SB(1, 0), cB + kstep, voffB); PG8_STAGE(PG8_SA(1, 0), cA + kstep, voffA); PG8_STAGE(PG8_SB(1, 1), cB + hstepB + kstep, voffB);
;     PG8_WAIT_V(6); PG8_BAR;
.LBB0_611:
	s_or_b64 exec, exec, s[0:1]
	v_readlane_b32 s4, v254, 0
	v_readlane_b32 s10, v254, 6
	v_readlane_b32 s11, v254, 7
	v_readlane_b32 s14, v254, 10
	v_readlane_b32 s15, v254, 11
	s_mul_i32 s0, s78, 0x21000
	v_readlane_b32 s16, v254, 12
	s_mov_b64 s[10:11], s[14:15]
	v_readlane_b32 s17, v254, 13
	s_add_u32 s16, s10, s0
	v_readlane_b32 s18, v254, 14
	v_readlane_b32 s19, v254, 15
	s_addc_u32 s17, s11, 0
	v_readlane_b32 s0, v254, 18
	v_readlane_b32 s1, v254, 19
	s_mov_b64 s[18:19], s[16:17]
	s_mov_b32 s52, s58
	s_mov_b32 s53, s31
	v_mov_b32_e32 v11, v236
	s_barrier
	s_cmpk_gt_i32 s53, 0x15ff
	v_readfirstlane_b32 s59, v11
	v_readlane_b32 s5, v254, 1
	v_readlane_b32 s6, v254, 2
	v_readlane_b32 s7, v254, 3
	v_readlane_b32 s8, v254, 4
	v_readlane_b32 s9, v254, 5
	v_readlane_b32 s12, v254, 8
	v_readlane_b32 s13, v254, 9
	s_cbranch_scc1 .LBB0_631
	v_lshlrev_b32_e32 v1, 4, v11
	v_add_u32_e32 v2, 0x2000, v1
	v_ashrrev_i32_e32 v3, 31, v2
	v_lshrrev_b32_e32 v3, 22, v3
	v_add_u32_e32 v3, v2, v3
	v_ashrrev_i32_e32 v10, 10, v3
	v_mul_i32_i24_e32 v3, 0x400, v10
	v_sub_u32_e32 v2, v2, v3
	v_lshrrev_b32_e32 v3, 4, v2
	v_bitop3_b32 v2, v3, v2, 32 bitop3:0x6c
	v_ashrrev_i32_e32 v3, 31, v2
	v_lshrrev_b32_e32 v3, 26, v3
	v_add_u32_e32 v3, v2, v3
	v_lshlrev_b32_e32 v5, 3, v10
	v_ashrrev_i32_e32 v4, 6, v3
	v_and_b32_e32 v5, -16, v5
	v_add_u32_e32 v5, v4, v5
	v_and_b32_e32 v4, 3, v4
	s_mov_b32 s2, 0xfffe0
	v_lshrrev_b32_e32 v6, 2, v5
	v_lshlrev_b32_e32 v12, 1, v5
	v_and_b32_e32 v3, 0xc0, v3
	v_and_or_b32 v4, v5, s2, v4
	v_and_b32_e32 v6, 4, v6
	v_and_b32_e32 v7, 24, v12
	v_sub_u32_e32 v2, v2, v3
	v_or3_b32 v4, v4, v6, v7
	v_lshlrev_b32_e32 v6, 5, v10
	v_ashrrev_i16_sdwa v2, v240, sext(v2) dst_sel:DWORD dst_unused:UNUSED_PAD src0_sel:DWORD src1_sel:BYTE_0
	v_and_b32_e32 v6, 32, v6
	v_bfe_i32 v13, v2, 0, 16
	v_and_b32_e32 v14, 63, v5
	s_mov_b32 s4, 0xfff80
	v_add_lshl_u32 v2, v6, v13, 1
	v_and_or_b32 v3, v12, s4, v14
	v_lshl_add_u32 v154, v4, 12, v2
	v_lshl_add_u32 v156, v3, 12, v2
	v_bfe_i32 v2, v11, 27, 1
	v_lshrrev_b32_e32 v2, 22, v2
	v_add_u32_e32 v2, v1, v2
	v_and_b32_e32 v2, 0xfffffc00, v2
	v_sub_u32_e32 v1, v1, v2
	v_ashrrev_i32_e32 v3, 31, v11
	v_lshrrev_b32_e32 v2, 4, v1
	v_lshrrev_b32_e32 v3, 26, v3
	v_bitop3_b32 v2, v2, v1, 32 bitop3:0x6c
	v_ashrrev_i32_e32 v1, 31, v1
	v_add_u32_e32 v3, v11, v3
	s_add_u32 s65, s0, 0x8e00000
	v_lshrrev_b32_e32 v1, 26, v1
	v_ashrrev_i32_e32 v15, 6, v3
	s_addc_u32 s72, s1, 0
	v_add_u32_e32 v1, v2, v1
	v_lshlrev_b32_e32 v3, 3, v15
	s_add_u32 s73, s0, 0x4c00000
	v_ashrrev_i32_e32 v1, 6, v1
	v_and_b32_e32 v3, -16, v3
	s_addc_u32 s74, s1, 0
	v_add_u32_e32 v3, v1, v3
	v_and_b32_e32 v4, 3, v1
	s_ashr_i32 s55, s53, 31
	v_and_or_b32 v4, v3, s2, v4
	s_lshr_b32 s2, s55, 29
	v_lshlrev_b32_e32 v16, 1, v3
	v_mul_i32_i24_e32 v1, 64, v1
	v_and_b32_e32 v18, 63, v3
	s_add_i32 s2, s53, s2
	s_ashr_i32 s3, s59, 6
	v_sub_u32_e32 v1, v2, v1
	v_and_or_b32 v2, v16, s4, v18
	s_ashr_i32 s4, s2, 3
	s_and_b32 s2, s2, -8
	s_ashr_i32 s75, s59, 8
	s_lshl_b32 s91, s3, 10
	s_sub_i32 s2, s53, s2
	s_cmp_lt_i32 s2, 0
	s_movk_i32 s5, 0x2c1
	s_cselect_b32 s5, s5, 0x2c0
	s_mul_i32 s2, s5, s2
	s_add_i32 s2, s2, s4
	s_mul_hi_i32 s4, s2, 0x2e8ba2e9
	s_lshr_b32 s5, s4, 31
	s_ashr_i32 s4, s4, 5
	s_add_i32 s4, s4, s5
	s_lshl_b32 s5, s4, 2
	s_mulk_i32 s4, 0xb0
	s_sub_i32 s4, s2, s4
	s_bfe_u32 s2, s4, 0x2001d
	s_add_i32 s6, s4, s2
	s_sext_i32_i16 s2, s6
	s_and_b32 s6, s6, 0xfffc
	s_sub_i32 s4, s4, s6
	s_sext_i32_i16 s4, s4
	v_lshrrev_b32_e32 v5, 2, v3
	s_lshr_b32 s2, s2, 2
	s_add_i32 s76, s5, s4
	v_and_b32_e32 v5, 4, v5
	v_and_b32_e32 v6, 24, v16
	s_ashr_i32 s77, s76, 31
	s_bfe_i64 s[6:7], s[2:3], 0x100000
	v_or3_b32 v4, v4, v5, v6
	v_lshlrev_b32_e32 v5, 5, v15
	v_ashrrev_i16_sdwa v1, v240, sext(v1) dst_sel:DWORD dst_unused:UNUSED_PAD src0_sel:DWORD src1_sel:BYTE_0
	s_lshl_b64 s[4:5], s[76:77], 20
	s_lshl_b64 s[6:7], s[6:7], 20
	v_and_b32_e32 v5, 32, v5
	v_bfe_i32 v17, v1, 0, 16
	s_add_u32 s78, s73, s6
	v_add_lshl_u32 v1, v5, v17, 1
	s_addc_u32 s79, s74, s7
	s_add_i32 s10, s91, 0
	v_lshl_add_u32 v158, v4, 12, v1
	s_add_i32 m0, s10, 0x10000
	v_lshl_add_u32 v160, v2, 12, v1
	global_load_lds_dwordx4 v158, s[78:79]
	s_add_i32 m0, s10, 0x12000
	s_add_u32 s80, s65, s4
	global_load_lds_dwordx4 v154, s[78:79]
	s_addc_u32 s81, s72, s5
	s_mov_b32 m0, s10
	s_add_i32 s11, s10, 0x2000
	global_load_lds_dwordx4 v160, s[80:81]
	s_mov_b32 m0, s11
	s_add_u32 s4, s78, 0x80000
	global_load_lds_dwordx4 v156, s[80:81]
	s_addc_u32 s5, s79, 0
	s_add_i32 m0, s10, 0x14000
	v_mov_b32_e32 v159, v0
	global_load_lds_dwordx4 v158, s[4:5]
	s_add_i32 m0, s10, 0x16000
	v_mov_b32_e32 v155, v0
	global_load_lds_dwordx4 v154, s[4:5]
	s_add_u32 s4, s80, 0x40000
	s_addc_u32 s5, s81, 0
	s_add_i32 s12, s10, 0x4000
	s_mov_b32 m0, s12
	s_add_i32 s13, s10, 0x6000
	global_load_lds_dwordx4 v160, s[4:5]
	s_mov_b32 m0, s13
	v_mov_b32_e32 v161, v0
	global_load_lds_dwordx4 v156, s[4:5]
	v_mov_b32_e32 v157, v0
	v_writelane_b32 v255, s20, 29
	v_lshl_add_u64 v[8:9], s[78:79], 0, v[158:159]
	v_lshl_add_u64 v[6:7], s[78:79], 0, v[154:155]
	v_lshl_add_u64 v[4:5], s[80:81], 0, v[160:161]
	s_cmp_lg_u32 s75, 1
	v_lshl_add_u64 v[2:3], s[80:81], 0, v[156:157]
	s_cbranch_scc1 .LBB0_614
	s_barrier
	s_setprio 1

; #define PG8_STAGE(bufoff, gbase, voff) do { _Pragma("unroll") for (int _i = 0; _i < 2; ++_i) \
;         __builtin_amdgcn_global_load_lds((const unsigned*)((const char*)(gbase) + (voff)[_i]), (LAS unsigned*)(lds + (bufoff) + ldsw + _i * 8192), 16, 0, 0); } while (0)
; #define PG8_LDA(dst, b, h) do { _Pragma("unroll") for (int m = 0; m < 4; ++m) _Pragma("unroll") for (int k = 0; k < 2; ++k) dst[m][k] = *(const LAS bf16x8*)(lds + PG8_SA(b, h) + aoff + m * 2048 + k * 1024); } while (0)
; #define PG8_LDB(dst, b, h) do { _Pragma("unroll") for (int n = 0; n < 2; ++n) _Pragma("unroll") for (int k = 0; k < 2; ++k) dst[n][k] = *(const LAS bf16x8*)(lds + PG8_SB(b, h) + boff + n * 2048 + k * 1024); } while (0)
; #define PG8_MMA(ai, bj, At, Bt) do { __builtin_amdgcn_s_setprio(1); _Pragma("unroll") for (int m = 0; m < 4; ++m) _Pragma("unroll") for (int n = 0; n < 2; ++n) _Pragma("unroll") for (int k = 0; k < 2; ++k) \
;         acc[ai][bj][m][n] = __builtin_amdgcn_mfma_f32_16x16x32_bf16(Bt[n][k], At[m][k], acc[ai][bj][m][n], 0, 0, 0); __builtin_amdgcn_s_setprio(0); } while (0)
; #define PG8_WAIT_V(n) asm volatile("s_waitcnt vmcnt(" #n ")" ::: "memory")
; #define PG8_WAIT_L(n) asm volatile("s_waitcnt lgkmcnt(" #n ")" ::: "memory")
; #define PG8_BAR __builtin_amdgcn_s_barrier()
; #define PG8_SCHED __builtin_amdgcn_sched_barrier(0)
; template <class Epi, class Sched, bool AREMAP>
; __device__ __forceinline__ void gemm_phase(LAS unsigned char* lds, const Gemm g, const Sched& S, const Epi& E, int wv) {
;     ...
;             PG8_LDB(B0, 0, 0); PG8_SCHED; PG8_LDA(At, 0, 0); PG8_STAGE(PG8_SA(1, 1), a1 + hstepA, voffA);
;             PG8_WAIT_L(8); PG8_BAR; PG8_WAIT_L(0); PG8_MMA(0, 0, At, B0); PG8_BAR; PG8_SCHED;
;             PG8_LDB(B1, 0, 1); PG8_STAGE(PG8_SB(0, 0), b2, voffB);
;             PG8_BAR; PG8_WAIT_L(0); PG8_MMA(0, 1, At, B1); PG8_BAR;
;             PG8_LDA(At, 0, 1); PG8_STAGE(PG8_SA(0, 0), a2, voffA);
;             PG8_BAR; PG8_WAIT_L(0); PG8_MMA(1, 0, At, B0); PG8_BAR; PG8_SCHED;
;             PG8_STAGE(PG8_SB(0, 1), b2 + hstepB, voffB);
;             PG8_WAIT_V(6); PG8_BAR; PG8_MMA(1, 1, At, B1); PG8_BAR;
.LBB0_619:
	s_add_u32 s38, s78, 0xfffc0080
	s_addc_u32 s39, s79, -1
	s_add_i32 s33, 0, 0x10000
	v_add_u32_e32 v142, s33, v1
	ds_read_b128 v[130:133], v142
	ds_read_b128 v[134:137], v142 offset:1024
	ds_read_b128 v[138:141], v142 offset:2048
	ds_read_b128 v[142:145], v142 offset:3072
	s_cmp_eq_u32 vcc_hi, 28
	s_cselect_b32 s97, s46, s39
	s_cselect_b32 s96, s47, s38
	s_cselect_b32 s81, s63, vcc_lo
	s_cselect_b32 s80, s67, s77
	v_lshl_add_u64 v[178:179], s[78:79], 0, v[168:169]
	s_add_i32 m0, s10, 0xc000
	ds_read_b128 v[146:149], v183
	ds_read_b128 v[150:153], v183 offset:1024
	ds_read_b128 v[170:173], v183 offset:2048
	ds_read_b128 v[174:177], v183 offset:3072
	ds_read_b128 v[184:187], v183 offset:4096
	ds_read_b128 v[192:195], v183 offset:5120
	ds_read_b128 v[196:199], v183 offset:6144
	ds_read_b128 v[200:203], v183 offset:7168
	global_load_lds_dwordx4 v[178:179], off
	v_lshl_add_u64 v[178:179], s[78:79], 0, v[166:167]
	s_add_i32 m0, s10, 0xe000
	s_nop 0
	global_load_lds_dwordx4 v[178:179], off
	s_waitcnt lgkmcnt(8)
	s_barrier
	s_waitcnt lgkmcnt(0)
	s_waitcnt lgkmcnt(0)
	v_mfma_f32_16x16x32_bf16 v[126:129], v[130:133], v[146:149], v[126:129]
	v_mfma_f32_16x16x32_bf16 v[62:65], v[138:141], v[146:149], v[62:65]
	v_mfma_f32_16x16x32_bf16 v[118:121], v[130:133], v[170:173], v[118:121]
	v_mfma_f32_16x16x32_bf16 v[54:57], v[138:141], v[170:173], v[54:57]
	v_mfma_f32_16x16x32_bf16 v[110:113], v[130:133], v[184:187], v[110:113]
	v_mfma_f32_16x16x32_bf16 v[46:49], v[138:141], v[184:187], v[46:49]
	v_mfma_f32_16x16x32_bf16 v[102:105], v[130:133], v[196:199], v[102:105]
	v_mfma_f32_16x16x32_bf16 v[38:41], v[138:141], v[196:199], v[38:41]
	v_mfma_f32_16x16x32_bf16 v[126:129], v[134:137], v[150:153], v[126:129]
	v_mfma_f32_16x16x32_bf16 v[62:65], v[142:145], v[150:153], v[62:65]
	v_mfma_f32_16x16x32_bf16 v[118:121], v[134:137], v[174:177], v[118:121]
	v_mfma_f32_16x16x32_bf16 v[54:57], v[142:145], v[174:177], v[54:57]
	v_mfma_f32_16x16x32_bf16 v[110:113], v[134:137], v[192:195], v[110:113]
	v_mfma_f32_16x16x32_bf16 v[46:49], v[142:145], v[192:195], v[46:49]
	v_mfma_f32_16x16x32_bf16 v[102:105], v[134:137], v[200:203], v[102:105]
	v_mfma_f32_16x16x32_bf16 v[38:41], v[142:145], v[200:203], v[38:41]
	s_barrier
	s_add_i32 s58, 0, 0x14000
	v_add_u32_e32 v178, s58, v1
	s_add_i32 s33, s33, s91
	ds_read_b128 v[204:207], v178
	ds_read_b128 v[208:211], v178 offset:1024
	ds_read_b128 v[212:215], v178 offset:2048
	ds_read_b128 v[216:219], v178 offset:3072
	v_lshl_add_u64 v[178:179], s[80:81], 0, v[158:159]
	s_mov_b32 m0, s33
	v_lshl_add_u64 v[220:221], s[80:81], 0, v[154:155]
	global_load_lds_dwordx4 v[178:179], off
	s_add_i32 m0, s33, 0x2000
	s_nop 0
	global_load_lds_dwordx4 v[220:221], off
	s_barrier
	s_waitcnt lgkmcnt(0)
	s_waitcnt lgkmcnt(0)
	v_mfma_f32_16x16x32_bf16 v[122:125], v[204:207], v[146:149], v[122:125]
	v_mfma_f32_16x16x32_bf16 v[58:61], v[212:215], v[146:149], v[58:61]
	v_mfma_f32_16x16x32_bf16 v[114:117], v[204:207], v[170:173], v[114:117]
	v_mfma_f32_16x16x32_bf16 v[50:53], v[212:215], v[170:173], v[50:53]
	v_mfma_f32_16x16x32_bf16 v[106:109], v[204:207], v[184:187], v[106:109]
	v_mfma_f32_16x16x32_bf16 v[42:45], v[212:215], v[184:187], v[42:45]
	v_mfma_f32_16x16x32_bf16 v[98:101], v[204:207], v[196:199], v[98:101]
	v_mfma_f32_16x16x32_bf16 v[34:37], v[212:215], v[196:199], v[34:37]
	v_mfma_f32_16x16x32_bf16 v[122:125], v[208:211], v[150:153], v[122:125]
	v_mfma_f32_16x16x32_bf16 v[58:61], v[216:219], v[150:153], v[58:61]
	v_mfma_f32_16x16x32_bf16 v[114:117], v[208:211], v[174:177], v[114:117]
	v_mfma_f32_16x16x32_bf16 v[50:53], v[216:219], v[174:177], v[50:53]
	v_mfma_f32_16x16x32_bf16 v[106:109], v[208:211], v[192:195], v[106:109]
	v_mfma_f32_16x16x32_bf16 v[42:45], v[216:219], v[192:195], v[42:45]
	v_mfma_f32_16x16x32_bf16 v[98:101], v[208:211], v[200:203], v[98:101]
	v_mfma_f32_16x16x32_bf16 v[34:37], v[216:219], v[200:203], v[34:37]
	s_mov_b32 m0, s10
	v_lshl_add_u64 v[222:223], s[96:97], 0, v[160:161]
	s_barrier
	ds_read_b128 v[146:149], v183 offset:16384
	ds_read_b128 v[150:153], v183 offset:17408
	ds_read_b128 v[170:173], v183 offset:18432
	ds_read_b128 v[174:177], v183 offset:19456
	ds_read_b128 v[184:187], v183 offset:20480
	ds_read_b128 v[192:195], v183 offset:21504
	ds_read_b128 v[196:199], v183 offset:22528
	ds_read_b128 v[200:203], v183 offset:23552
	global_load_lds_dwordx4 v[222:223], off
	v_lshl_add_u64 v[224:225], s[96:97], 0, v[156:157]
	s_mov_b32 m0, s11
	s_nop 0
	global_load_lds_dwordx4 v[224:225], off
	s_barrier
	s_waitcnt lgkmcnt(0)
	s_waitcnt lgkmcnt(0)
	v_mfma_f32_16x16x32_bf16 v[94:97], v[130:133], v[146:149], v[94:97]
	v_mfma_f32_16x16x32_bf16 v[30:33], v[138:141], v[146:149], v[30:33]
	v_mfma_f32_16x16x32_bf16 v[86:89], v[130:133], v[170:173], v[86:89]
	v_mfma_f32_16x16x32_bf16 v[22:25], v[138:141], v[170:173], v[22:25]
	v_mfma_f32_16x16x32_bf16 v[78:81], v[130:133], v[184:187], v[78:81]
	v_mfma_f32_16x16x32_bf16 v[14:17], v[138:141], v[184:187], v[14:17]
	v_mfma_f32_16x16x32_bf16 v[70:73], v[130:133], v[196:199], v[70:73]
	v_mfma_f32_16x16x32_bf16 v[6:9], v[138:141], v[196:199], v[6:9]
	v_mfma_f32_16x16x32_bf16 v[94:97], v[134:137], v[150:153], v[94:97]
	v_mfma_f32_16x16x32_bf16 v[30:33], v[142:145], v[150:153], v[30:33]
	v_mfma_f32_16x16x32_bf16 v[86:89], v[134:137], v[174:177], v[86:89]
	v_mfma_f32_16x16x32_bf16 v[22:25], v[142:145], v[174:177], v[22:25]
	v_mfma_f32_16x16x32_bf16 v[78:81], v[134:137], v[192:195], v[78:81]
	v_mfma_f32_16x16x32_bf16 v[14:17], v[142:145], v[192:195], v[14:17]
	v_mfma_f32_16x16x32_bf16 v[70:73], v[134:137], v[200:203], v[70:73]
	v_mfma_f32_16x16x32_bf16 v[6:9], v[142:145], v[200:203], v[6:9]
	s_barrier
; #define PG8_STAGE(bufoff, gbase, voff) do { _Pragma("unroll") for (int _i = 0; _i < 2; ++_i) \
;         __builtin_amdgcn_global_load_lds((const unsigned*)((const char*)(gbase) + (voff)[_i]), (LAS unsigned*)(lds + (bufoff) + ldsw + _i * 8192), 16, 0, 0); } while (0)
; #define PG8_LDA(dst, b, h) do { _Pragma("unroll") for (int m = 0; m < 4; ++m) _Pragma("unroll") for (int k = 0; k < 2; ++k) dst[m][k] = *(const LAS bf16x8*)(lds + PG8_SA(b, h) + aoff + m * 2048 + k * 1024); } while (0)
; #define PG8_LDB(dst, b, h) do { _Pragma("unroll") for (int n = 0; n < 2; ++n) _Pragma("unroll") for (int k = 0; k < 2; ++k) dst[n][k] = *(const LAS bf16x8*)(lds + PG8_SB(b, h) + boff + n * 2048 + k * 1024); } while (0)
; #define PG8_MMA(ai, bj, At, Bt) do { __builtin_amdgcn_s_setprio(1); _Pragma("unroll") for (int m = 0; m < 4; ++m) _Pragma("unroll") for (int n = 0; n < 2; ++n) _Pragma("unroll") for (int k = 0; k < 2; ++k) \
;         acc[ai][bj][m][n] = __builtin_amdgcn_mfma_f32_16x16x32_bf16(Bt[n][k], At[m][k], acc[ai][bj][m][n], 0, 0, 0); __builtin_amdgcn_s_setprio(0); } while (0)
; #define PG8_WAIT_V(n) asm volatile("s_waitcnt vmcnt(" #n ")" ::: "memory")
; #define PG8_WAIT_L(n) asm volatile("s_waitcnt lgkmcnt(" #n ")" ::: "memory")
; #define PG8_BAR __builtin_amdgcn_s_barrier()
; #define PG8_SCHED __builtin_amdgcn_sched_barrier(0)
; template <class Epi, class Sched, bool AREMAP>
; __device__ __forceinline__ void gemm_phase(LAS unsigned char* lds, const Gemm g, const Sched& S, const Epi& E, int wv) {
;     ...
;             PG8_STAGE(PG8_SB(0, 1), b2 + hstepB, voffB);
;             PG8_WAIT_V(6); PG8_BAR; PG8_MMA(1, 1, At, B1); PG8_BAR;
;             PG8_LDB(B0, 1, 0); PG8_SCHED; PG8_LDA(At, 1, 0); PG8_STAGE(PG8_SA(0, 1), a2 + hstepA, voffA);
;             PG8_WAIT_L(8); PG8_BAR; PG8_WAIT_L(0); PG8_MMA(0, 0, At, B0); PG8_BAR; PG8_SCHED;
;             PG8_LDB(B1, 1, 1); PG8_STAGE(PG8_SB(1, 0), b3, voffB);
;             PG8_BAR; PG8_WAIT_L(0); PG8_MMA(0, 1, At, B1); PG8_BAR;
;             PG8_LDA(At, 1, 1); PG8_STAGE(PG8_SA(1, 0), a3, voffA);
	s_add_u32 s38, s80, 0x80000
	s_addc_u32 s39, s81, 0
	s_add_i32 s33, s58, s91
	v_lshl_add_u64 v[130:131], s[38:39], 0, v[158:159]
	s_mov_b32 m0, s33
	s_nop 0
	global_load_lds_dwordx4 v[130:131], off
	v_lshl_add_u64 v[130:131], s[38:39], 0, v[154:155]
	s_add_i32 m0, s33, 0x2000
	s_nop 0
	global_load_lds_dwordx4 v[130:131], off
	s_waitcnt vmcnt(6)
	s_barrier
	v_mfma_f32_16x16x32_bf16 v[90:93], v[204:207], v[146:149], v[90:93]
	v_mfma_f32_16x16x32_bf16 v[26:29], v[212:215], v[146:149], v[26:29]
	v_mfma_f32_16x16x32_bf16 v[82:85], v[204:207], v[170:173], v[82:85]
	v_mfma_f32_16x16x32_bf16 v[18:21], v[212:215], v[170:173], v[18:21]
	v_mfma_f32_16x16x32_bf16 v[74:77], v[204:207], v[184:187], v[74:77]
	v_mfma_f32_16x16x32_bf16 v[10:13], v[212:215], v[184:187], v[10:13]
	v_mfma_f32_16x16x32_bf16 v[66:69], v[204:207], v[196:199], v[66:69]
	v_mfma_f32_16x16x32_bf16 v[2:5], v[212:215], v[196:199], v[2:5]
	v_mfma_f32_16x16x32_bf16 v[90:93], v[208:211], v[150:153], v[90:93]
	v_mfma_f32_16x16x32_bf16 v[26:29], v[216:219], v[150:153], v[26:29]
	v_mfma_f32_16x16x32_bf16 v[82:85], v[208:211], v[174:177], v[82:85]
	v_mfma_f32_16x16x32_bf16 v[18:21], v[216:219], v[174:177], v[18:21]
	v_mfma_f32_16x16x32_bf16 v[74:77], v[208:211], v[192:195], v[74:77]
	v_mfma_f32_16x16x32_bf16 v[10:13], v[216:219], v[192:195], v[10:13]
	v_mfma_f32_16x16x32_bf16 v[66:69], v[208:211], v[200:203], v[66:69]
	v_mfma_f32_16x16x32_bf16 v[2:5], v[216:219], v[200:203], v[2:5]
	s_add_i32 s33, 0, 0x18000
	v_add_u32_e32 v142, s33, v1
	s_barrier
	ds_read_b128 v[130:133], v142
	ds_read_b128 v[134:137], v142 offset:1024
	ds_read_b128 v[138:141], v142 offset:2048
	ds_read_b128 v[142:145], v142 offset:3072
	s_add_u32 s38, s96, 0x40000
	s_addc_u32 s39, s97, 0
	s_mov_b32 m0, s12
	v_lshl_add_u64 v[204:205], s[38:39], 0, v[160:161]
	ds_read_b128 v[146:149], v183 offset:32768
	ds_read_b128 v[150:153], v183 offset:33792
	ds_read_b128 v[170:173], v183 offset:34816
	ds_read_b128 v[174:177], v183 offset:35840
	ds_read_b128 v[184:187], v183 offset:36864
	ds_read_b128 v[192:195], v183 offset:37888
	ds_read_b128 v[196:199], v183 offset:38912
	ds_read_b128 v[200:203], v183 offset:39936
	global_load_lds_dwordx4 v[204:205], off
	v_lshl_add_u64 v[204:205], s[38:39], 0, v[156:157]
	s_mov_b32 m0, s13
	s_nop 0
	global_load_lds_dwordx4 v[204:205], off
	s_waitcnt lgkmcnt(8)
	s_barrier
	s_waitcnt lgkmcnt(0)
	s_waitcnt lgkmcnt(0)
	v_mfma_f32_16x16x32_bf16 v[126:129], v[130:133], v[146:149], v[126:129]
	v_mfma_f32_16x16x32_bf16 v[62:65], v[138:141], v[146:149], v[62:65]
	v_mfma_f32_16x16x32_bf16 v[118:121], v[130:133], v[170:173], v[118:121]
	v_mfma_f32_16x16x32_bf16 v[54:57], v[138:141], v[170:173], v[54:57]
	v_mfma_f32_16x16x32_bf16 v[110:113], v[130:133], v[184:187], v[110:113]
	v_mfma_f32_16x16x32_bf16 v[46:49], v[138:141], v[184:187], v[46:49]
	v_mfma_f32_16x16x32_bf16 v[102:105], v[130:133], v[196:199], v[102:105]
	v_mfma_f32_16x16x32_bf16 v[38:41], v[138:141], v[196:199], v[38:41]
	v_mfma_f32_16x16x32_bf16 v[126:129], v[134:137], v[150:153], v[126:129]
	v_mfma_f32_16x16x32_bf16 v[62:65], v[142:145], v[150:153], v[62:65]
	v_mfma_f32_16x16x32_bf16 v[118:121], v[134:137], v[174:177], v[118:121]
	v_mfma_f32_16x16x32_bf16 v[54:57], v[142:145], v[174:177], v[54:57]
	v_mfma_f32_16x16x32_bf16 v[110:113], v[134:137], v[192:195], v[110:113]
	v_mfma_f32_16x16x32_bf16 v[46:49], v[142:145], v[192:195], v[46:49]
	v_mfma_f32_16x16x32_bf16 v[102:105], v[134:137], v[200:203], v[102:105]
	v_mfma_f32_16x16x32_bf16 v[38:41], v[142:145], v[200:203], v[38:41]
	s_barrier
	s_add_i32 s58, 0, 0x1c000
	s_add_i32 s33, s33, s91
	v_add_u32_e32 v216, s58, v1
	v_lshl_add_u64 v[178:179], v[178:179], 0, s[86:87]
	s_mov_b32 m0, s33
	ds_read_b128 v[204:207], v216
	ds_read_b128 v[208:211], v216 offset:1024
	ds_read_b128 v[212:215], v216 offset:2048
	ds_read_b128 v[216:219], v216 offset:3072
	global_load_lds_dwordx4 v[178:179], off
	v_lshl_add_u64 v[178:179], v[220:221], 0, s[86:87]
	s_add_i32 m0, s33, 0x2000
	s_nop 0
	global_load_lds_dwordx4 v[178:179], off
	s_barrier
	s_waitcnt lgkmcnt(0)
	s_waitcnt lgkmcnt(0)
	v_mfma_f32_16x16x32_bf16 v[122:125], v[204:207], v[146:149], v[122:125]
	v_mfma_f32_16x16x32_bf16 v[58:61], v[212:215], v[146:149], v[58:61]
	v_mfma_f32_16x16x32_bf16 v[114:117], v[204:207], v[170:173], v[114:117]
	v_mfma_f32_16x16x32_bf16 v[50:53], v[212:215], v[170:173], v[50:53]
	v_mfma_f32_16x16x32_bf16 v[106:109], v[204:207], v[184:187], v[106:109]
	v_mfma_f32_16x16x32_bf16 v[42:45], v[212:215], v[184:187], v[42:45]
	v_mfma_f32_16x16x32_bf16 v[98:101], v[204:207], v[196:199], v[98:101]
	v_mfma_f32_16x16x32_bf16 v[34:37], v[212:215], v[196:199], v[34:37]
	v_mfma_f32_16x16x32_bf16 v[122:125], v[208:211], v[150:153], v[122:125]
	v_mfma_f32_16x16x32_bf16 v[58:61], v[216:219], v[150:153], v[58:61]
	v_mfma_f32_16x16x32_bf16 v[114:117], v[208:211], v[174:177], v[114:117]
	v_mfma_f32_16x16x32_bf16 v[50:53], v[216:219], v[174:177], v[50:53]
	v_mfma_f32_16x16x32_bf16 v[106:109], v[208:211], v[192:195], v[106:109]
	v_mfma_f32_16x16x32_bf16 v[42:45], v[216:219], v[192:195], v[42:45]
	v_mfma_f32_16x16x32_bf16 v[98:101], v[208:211], v[200:203], v[98:101]
	v_mfma_f32_16x16x32_bf16 v[34:37], v[216:219], v[200:203], v[34:37]
	s_mov_b32 m0, s14
	v_lshl_add_u64 v[178:179], v[222:223], 0, s[86:87]
	s_barrier
	ds_read_b128 v[146:149], v183 offset:49152
	ds_read_b128 v[150:153], v183 offset:50176
	ds_read_b128 v[170:173], v183 offset:51200
	ds_read_b128 v[174:177], v183 offset:52224
	ds_read_b128 v[184:187], v183 offset:53248
	ds_read_b128 v[192:195], v183 offset:54272
	ds_read_b128 v[196:199], v183 offset:55296
	ds_read_b128 v[200:203], v183 offset:56320
	global_load_lds_dwordx4 v[178:179], off
	v_lshl_add_u64 v[178:179], v[224:225], 0, s[86:87]
	s_mov_b32 m0, s15
	s_nop 0
	global_load_lds_dwordx4 v[178:179], off
	s_barrier
; #define PG8_STAGE(bufoff, gbase, voff) do { _Pragma("unroll") for (int _i = 0; _i < 2; ++_i) \
;         __builtin_amdgcn_global_load_lds((const unsigned*)((const char*)(gbase) + (voff)[_i]), (LAS unsigned*)(lds + (bufoff) + ldsw + _i * 8192), 16, 0, 0); } while (0)
; #define PG8_MMA(ai, bj, At, Bt) do { __builtin_amdgcn_s_setprio(1); _Pragma("unroll") for (int m = 0; m < 4; ++m) _Pragma("unroll") for (int n = 0; n < 2; ++n) _Pragma("unroll") for (int k = 0; k < 2; ++k) \
;         acc[ai][bj][m][n] = __builtin_amdgcn_mfma_f32_16x16x32_bf16(Bt[n][k], At[m][k], acc[ai][bj][m][n], 0, 0, 0); __builtin_amdgcn_s_setprio(0); } while (0)
; #define PG8_WAIT_V(n) asm volatile("s_waitcnt vmcnt(" #n ")" ::: "memory")
; #define PG8_WAIT_L(n) asm volatile("s_waitcnt lgkmcnt(" #n ")" ::: "memory")
; #define PG8_BAR __builtin_amdgcn_s_barrier()
; #define PG8_SCHED __builtin_amdgcn_sched_barrier(0)
; template <class Epi, class Sched, bool AREMAP>
; __device__ __forceinline__ void gemm_phase(LAS unsigned char* lds, const Gemm g, const Sched& S, const Epi& E, int wv) {
;     ...
;             PG8_BAR; PG8_WAIT_L(0); PG8_MMA(1, 0, At, B0); PG8_BAR; PG8_SCHED;
;             PG8_STAGE(PG8_SB(1, 1), b3 + hstepB, voffB);
;             PG8_WAIT_V(6); PG8_BAR; PG8_MMA(1, 1, At, B1); PG8_BAR;
;         }
	s_waitcnt lgkmcnt(0)
	s_waitcnt lgkmcnt(0)
	v_mfma_f32_16x16x32_bf16 v[94:97], v[130:133], v[146:149], v[94:97]
	v_mfma_f32_16x16x32_bf16 v[30:33], v[138:141], v[146:149], v[30:33]
	v_mfma_f32_16x16x32_bf16 v[86:89], v[130:133], v[170:173], v[86:89]
	v_mfma_f32_16x16x32_bf16 v[22:25], v[138:141], v[170:173], v[22:25]
	v_mfma_f32_16x16x32_bf16 v[78:81], v[130:133], v[184:187], v[78:81]
	v_mfma_f32_16x16x32_bf16 v[14:17], v[138:141], v[184:187], v[14:17]
	v_mfma_f32_16x16x32_bf16 v[70:73], v[130:133], v[196:199], v[70:73]
	v_mfma_f32_16x16x32_bf16 v[6:9], v[138:141], v[196:199], v[6:9]
	v_mfma_f32_16x16x32_bf16 v[94:97], v[134:137], v[150:153], v[94:97]
	v_mfma_f32_16x16x32_bf16 v[30:33], v[142:145], v[150:153], v[30:33]
	v_mfma_f32_16x16x32_bf16 v[86:89], v[134:137], v[174:177], v[86:89]
	v_mfma_f32_16x16x32_bf16 v[22:25], v[142:145], v[174:177], v[22:25]
	v_mfma_f32_16x16x32_bf16 v[78:81], v[134:137], v[192:195], v[78:81]
	v_mfma_f32_16x16x32_bf16 v[14:17], v[142:145], v[192:195], v[14:17]
	v_mfma_f32_16x16x32_bf16 v[70:73], v[134:137], v[200:203], v[70:73]
	v_mfma_f32_16x16x32_bf16 v[6:9], v[142:145], v[200:203], v[6:9]
	s_barrier
	s_add_u32 s38, s80, 0x80080
	s_addc_u32 s39, s81, 0
	s_add_i32 s33, s58, s91
	v_lshl_add_u64 v[130:131], s[38:39], 0, v[158:159]
	s_mov_b32 m0, s33
	s_nop 0
	global_load_lds_dwordx4 v[130:131], off
	v_lshl_add_u64 v[130:131], s[38:39], 0, v[154:155]
	s_add_i32 m0, s33, 0x2000
	s_nop 0
	global_load_lds_dwordx4 v[130:131], off
	s_waitcnt vmcnt(6)
	s_barrier
	v_mfma_f32_16x16x32_bf16 v[90:93], v[204:207], v[146:149], v[90:93]
	v_mfma_f32_16x16x32_bf16 v[26:29], v[212:215], v[146:149], v[26:29]
	v_mfma_f32_16x16x32_bf16 v[82:85], v[204:207], v[170:173], v[82:85]
	v_mfma_f32_16x16x32_bf16 v[18:21], v[212:215], v[170:173], v[18:21]
	v_mfma_f32_16x16x32_bf16 v[74:77], v[204:207], v[184:187], v[74:77]
	v_mfma_f32_16x16x32_bf16 v[10:13], v[212:215], v[184:187], v[10:13]
	v_mfma_f32_16x16x32_bf16 v[66:69], v[204:207], v[196:199], v[66:69]
	v_mfma_f32_16x16x32_bf16 v[2:5], v[212:215], v[196:199], v[2:5]
	v_mfma_f32_16x16x32_bf16 v[90:93], v[208:211], v[150:153], v[90:93]
	v_mfma_f32_16x16x32_bf16 v[26:29], v[216:219], v[150:153], v[26:29]
	v_mfma_f32_16x16x32_bf16 v[82:85], v[208:211], v[174:177], v[82:85]
	v_mfma_f32_16x16x32_bf16 v[18:21], v[216:219], v[174:177], v[18:21]
	v_mfma_f32_16x16x32_bf16 v[74:77], v[208:211], v[192:195], v[74:77]
	v_mfma_f32_16x16x32_bf16 v[10:13], v[216:219], v[192:195], v[10:13]
	v_mfma_f32_16x16x32_bf16 v[66:69], v[208:211], v[200:203], v[66:69]
	v_mfma_f32_16x16x32_bf16 v[2:5], v[216:219], v[200:203], v[2:5]
	s_add_i32 vcc_hi, vcc_hi, 2
	s_add_u32 s77, s77, 0x100
	s_addc_u32 vcc_lo, vcc_lo, 0
	s_add_u32 s78, s78, 0x100
	s_addc_u32 s79, s79, 0
	s_cmp_gt_u32 vcc_hi, 29
	s_barrier
	s_cbranch_scc0 .LBB0_619
; __device__ __forceinline__ unsigned cvt_pk_bf16(float lo, float hi) { f32x2_t f = {lo, hi}; bf16x2_t v = __builtin_convertvector(f, bf16x2_t); return __builtin_bit_cast(unsigned, v); }
; __device__ __forceinline__ float sigmoidf_(float x) { return __builtin_amdgcn_rcpf(1.0f + __expf(-x)); }
;     __device__ __forceinline__ void operator()(const f32x4 (&acc)[2][2][4][2], const Unit& u, int wr, int wc, int fr, int fq) const {
;         const int lane = fq * 16 + fr;
;         const int ch0 = u.pn * 128 + wc * 32 + 8 * fq;
;         const int seg = u.pm * 2 + wr, tok0 = seg * 128 + fr;
;         const int src1 = (lane & 48) | ((fr + 15) & 15), src2 = (lane & 48) | ((fr + 14) & 15);
; #pragma unroll
;         for (int n = 0; n < 2; ++n) {
;             const int ch = ch0 + 4 * n;
;             f32x4 wv[3], wg[3];
; #pragma unroll
;             for (int k = 0; k < 3; ++k) { wv[k] = *(const f32x4*)(cw + k * NUP + ch); wg[k] = *(const f32x4*)(cw + k * NUP + DFF + ch); }
;             f32x4 pv1 = {0.f, 0.f, 0.f, 0.f}, pv2 = pv1, pg1 = pv1, pg2 = pv1;
; #pragma unroll
;             for (int q = 0; q < 8; ++q) {
;                 const int ai = q >> 2, m = q & 3;
;                 const f32x4 av = acc[ai][0][m][n], ag = acc[ai][1][m][n];
;                 f32x4 rv1, rv2, rg1, rg2;
; #pragma unroll
;                 for (int j = 0; j < 4; ++j) { rv1[j] = SHI(lane, av[j], src1); rv2[j] = SHI(lane, av[j], src2); rg1[j] = SHI(lane, ag[j], src1); rg2[j] = SHI(lane, ag[j], src2); }
;                 const f32x4 sv1 = fr >= 1 ? rv1 : pv1, sv2 = fr >= 2 ? rv2 : pv2, sg1 = fr >= 1 ? rg1 : pg1, sg2 = fr >= 2 ? rg2 : pg2;
;                 const f32x4 ov = wv[2] * av + wv[1] * sv1 + wv[0] * sv2;
;                 const f32x4 og = wg[2] * ag + wg[1] * sg1 + wg[0] * sg2;
;                 u32x2 w;
;                 w.x = cvt_pk_bf16(og[0] * sigmoidf_(og[0]) * ov[0], og[1] * sigmoidf_(og[1]) * ov[1]);
;                 w.y = cvt_pk_bf16(og[2] * sigmoidf_(og[2]) * ov[2], og[3] * sigmoidf_(og[3]) * ov[3]);
;                 *(u32x2*)(act + (size_t)(tok0 + q * 16) * DFF + ch) = w;
;                 if (q == 0 && fr < 2) { float* hp = halo + ((size_t)seg * 4 + fr) * NUP + ch; *(f32x4*)hp = av; *(f32x4*)(hp + DFF) = ag; }
;                 if (q == 7 && fr >= 14) { float* hp = halo + ((size_t)seg * 4 + (fr - 12)) * NUP + ch; *(f32x4*)hp = av; *(f32x4*)(hp + DFF) = ag; }
	v_lshl_or_b32 v170, s37, 7, v182
	s_lshl_b32 s37, s76, 1
	s_add_i32 s46, s37, s75
	s_ashr_i32 s47, s46, 31
	s_lshl_b64 s[76:77], s[46:47], 2
	v_lshl_add_u64 v[130:131], s[76:77], 0, v[162:163]
	s_mov_b32 s33, 0xb000
	v_ashrrev_i32_e32 v171, 31, v170
	v_lshl_or_b32 v184, s46, 7, v162
	v_mad_u64_u32 v[176:177], s[46:47], v130, s33, 0
	v_lshlrev_b64 v[142:143], 2, v[170:171]
	v_mad_i32_i24 v177, v131, s33, v177
	v_lshl_add_u64 v[130:131], s[24:25], 0, v[142:143]
	v_lshl_add_u64 v[138:139], s[26:27], 0, v[142:143]
	global_load_dwordx4 v[130:133], v[130:131], off
	v_lshl_add_u64 v[144:145], s[30:31], 0, v[142:143]
	global_load_dwordx4 v[146:149], v[138:139], off
	v_lshl_add_u64 v[172:173], s[18:19], 0, v[142:143]
	v_lshl_add_u64 v[138:139], s[28:29], 0, v[142:143]
	global_load_dwordx4 v[150:153], v[144:145], off
	global_load_dwordx4 v[134:137], v[172:173], off
	v_lshl_add_u64 v[142:143], s[34:35], 0, v[142:143]
	global_load_dwordx4 v[138:141], v[138:139], off
	v_mov_b32_dpp v199, v126 row_ror:1 row_mask:0xf bank_mask:0xf
	global_load_dwordx4 v[142:145], v[142:143], off
	v_mov_b32_dpp v204, v127 row_ror:1 row_mask:0xf bank_mask:0xf
	v_mov_b32_dpp v206, v128 row_ror:1 row_mask:0xf bank_mask:0xf
	v_mov_b32_dpp v208, v129 row_ror:1 row_mask:0xf bank_mask:0xf
	v_mov_b32_dpp v196, v126 row_ror:2 row_mask:0xf bank_mask:0xf
	v_mov_b32_dpp v186, v122 row_ror:1 row_mask:0xf bank_mask:0xf
	v_mov_b32_dpp v201, v127 row_ror:2 row_mask:0xf bank_mask:0xf
	v_mov_b32_dpp v198, v123 row_ror:1 row_mask:0xf bank_mask:0xf
	v_mov_b32_dpp v203, v128 row_ror:2 row_mask:0xf bank_mask:0xf
	v_mov_b32_dpp v200, v124 row_ror:1 row_mask:0xf bank_mask:0xf
	v_mov_b32_dpp v207, v129 row_ror:2 row_mask:0xf bank_mask:0xf
	v_mov_b32_dpp v205, v125 row_ror:1 row_mask:0xf bank_mask:0xf
	v_mov_b32_dpp v185, v122 row_ror:2 row_mask:0xf bank_mask:0xf
	v_mov_b32_dpp v187, v123 row_ror:2 row_mask:0xf bank_mask:0xf
	v_mov_b32_dpp v197, v124 row_ror:2 row_mask:0xf bank_mask:0xf
	v_mov_b32_dpp v202, v125 row_ror:2 row_mask:0xf bank_mask:0xf
	s_waitcnt lgkmcnt(0)
	v_cndmask_b32_e64 v175, v204, 0, s[0:1]
	v_cndmask_b32_e64 v174, v199, 0, s[0:1]
	v_cndmask_b32_e64 v179, v208, 0, s[0:1]
	v_cndmask_b32_e64 v178, v206, 0, s[0:1]
	v_cndmask_b32_e64 v193, 0, v201, s[2:3]
	v_cndmask_b32_e64 v192, 0, v196, s[2:3]
	v_cndmask_b32_e64 v195, 0, v207, s[2:3]
	v_cndmask_b32_e64 v194, 0, v203, s[2:3]
	v_cndmask_b32_e64 v211, v198, 0, s[0:1]
	v_cndmask_b32_e64 v210, v186, 0, s[0:1]
	v_cndmask_b32_e64 v213, v205, 0, s[0:1]
	v_cndmask_b32_e64 v212, v200, 0, s[0:1]
	v_cndmask_b32_e64 v215, 0, v187, s[2:3]
	v_cndmask_b32_e64 v214, 0, v185, s[2:3]
	v_cndmask_b32_e64 v217, 0, v202, s[2:3]
	v_cndmask_b32_e64 v216, 0, v197, s[2:3]
	s_movk_i32 s33, 0x2c00
	v_lshl_add_u64 v[176:177], s[22:23], 0, v[176:177]
	v_lshl_add_u64 v[176:177], v[170:171], 2, v[176:177]
	s_waitcnt vmcnt(0)
	v_pk_mul_f32 v[178:179], v[148:149], v[178:179]
	v_pk_mul_f32 v[174:175], v[146:147], v[174:175]
	v_pk_fma_f32 v[178:179], v[128:129], v[152:153], v[178:179]
	v_pk_fma_f32 v[174:175], v[126:127], v[150:151], v[174:175]
	v_pk_fma_f32 v[194:195], v[136:137], v[194:195], v[178:179]
	v_pk_fma_f32 v[174:175], v[134:135], v[192:193], v[174:175]
	v_pk_mul_f32 v[178:179], v[140:141], v[212:213]
	v_pk_mul_f32 v[192:193], v[138:139], v[210:211]
	v_pk_fma_f32 v[178:179], v[124:125], v[144:145], v[178:179]
	v_pk_fma_f32 v[192:193], v[122:123], v[142:143], v[192:193]
	v_pk_fma_f32 v[210:211], v[132:133], v[216:217], v[178:179]
	v_pk_fma_f32 v[178:179], v[130:131], v[214:215], v[192:193]
	s_nop 0
	v_mul_f32_e32 v192, 0xbfb8aa3b, v178
	v_mul_f32_e32 v193, 0xbfb8aa3b, v179
	v_exp_f32_e32 v192, v192
	v_exp_f32_e32 v193, v193
	v_add_f32_e32 v192, 1.0, v192
	v_add_f32_e32 v193, 1.0, v193
	v_rcp_f32_e32 v192, v192
	v_rcp_f32_e32 v193, v193
	s_nop 0
	v_pk_mul_f32 v[178:179], v[178:179], v[192:193]
	s_nop 0
	v_pk_mul_f32 v[174:175], v[174:175], v[178:179]
	s_nop 0
	v_cvt_pk_bf16_f32 v178, v174, v175
	v_mul_f32_e32 v174, 0xbfb8aa3b, v210
	v_mul_f32_e32 v175, 0xbfb8aa3b, v211
	v_exp_f32_e32 v174, v174
	v_exp_f32_e32 v175, v175
	v_add_f32_e32 v174, 1.0, v174
	v_add_f32_e32 v175, 1.0, v175
	v_rcp_f32_e32 v174, v174
	v_rcp_f32_e32 v175, v175
	s_nop 0
	v_pk_mul_f32 v[174:175], v[210:211], v[174:175]
	s_nop 0
	v_pk_mul_f32 v[174:175], v[194:195], v[174:175]
	s_nop 0
	v_cvt_pk_bf16_f32 v179, v174, v175
	v_mov_b64_e32 v[174:175], s[20:21]
	v_mad_i64_i32 v[174:175], s[46:47], v184, s33, v[174:175]
	v_lshl_add_u64 v[174:175], v[170:171], 1, v[174:175]
	global_store_dwordx2 v[174:175], v[178:179], off
	s_and_saveexec_b64 s[78:79], s[4:5]
	s_cbranch_execz .LBB0_622
	global_store_dwordx4 v[176:177], v[126:129], off
	s_nop 1
	v_add_co_u32_e32 v126, vcc, 0x5000, v176
	s_nop 1
	v_addc_co_u32_e32 v127, vcc, 0, v177, vcc
	global_store_dwordx4 v[126:127], v[122:125], off offset:2048

; __device__ __forceinline__ int otid(int wv) { int t = (wv << 6) | (int)__builtin_amdgcn_mbcnt_hi(~0u, __builtin_amdgcn_mbcnt_lo(~0u, 0u)); asm volatile("" : "+v"(t)); return t; }
; __device__ __forceinline__ void grid_bar(unsigned* ctr, unsigned& target, int G, int wv) {
;     asm volatile("s_waitcnt vmcnt(0) lgkmcnt(0)" ::: "memory");
;     __syncthreads();
;     target = (unsigned)__builtin_amdgcn_readfirstlane((int)(target + (unsigned)G));
;     if (otid(wv) == 0) {
;         __builtin_amdgcn_fence(__ATOMIC_RELEASE, "agent");
;         asm volatile("s_waitcnt vmcnt(0)" ::: "memory");
;         __hip_atomic_fetch_add(ctr, 1u, __ATOMIC_RELAXED, __HIP_MEMORY_SCOPE_AGENT);
;         while (__hip_atomic_load(ctr, __ATOMIC_RELAXED, __HIP_MEMORY_SCOPE_AGENT) < target) __builtin_amdgcn_s_sleep(1);
;         __builtin_amdgcn_fence(__ATOMIC_ACQUIRE, "agent");
;         asm volatile("s_waitcnt vmcnt(0)" ::: "memory");
;     }
;     __syncthreads();
; }
.LBB0_631:
	s_setprio 0
	s_waitcnt vmcnt(0) lgkmcnt(0)
	v_mov_b32_e32 v1, v236
	s_waitcnt lgkmcnt(0)
	s_barrier
	s_add_i32 s10, s20, s33
	s_nop 0
	v_cmp_eq_u32_e32 vcc, 0, v1
	s_and_saveexec_b64 s[0:1], vcc
	v_readlane_b32 s68, v255, 33
	v_readlane_b32 s72, v255, 35
	s_mov_b64 s[52:53], 0x41000
	v_readlane_b32 s69, v255, 34
	v_readlane_b32 s73, v255, 36
	s_cbranch_execz .LBB0_637
	s_mov_b64 s[2:3], exec
	buffer_wbl2 sc1
	s_waitcnt vmcnt(0)
	s_waitcnt vmcnt(0)
	v_mbcnt_lo_u32_b32 v1, s2, 0
	v_mbcnt_hi_u32_b32 v1, s3, v1
	v_cmp_eq_u32_e32 vcc, 0, v1
	s_and_saveexec_b64 s[4:5], vcc
	s_cbranch_execz .LBB0_634
	s_bcnt1_i32_b64 s2, s[2:3]
	v_mov_b32_e32 v1, s2
	v_readlane_b32 s2, v254, 30
	v_readlane_b32 s3, v254, 31
	s_nop 4
	global_atomic_add v0, v1, s[2:3]

; __device__ __forceinline__ int otid(int wv) { int t = (wv << 6) | (int)__builtin_amdgcn_mbcnt_hi(~0u, __builtin_amdgcn_mbcnt_lo(~0u, 0u)); asm volatile("" : "+v"(t)); return t; }
; __device__ __forceinline__ void grid_bar(unsigned* ctr, unsigned& target, int G, int wv) {
;     asm volatile("s_waitcnt vmcnt(0) lgkmcnt(0)" ::: "memory");
;     __syncthreads();
;     target = (unsigned)__builtin_amdgcn_readfirstlane((int)(target + (unsigned)G));
;     if (otid(wv) == 0) {
;         __builtin_amdgcn_fence(__ATOMIC_RELEASE, "agent");
;         asm volatile("s_waitcnt vmcnt(0)" ::: "memory");
;         __hip_atomic_fetch_add(ctr, 1u, __ATOMIC_RELAXED, __HIP_MEMORY_SCOPE_AGENT);
;         while (__hip_atomic_load(ctr, __ATOMIC_RELAXED, __HIP_MEMORY_SCOPE_AGENT) < target) __builtin_amdgcn_s_sleep(1);
;         __builtin_amdgcn_fence(__ATOMIC_ACQUIRE, "agent");
;         asm volatile("s_waitcnt vmcnt(0)" ::: "memory");
;     }
;     __syncthreads();
; }
.LBB0_646:
	s_or_b64 exec, exec, s[0:1]
	s_setprio 0
	s_waitcnt vmcnt(0) lgkmcnt(0)
	v_mov_b32_e32 v1, v236
	s_waitcnt lgkmcnt(0)
	s_barrier
	s_add_i32 s10, s10, s33
	s_nop 0
	v_cmp_eq_u32_e32 vcc, 0, v1
	s_and_saveexec_b64 s[0:1], vcc
	s_cbranch_execz .LBB0_652
	s_mov_b64 s[2:3], exec
	buffer_wbl2 sc1
	s_waitcnt vmcnt(0)
	s_waitcnt vmcnt(0)
	v_mbcnt_lo_u32_b32 v1, s2, 0
	v_mbcnt_hi_u32_b32 v1, s3, v1
	v_cmp_eq_u32_e32 vcc, 0, v1
	s_and_saveexec_b64 s[4:5], vcc
	s_cbranch_execz .LBB0_649
	s_bcnt1_i32_b64 s2, s[2:3]
	v_mov_b32_e32 v1, s2
	v_readlane_b32 s2, v254, 30
	v_readlane_b32 s3, v254, 31
	s_nop 4
	global_atomic_add v0, v1, s[2:3]

; __device__ __forceinline__ int otid(int wv) { int t = (wv << 6) | (int)__builtin_amdgcn_mbcnt_hi(~0u, __builtin_amdgcn_mbcnt_lo(~0u, 0u)); asm volatile("" : "+v"(t)); return t; }
;     __device__ bool next(int i, Unit& u) const { return map((long)i * G + c, u); }
;     __device__ bool next(int i, Unit& u) const { const int t = i / 3, b = i - 3 * t; if (!so.map((long)t * so.G + so.c, u)) return false; u.pn += 8 * b; return true; }
; #define PG8_BAR __builtin_amdgcn_s_barrier()
; template <class Epi, class Sched, bool AREMAP>
; __device__ __forceinline__ void gemm_phase(LAS unsigned char* lds, const Gemm g, const Sched& S, const Epi& E, int wv) {
;     const int tid = otid(wv), wid = __builtin_amdgcn_readfirstlane(tid >> 6), lane = tid & 63, wr = wid >> 2, wc = wid & 3, fr = lane & 15, fq = lane >> 4;
;     const int K = g.K, nt = K / BK;
;     unsigned voffA[2], voffB[2];
; #pragma unroll
;     for (int i = 0; i < 2; ++i) { int R, C; stage_rc(tid * 16 + i * 8192, R, C); const int Rb = Epi::PERM ? ((R & ~31) + perm32(R & 31)) : R;
;         const int Ra = AREMAP ? ((R >> 6) * 128 + (R & 63)) : R;
;         voffA[i] = (unsigned)(Ra * g.lda + C) * 2u; voffB[i] = (unsigned)(Rb * g.ldb + C) * 2u; }
;     const size_t kstep = (size_t)(BK * 2);
;     const size_t hstepA = (size_t)(AREMAP ? 64 : HALF) * g.lda * 2, hstepB = (size_t)HALF * g.ldb * 2;
;     const size_t tstepA = (size_t)BM * g.lda * 2, tstepB = (size_t)BM * g.ldb * 2;
;     const unsigned ldsw = (unsigned)wid * 1024u;
;     const int aoff = lds_byte(wr * 64 + fr, fq * 8), boff = lds_byte(wc * 32 + fr, fq * 8);
;     ...
;     Unit cur, nxt; int ui = 0;
;     if (!S.next(0, cur)) return;
;     f32x4 acc[2][2][4][2];
; #pragma unroll
;     for (int a = 0; a < 2; ++a)
; #pragma unroll
;         for (int b = 0; b < 2; ++b)
; #pragma unroll
;             for (int m = 0; m < 4; ++m)
; #pragma unroll
;                 for (int n = 0; n < 2; ++n) acc[a][b][m][n] = (f32x4){0.f, 0.f, 0.f, 0.f};
;     bf16x8 At[4][2], B0[2][2], B1[2][2];
;     ...
;     const char* cA = PG8_UA(cur); const char* cB = PG8_UB(cur);
;     PG8_STAGE(PG8_SB(0, 0), cB, voffB); PG8_STAGE(PG8_SA(0, 0), cA, voffA); PG8_STAGE(PG8_SB(0, 1), cB + hstepB, voffB); PG8_STAGE(PG8_SA(0, 1), cA + hstepA, voffA);
;     if (wr == 1) PG8_BAR;
.LBB0_658:
	s_andn2_b64 vcc, exec, s[2:3]
	s_cbranch_vccnz .LBB0_713
	v_bfe_i32 v3, v13, 27, 1
	v_lshlrev_b32_e32 v2, 4, v13
	v_lshrrev_b32_e32 v3, 22, v3
	v_add_u32_e32 v3, v2, v3
	v_and_b32_e32 v3, 0xfffffc00, v3
	v_ashrrev_i32_e32 v1, 31, v13
	v_sub_u32_e32 v3, v2, v3
	v_lshrrev_b32_e32 v1, 26, v1
	v_lshrrev_b32_e32 v4, 4, v3
	v_add_u32_e32 v1, v13, v1
	v_bitop3_b32 v4, v4, v3, 32 bitop3:0x6c
	v_ashrrev_i32_e32 v3, 31, v3
	v_ashrrev_i32_e32 v1, 6, v1
	v_lshrrev_b32_e32 v3, 26, v3
	v_lshlrev_b32_e32 v5, 3, v1
	v_add_u32_e32 v3, v4, v3
	s_add_u32 s14, s0, 0x10e00000
	v_and_b32_e32 v5, 0x7ffff0, v5
	v_ashrrev_i32_e32 v11, 6, v3
	s_addc_u32 s15, s1, 0
	v_add_u32_e32 v3, v11, v5
	v_lshlrev_b32_e32 v5, 5, v1
	s_add_u32 s30, s0, 0x7800000
	v_and_b32_e32 v10, 32, v5
	v_mul_i32_i24_e32 v5, 64, v11
	s_addc_u32 s31, s1, 0
	v_sub_u32_e32 v4, v4, v5
	s_movk_i32 s1, 0x1600
	v_ashrrev_i16_sdwa v4, v240, sext(v4) dst_sel:DWORD dst_unused:UNUSED_PAD src0_sel:DWORD src1_sel:BYTE_0
	v_mul_lo_u32 v3, v3, s1
	v_bfe_i32 v12, v4, 0, 16
	v_or_b32_e32 v3, v3, v10
	v_add_u32_e32 v2, 0x2000, v2
	v_add_lshl_u32 v196, v3, v12, 1
	v_ashrrev_i32_e32 v3, 31, v2
	v_lshrrev_b32_e32 v3, 22, v3
	v_add_u32_e32 v3, v2, v3
	v_ashrrev_i32_e32 v14, 10, v3
	v_mul_i32_i24_e32 v3, 0x400, v14
	v_sub_u32_e32 v2, v2, v3
	v_lshrrev_b32_e32 v3, 4, v2
	v_bitop3_b32 v2, v3, v2, 32 bitop3:0x6c
	v_ashrrev_i32_e32 v4, 31, v2
	v_lshrrev_b32_e32 v4, 26, v4
	v_add_u32_e32 v4, v2, v4
	v_lshlrev_b32_e32 v3, 3, v14
	v_ashrrev_i32_e32 v15, 6, v4
	v_and_b32_e32 v4, 0xc0, v4
	v_and_b32_e32 v3, 0x7ffff0, v3
	v_sub_u32_e32 v2, v2, v4
	v_add_u32_e32 v3, v15, v3
	v_ashrrev_i16_sdwa v2, v240, sext(v2) dst_sel:DWORD dst_unused:UNUSED_PAD src0_sel:DWORD src1_sel:BYTE_0
	v_bfe_i32 v17, v2, 0, 16
	v_mul_lo_u32 v2, v3, s1
	s_ashr_i32 s1, s13, 6
	s_ashr_i32 s0, s13, 8
	s_lshl_b32 s34, s1, 10
	s_mul_i32 s5, s63, 0x2c0000
	s_mul_hi_i32 s4, s63, 0x2c0000
	s_add_u32 s26, s30, s5
	v_lshlrev_b32_e32 v5, 5, v14
	s_addc_u32 s27, s31, s4
	s_add_i32 s35, s34, 0
	v_and_b32_e32 v16, 32, v5
	s_add_i32 m0, s35, 0x10000
	v_or_b32_e32 v2, v2, v16
	s_mul_i32 s3, s62, 0x2c0000
	global_load_lds_dwordx4 v196, s[26:27]
	s_add_i32 m0, s35, 0x12000
	v_add_lshl_u32 v198, v2, v17, 1
	s_mul_hi_i32 s2, s62, 0x2c0000
	s_add_u32 s24, s14, s3
	global_load_lds_dwordx4 v198, s[26:27]
	s_addc_u32 s25, s15, s2
	s_mov_b32 m0, s35
	s_add_i32 s36, s35, 0x2000
	global_load_lds_dwordx4 v196, s[24:25]
	s_mov_b32 m0, s36
	s_add_u32 s2, s26, 0x160000
	global_load_lds_dwordx4 v198, s[24:25]
	s_addc_u32 s3, s27, 0
	s_add_i32 m0, s35, 0x14000
	v_mov_b32_e32 v197, v0
	global_load_lds_dwordx4 v196, s[2:3]
	s_add_i32 m0, s35, 0x16000
	v_mov_b32_e32 v199, v0
	global_load_lds_dwordx4 v198, s[2:3]
	s_add_u32 s2, s24, 0x160000
	s_addc_u32 s3, s25, 0
	s_add_i32 s37, s35, 0x4000
	s_mov_b32 m0, s37
	s_add_i32 s41, s35, 0x6000
	global_load_lds_dwordx4 v196, s[2:3]
	s_mov_b32 m0, s41
	v_lshl_add_u64 v[8:9], s[26:27], 0, v[196:197]
	global_load_lds_dwordx4 v198, s[2:3]
	v_lshl_add_u64 v[6:7], s[26:27], 0, v[198:199]
	v_lshl_add_u64 v[4:5], s[24:25], 0, v[196:197]
	s_cmp_lg_u32 s0, 1
	v_lshl_add_u64 v[2:3], s[24:25], 0, v[198:199]
	s_cbranch_scc1 .LBB0_661
	s_barrier
	s_setprio 1

; #define PG8_STAGE(bufoff, gbase, voff) do { _Pragma("unroll") for (int _i = 0; _i < 2; ++_i) \
;         __builtin_amdgcn_global_load_lds((const unsigned*)((const char*)(gbase) + (voff)[_i]), (LAS unsigned*)(lds + (bufoff) + ldsw + _i * 8192), 16, 0, 0); } while (0)
; #define PG8_LDA(dst, b, h) do { _Pragma("unroll") for (int m = 0; m < 4; ++m) _Pragma("unroll") for (int k = 0; k < 2; ++k) dst[m][k] = *(const LAS bf16x8*)(lds + PG8_SA(b, h) + aoff + m * 2048 + k * 1024); } while (0)
; #define PG8_LDB(dst, b, h) do { _Pragma("unroll") for (int n = 0; n < 2; ++n) _Pragma("unroll") for (int k = 0; k < 2; ++k) dst[n][k] = *(const LAS bf16x8*)(lds + PG8_SB(b, h) + boff + n * 2048 + k * 1024); } while (0)
; #define PG8_MMA(ai, bj, At, Bt) do { __builtin_amdgcn_s_setprio(1); _Pragma("unroll") for (int m = 0; m < 4; ++m) _Pragma("unroll") for (int n = 0; n < 2; ++n) _Pragma("unroll") for (int k = 0; k < 2; ++k) \
;         acc[ai][bj][m][n] = __builtin_amdgcn_mfma_f32_16x16x32_bf16(Bt[n][k], At[m][k], acc[ai][bj][m][n], 0, 0, 0); __builtin_amdgcn_s_setprio(0); } while (0)
; #define PG8_WAIT_L(n) asm volatile("s_waitcnt lgkmcnt(" #n ")" ::: "memory")
; #define PG8_BAR __builtin_amdgcn_s_barrier()
; #define PG8_SCHED __builtin_amdgcn_sched_barrier(0)
; template <class Epi, class Sched, bool AREMAP>
; __device__ __forceinline__ void gemm_phase(LAS unsigned char* lds, const Gemm g, const Sched& S, const Epi& E, int wv) {
;     ...
;             PG8_LDB(B0, 0, 0); PG8_SCHED; PG8_LDA(At, 0, 0); PG8_STAGE(PG8_SA(1, 1), a1 + hstepA, voffA);
;             PG8_WAIT_L(8); PG8_BAR; PG8_WAIT_L(0); PG8_MMA(0, 0, At, B0); PG8_BAR; PG8_SCHED;
;             PG8_LDB(B1, 0, 1); PG8_STAGE(PG8_SB(0, 0), b2, voffB);
;             PG8_BAR; PG8_WAIT_L(0); PG8_MMA(0, 1, At, B1); PG8_BAR;
;             PG8_LDA(At, 0, 1); PG8_STAGE(PG8_SA(0, 0), a2, voffA);
;             PG8_BAR; PG8_WAIT_L(0); PG8_MMA(1, 0, At, B0); PG8_BAR; PG8_SCHED;
.LBB0_674:
	s_add_u32 s2, s24, 0x100
	s_addc_u32 s3, s25, 0
	s_add_i32 s33, 0, 0x10000
	v_add_u32_e32 v1, s33, v250
	ds_read_b128 v[130:133], v1
	ds_read_b128 v[134:137], v1 offset:1024
	ds_read_b128 v[138:141], v1 offset:2048
	ds_read_b128 v[142:145], v1 offset:3072
	s_cmpk_eq_i32 s67, 0x54
	s_cselect_b32 s29, s23, s3
	s_cselect_b32 s28, s22, s2
	s_cselect_b32 s27, s5, s66
	s_cselect_b32 s26, s4, s65
	v_lshl_add_u64 v[178:179], s[24:25], 0, v[202:203]
	s_add_i32 m0, s35, 0xc000
	ds_read_b128 v[146:149], v252
	ds_read_b128 v[150:153], v252 offset:1024
	ds_read_b128 v[154:157], v252 offset:2048
	ds_read_b128 v[158:161], v252 offset:3072
	ds_read_b128 v[162:165], v252 offset:4096
	ds_read_b128 v[166:169], v252 offset:5120
	ds_read_b128 v[170:173], v252 offset:6144
	ds_read_b128 v[174:177], v252 offset:7168
	global_load_lds_dwordx4 v[178:179], off
	v_lshl_add_u64 v[178:179], s[24:25], 0, v[200:201]
	s_add_i32 m0, s35, 0xe000
	s_nop 0
	global_load_lds_dwordx4 v[178:179], off
	s_waitcnt lgkmcnt(8)
	s_barrier
	s_waitcnt lgkmcnt(0)
	s_waitcnt lgkmcnt(0)
	v_mfma_f32_16x16x32_bf16 v[126:129], v[130:133], v[146:149], v[126:129]
	v_mfma_f32_16x16x32_bf16 v[110:113], v[138:141], v[146:149], v[110:113]
	v_mfma_f32_16x16x32_bf16 v[122:125], v[130:133], v[154:157], v[122:125]
	v_mfma_f32_16x16x32_bf16 v[106:109], v[138:141], v[154:157], v[106:109]
	v_mfma_f32_16x16x32_bf16 v[118:121], v[130:133], v[162:165], v[118:121]
	v_mfma_f32_16x16x32_bf16 v[102:105], v[138:141], v[162:165], v[102:105]
	v_mfma_f32_16x16x32_bf16 v[114:117], v[130:133], v[170:173], v[114:117]
	v_mfma_f32_16x16x32_bf16 v[98:101], v[138:141], v[170:173], v[98:101]
	v_mfma_f32_16x16x32_bf16 v[126:129], v[134:137], v[150:153], v[126:129]
	v_mfma_f32_16x16x32_bf16 v[110:113], v[142:145], v[150:153], v[110:113]
	v_mfma_f32_16x16x32_bf16 v[122:125], v[134:137], v[158:161], v[122:125]
	v_mfma_f32_16x16x32_bf16 v[106:109], v[142:145], v[158:161], v[106:109]
	v_mfma_f32_16x16x32_bf16 v[118:121], v[134:137], v[166:169], v[118:121]
	v_mfma_f32_16x16x32_bf16 v[102:105], v[142:145], v[166:169], v[102:105]
	v_mfma_f32_16x16x32_bf16 v[114:117], v[134:137], v[174:177], v[114:117]
	v_mfma_f32_16x16x32_bf16 v[98:101], v[142:145], v[174:177], v[98:101]
	s_barrier
	s_add_i32 s38, 0, 0x14000
	s_add_i32 s24, s33, s34
	v_add_u32_e32 v1, s38, v250
	v_lshl_add_u64 v[186:187], s[26:27], 0, v[196:197]
	s_mov_b32 m0, s24
	ds_read_b128 v[178:181], v1
	ds_read_b128 v[182:185], v1 offset:1024
	ds_read_b128 v[192:195], v1 offset:2048
	ds_read_b128 v[204:207], v1 offset:3072
	global_load_lds_dwordx4 v[186:187], off
	v_lshl_add_u64 v[208:209], s[26:27], 0, v[198:199]
	s_add_i32 m0, s24, 0x2000
	s_nop 0
	global_load_lds_dwordx4 v[208:209], off
	s_barrier
	s_waitcnt lgkmcnt(0)
	s_waitcnt lgkmcnt(0)
	v_mfma_f32_16x16x32_bf16 v[94:97], v[178:181], v[146:149], v[94:97]
	v_mfma_f32_16x16x32_bf16 v[78:81], v[192:195], v[146:149], v[78:81]
	v_mfma_f32_16x16x32_bf16 v[90:93], v[178:181], v[154:157], v[90:93]
	v_mfma_f32_16x16x32_bf16 v[74:77], v[192:195], v[154:157], v[74:77]
	v_mfma_f32_16x16x32_bf16 v[86:89], v[178:181], v[162:165], v[86:89]
	v_mfma_f32_16x16x32_bf16 v[70:73], v[192:195], v[162:165], v[70:73]
	v_mfma_f32_16x16x32_bf16 v[82:85], v[178:181], v[170:173], v[82:85]
	v_mfma_f32_16x16x32_bf16 v[66:69], v[192:195], v[170:173], v[66:69]
	v_mfma_f32_16x16x32_bf16 v[94:97], v[182:185], v[150:153], v[94:97]
	v_mfma_f32_16x16x32_bf16 v[78:81], v[204:207], v[150:153], v[78:81]
	v_mfma_f32_16x16x32_bf16 v[90:93], v[182:185], v[158:161], v[90:93]
	v_mfma_f32_16x16x32_bf16 v[74:77], v[204:207], v[158:161], v[74:77]
	v_mfma_f32_16x16x32_bf16 v[86:89], v[182:185], v[166:169], v[86:89]
	v_mfma_f32_16x16x32_bf16 v[70:73], v[204:207], v[166:169], v[70:73]
	v_mfma_f32_16x16x32_bf16 v[82:85], v[182:185], v[174:177], v[82:85]
	v_mfma_f32_16x16x32_bf16 v[66:69], v[204:207], v[174:177], v[66:69]
	s_mov_b32 m0, s35
	v_lshl_add_u64 v[210:211], s[28:29], 0, v[196:197]
	s_barrier
	ds_read_b128 v[146:149], v252 offset:16384
	ds_read_b128 v[150:153], v252 offset:17408
	ds_read_b128 v[154:157], v252 offset:18432
	ds_read_b128 v[158:161], v252 offset:19456
	ds_read_b128 v[162:165], v252 offset:20480
	ds_read_b128 v[166:169], v252 offset:21504
	ds_read_b128 v[170:173], v252 offset:22528
	ds_read_b128 v[174:177], v252 offset:23552
	global_load_lds_dwordx4 v[210:211], off
	v_lshl_add_u64 v[212:213], s[28:29], 0, v[198:199]
	s_mov_b32 m0, s36
	s_nop 0
	global_load_lds_dwordx4 v[212:213], off
	s_barrier
	s_waitcnt lgkmcnt(0)
	s_waitcnt lgkmcnt(0)
	v_mfma_f32_16x16x32_bf16 v[62:65], v[130:133], v[146:149], v[62:65]
	v_mfma_f32_16x16x32_bf16 v[46:49], v[138:141], v[146:149], v[46:49]
	v_mfma_f32_16x16x32_bf16 v[58:61], v[130:133], v[154:157], v[58:61]
	v_mfma_f32_16x16x32_bf16 v[42:45], v[138:141], v[154:157], v[42:45]
	v_mfma_f32_16x16x32_bf16 v[54:57], v[130:133], v[162:165], v[54:57]
	v_mfma_f32_16x16x32_bf16 v[38:41], v[138:141], v[162:165], v[38:41]
	v_mfma_f32_16x16x32_bf16 v[50:53], v[130:133], v[170:173], v[50:53]
	v_mfma_f32_16x16x32_bf16 v[34:37], v[138:141], v[170:173], v[34:37]
	v_mfma_f32_16x16x32_bf16 v[62:65], v[134:137], v[150:153], v[62:65]
	v_mfma_f32_16x16x32_bf16 v[46:49], v[142:145], v[150:153], v[46:49]
	v_mfma_f32_16x16x32_bf16 v[58:61], v[134:137], v[158:161], v[58:61]
	v_mfma_f32_16x16x32_bf16 v[42:45], v[142:145], v[158:161], v[42:45]
	v_mfma_f32_16x16x32_bf16 v[54:57], v[134:137], v[166:169], v[54:57]
	v_mfma_f32_16x16x32_bf16 v[38:41], v[142:145], v[166:169], v[38:41]
	v_mfma_f32_16x16x32_bf16 v[50:53], v[134:137], v[174:177], v[50:53]
	v_mfma_f32_16x16x32_bf16 v[34:37], v[142:145], v[174:177], v[34:37]
	s_barrier
; #define PG8_STAGE(bufoff, gbase, voff) do { _Pragma("unroll") for (int _i = 0; _i < 2; ++_i) \
;         __builtin_amdgcn_global_load_lds((const unsigned*)((const char*)(gbase) + (voff)[_i]), (LAS unsigned*)(lds + (bufoff) + ldsw + _i * 8192), 16, 0, 0); } while (0)
; #define PG8_LDA(dst, b, h) do { _Pragma("unroll") for (int m = 0; m < 4; ++m) _Pragma("unroll") for (int k = 0; k < 2; ++k) dst[m][k] = *(const LAS bf16x8*)(lds + PG8_SA(b, h) + aoff + m * 2048 + k * 1024); } while (0)
; #define PG8_LDB(dst, b, h) do { _Pragma("unroll") for (int n = 0; n < 2; ++n) _Pragma("unroll") for (int k = 0; k < 2; ++k) dst[n][k] = *(const LAS bf16x8*)(lds + PG8_SB(b, h) + boff + n * 2048 + k * 1024); } while (0)
; #define PG8_MMA(ai, bj, At, Bt) do { __builtin_amdgcn_s_setprio(1); _Pragma("unroll") for (int m = 0; m < 4; ++m) _Pragma("unroll") for (int n = 0; n < 2; ++n) _Pragma("unroll") for (int k = 0; k < 2; ++k) \
;         acc[ai][bj][m][n] = __builtin_amdgcn_mfma_f32_16x16x32_bf16(Bt[n][k], At[m][k], acc[ai][bj][m][n], 0, 0, 0); __builtin_amdgcn_s_setprio(0); } while (0)
; #define PG8_WAIT_V(n) asm volatile("s_waitcnt vmcnt(" #n ")" ::: "memory")
; #define PG8_WAIT_L(n) asm volatile("s_waitcnt lgkmcnt(" #n ")" ::: "memory")
; #define PG8_BAR __builtin_amdgcn_s_barrier()
; #define PG8_SCHED __builtin_amdgcn_sched_barrier(0)
; template <class Epi, class Sched, bool AREMAP>
; __device__ __forceinline__ void gemm_phase(LAS unsigned char* lds, const Gemm g, const Sched& S, const Epi& E, int wv) {
;     ...
;             PG8_STAGE(PG8_SB(0, 1), b2 + hstepB, voffB);
;             PG8_WAIT_V(6); PG8_BAR; PG8_MMA(1, 1, At, B1); PG8_BAR;
;             PG8_LDB(B0, 1, 0); PG8_SCHED; PG8_LDA(At, 1, 0); PG8_STAGE(PG8_SA(0, 1), a2 + hstepA, voffA);
;             PG8_WAIT_L(8); PG8_BAR; PG8_WAIT_L(0); PG8_MMA(0, 0, At, B0); PG8_BAR; PG8_SCHED;
;             PG8_LDB(B1, 1, 1); PG8_STAGE(PG8_SB(1, 0), b3, voffB);
	s_add_u32 s24, s26, 0x160000
	s_addc_u32 s25, s27, 0
	s_add_i32 s33, s38, s34
	v_lshl_add_u64 v[130:131], s[24:25], 0, v[196:197]
	s_mov_b32 m0, s33
	s_nop 0
	global_load_lds_dwordx4 v[130:131], off
	v_lshl_add_u64 v[130:131], s[24:25], 0, v[198:199]
	s_add_i32 m0, s33, 0x2000
	s_nop 0
	global_load_lds_dwordx4 v[130:131], off
	s_waitcnt vmcnt(6)
	s_barrier
	v_mfma_f32_16x16x32_bf16 v[30:33], v[178:181], v[146:149], v[30:33]
	v_mfma_f32_16x16x32_bf16 v[14:17], v[192:195], v[146:149], v[14:17]
	v_mfma_f32_16x16x32_bf16 v[26:29], v[178:181], v[154:157], v[26:29]
	v_mfma_f32_16x16x32_bf16 v[10:13], v[192:195], v[154:157], v[10:13]
	v_mfma_f32_16x16x32_bf16 v[22:25], v[178:181], v[162:165], v[22:25]
	v_mfma_f32_16x16x32_bf16 v[6:9], v[192:195], v[162:165], v[6:9]
	v_mfma_f32_16x16x32_bf16 v[18:21], v[178:181], v[170:173], v[18:21]
	v_mfma_f32_16x16x32_bf16 v[2:5], v[192:195], v[170:173], v[2:5]
	v_mfma_f32_16x16x32_bf16 v[30:33], v[182:185], v[150:153], v[30:33]
	v_mfma_f32_16x16x32_bf16 v[14:17], v[204:207], v[150:153], v[14:17]
	v_mfma_f32_16x16x32_bf16 v[26:29], v[182:185], v[158:161], v[26:29]
	v_mfma_f32_16x16x32_bf16 v[10:13], v[204:207], v[158:161], v[10:13]
	v_mfma_f32_16x16x32_bf16 v[22:25], v[182:185], v[166:169], v[22:25]
	v_mfma_f32_16x16x32_bf16 v[6:9], v[204:207], v[166:169], v[6:9]
	v_mfma_f32_16x16x32_bf16 v[18:21], v[182:185], v[174:177], v[18:21]
	v_mfma_f32_16x16x32_bf16 v[2:5], v[204:207], v[174:177], v[2:5]
	s_add_i32 s33, 0, 0x18000
	v_add_u32_e32 v1, s33, v250
	s_barrier
	ds_read_b128 v[130:133], v1
	ds_read_b128 v[134:137], v1 offset:1024
	ds_read_b128 v[138:141], v1 offset:2048
	ds_read_b128 v[142:145], v1 offset:3072
	s_add_u32 s24, s28, 0x160000
	s_addc_u32 s25, s29, 0
	s_mov_b32 m0, s37
	v_lshl_add_u64 v[178:179], s[24:25], 0, v[196:197]
	ds_read_b128 v[146:149], v252 offset:32768
	ds_read_b128 v[150:153], v252 offset:33792
	ds_read_b128 v[154:157], v252 offset:34816
	ds_read_b128 v[158:161], v252 offset:35840
	ds_read_b128 v[162:165], v252 offset:36864
	ds_read_b128 v[166:169], v252 offset:37888
	ds_read_b128 v[170:173], v252 offset:38912
	ds_read_b128 v[174:177], v252 offset:39936
	global_load_lds_dwordx4 v[178:179], off
	v_lshl_add_u64 v[178:179], s[24:25], 0, v[198:199]
	s_mov_b32 m0, s41
	s_nop 0
	global_load_lds_dwordx4 v[178:179], off
	s_waitcnt lgkmcnt(8)
	s_barrier
	s_waitcnt lgkmcnt(0)
	s_waitcnt lgkmcnt(0)
	v_mfma_f32_16x16x32_bf16 v[126:129], v[130:133], v[146:149], v[126:129]
	v_mfma_f32_16x16x32_bf16 v[110:113], v[138:141], v[146:149], v[110:113]
	v_mfma_f32_16x16x32_bf16 v[122:125], v[130:133], v[154:157], v[122:125]
	v_mfma_f32_16x16x32_bf16 v[106:109], v[138:141], v[154:157], v[106:109]
	v_mfma_f32_16x16x32_bf16 v[118:121], v[130:133], v[162:165], v[118:121]
	v_mfma_f32_16x16x32_bf16 v[102:105], v[138:141], v[162:165], v[102:105]
	v_mfma_f32_16x16x32_bf16 v[114:117], v[130:133], v[170:173], v[114:117]
	v_mfma_f32_16x16x32_bf16 v[98:101], v[138:141], v[170:173], v[98:101]
	v_mfma_f32_16x16x32_bf16 v[126:129], v[134:137], v[150:153], v[126:129]
	v_mfma_f32_16x16x32_bf16 v[110:113], v[142:145], v[150:153], v[110:113]
	v_mfma_f32_16x16x32_bf16 v[122:125], v[134:137], v[158:161], v[122:125]
	v_mfma_f32_16x16x32_bf16 v[106:109], v[142:145], v[158:161], v[106:109]
	v_mfma_f32_16x16x32_bf16 v[118:121], v[134:137], v[166:169], v[118:121]
	v_mfma_f32_16x16x32_bf16 v[102:105], v[142:145], v[166:169], v[102:105]
	v_mfma_f32_16x16x32_bf16 v[114:117], v[134:137], v[174:177], v[114:117]
	v_mfma_f32_16x16x32_bf16 v[98:101], v[142:145], v[174:177], v[98:101]
	s_barrier
	s_add_i32 s28, 0, 0x1c000
	s_add_i32 s24, s33, s34
	v_add_u32_e32 v1, s28, v250
	v_lshl_add_u64 v[186:187], v[186:187], 0, s[86:87]
	s_mov_b32 m0, s24
	ds_read_b128 v[178:181], v1
	ds_read_b128 v[182:185], v1 offset:1024
	ds_read_b128 v[192:195], v1 offset:2048
	ds_read_b128 v[204:207], v1 offset:3072
	global_load_lds_dwordx4 v[186:187], off
	v_lshl_add_u64 v[186:187], v[208:209], 0, s[86:87]
	s_add_i32 m0, s24, 0x2000
	s_nop 0
	global_load_lds_dwordx4 v[186:187], off
	s_barrier
; #define PG8_STAGE(bufoff, gbase, voff) do { _Pragma("unroll") for (int _i = 0; _i < 2; ++_i) \
;         __builtin_amdgcn_global_load_lds((const unsigned*)((const char*)(gbase) + (voff)[_i]), (LAS unsigned*)(lds + (bufoff) + ldsw + _i * 8192), 16, 0, 0); } while (0)
; #define PG8_LDA(dst, b, h) do { _Pragma("unroll") for (int m = 0; m < 4; ++m) _Pragma("unroll") for (int k = 0; k < 2; ++k) dst[m][k] = *(const LAS bf16x8*)(lds + PG8_SA(b, h) + aoff + m * 2048 + k * 1024); } while (0)
; #define PG8_MMA(ai, bj, At, Bt) do { __builtin_amdgcn_s_setprio(1); _Pragma("unroll") for (int m = 0; m < 4; ++m) _Pragma("unroll") for (int n = 0; n < 2; ++n) _Pragma("unroll") for (int k = 0; k < 2; ++k) \
;         acc[ai][bj][m][n] = __builtin_amdgcn_mfma_f32_16x16x32_bf16(Bt[n][k], At[m][k], acc[ai][bj][m][n], 0, 0, 0); __builtin_amdgcn_s_setprio(0); } while (0)
; #define PG8_WAIT_V(n) asm volatile("s_waitcnt vmcnt(" #n ")" ::: "memory")
; #define PG8_WAIT_L(n) asm volatile("s_waitcnt lgkmcnt(" #n ")" ::: "memory")
; #define PG8_BAR __builtin_amdgcn_s_barrier()
; #define PG8_SCHED __builtin_amdgcn_sched_barrier(0)
; template <class Epi, class Sched, bool AREMAP>
; __device__ __forceinline__ void gemm_phase(LAS unsigned char* lds, const Gemm g, const Sched& S, const Epi& E, int wv) {
;     ...
;             PG8_BAR; PG8_WAIT_L(0); PG8_MMA(0, 1, At, B1); PG8_BAR;
;             PG8_LDA(At, 1, 1); PG8_STAGE(PG8_SA(1, 0), a3, voffA);
;             PG8_BAR; PG8_WAIT_L(0); PG8_MMA(1, 0, At, B0); PG8_BAR; PG8_SCHED;
;             PG8_STAGE(PG8_SB(1, 1), b3 + hstepB, voffB);
;             PG8_WAIT_V(6); PG8_BAR; PG8_MMA(1, 1, At, B1); PG8_BAR;
;     __device__ __forceinline__ void operator()(const f32x4 (&acc)[2][2][4][2], const Unit& u, int wr, int wc, int fr, int fq) const {
;     ...
;             for (int m = 0; m < 4; ++m) { mu[m] = 0.f; rs[m] = 1.f;
;                 if (stats) { const float* sp = stats + (size_t)(row0 + ai * HALF + m * 16) * 2; mu[m] = sp[0]; rs[m] = sp[1]; } }
	s_waitcnt lgkmcnt(0)
	s_waitcnt lgkmcnt(0)
	v_mfma_f32_16x16x32_bf16 v[94:97], v[178:181], v[146:149], v[94:97]
	v_mfma_f32_16x16x32_bf16 v[78:81], v[192:195], v[146:149], v[78:81]
	v_mfma_f32_16x16x32_bf16 v[90:93], v[178:181], v[154:157], v[90:93]
	v_mfma_f32_16x16x32_bf16 v[74:77], v[192:195], v[154:157], v[74:77]
	v_mfma_f32_16x16x32_bf16 v[86:89], v[178:181], v[162:165], v[86:89]
	v_mfma_f32_16x16x32_bf16 v[70:73], v[192:195], v[162:165], v[70:73]
	v_mfma_f32_16x16x32_bf16 v[82:85], v[178:181], v[170:173], v[82:85]
	v_mfma_f32_16x16x32_bf16 v[66:69], v[192:195], v[170:173], v[66:69]
	v_mfma_f32_16x16x32_bf16 v[94:97], v[182:185], v[150:153], v[94:97]
	v_mfma_f32_16x16x32_bf16 v[78:81], v[204:207], v[150:153], v[78:81]
	v_mfma_f32_16x16x32_bf16 v[90:93], v[182:185], v[158:161], v[90:93]
	v_mfma_f32_16x16x32_bf16 v[74:77], v[204:207], v[158:161], v[74:77]
	v_mfma_f32_16x16x32_bf16 v[86:89], v[182:185], v[166:169], v[86:89]
	v_mfma_f32_16x16x32_bf16 v[70:73], v[204:207], v[166:169], v[70:73]
	v_mfma_f32_16x16x32_bf16 v[82:85], v[182:185], v[174:177], v[82:85]
	v_mfma_f32_16x16x32_bf16 v[66:69], v[204:207], v[174:177], v[66:69]
	s_mov_b32 m0, s46
	v_lshl_add_u64 v[186:187], v[210:211], 0, s[86:87]
	s_barrier
	ds_read_b128 v[146:149], v252 offset:49152
	ds_read_b128 v[150:153], v252 offset:50176
	ds_read_b128 v[154:157], v252 offset:51200
	ds_read_b128 v[158:161], v252 offset:52224
	ds_read_b128 v[162:165], v252 offset:53248
	ds_read_b128 v[166:169], v252 offset:54272
	ds_read_b128 v[170:173], v252 offset:55296
	ds_read_b128 v[174:177], v252 offset:56320
	global_load_lds_dwordx4 v[186:187], off
	v_lshl_add_u64 v[186:187], v[212:213], 0, s[86:87]
	s_mov_b32 m0, s47
	s_nop 0
	global_load_lds_dwordx4 v[186:187], off
	s_barrier
	s_waitcnt lgkmcnt(0)
	s_waitcnt lgkmcnt(0)
	v_mfma_f32_16x16x32_bf16 v[62:65], v[130:133], v[146:149], v[62:65]
	v_mfma_f32_16x16x32_bf16 v[46:49], v[138:141], v[146:149], v[46:49]
	v_mfma_f32_16x16x32_bf16 v[58:61], v[130:133], v[154:157], v[58:61]
	v_mfma_f32_16x16x32_bf16 v[42:45], v[138:141], v[154:157], v[42:45]
	v_mfma_f32_16x16x32_bf16 v[54:57], v[130:133], v[162:165], v[54:57]
	v_mfma_f32_16x16x32_bf16 v[38:41], v[138:141], v[162:165], v[38:41]
	v_mfma_f32_16x16x32_bf16 v[50:53], v[130:133], v[170:173], v[50:53]
	v_mfma_f32_16x16x32_bf16 v[34:37], v[138:141], v[170:173], v[34:37]
	v_mfma_f32_16x16x32_bf16 v[62:65], v[134:137], v[150:153], v[62:65]
	v_mfma_f32_16x16x32_bf16 v[46:49], v[142:145], v[150:153], v[46:49]
	v_mfma_f32_16x16x32_bf16 v[58:61], v[134:137], v[158:161], v[58:61]
	v_mfma_f32_16x16x32_bf16 v[42:45], v[142:145], v[158:161], v[42:45]
	v_mfma_f32_16x16x32_bf16 v[54:57], v[134:137], v[166:169], v[54:57]
	v_mfma_f32_16x16x32_bf16 v[38:41], v[142:145], v[166:169], v[38:41]
	v_mfma_f32_16x16x32_bf16 v[50:53], v[134:137], v[174:177], v[50:53]
	v_mfma_f32_16x16x32_bf16 v[34:37], v[142:145], v[174:177], v[34:37]
	s_barrier
	s_add_u32 s24, s26, 0x160080
	s_addc_u32 s25, s27, 0
	s_add_i32 s26, s28, s34
	v_lshl_add_u64 v[130:131], s[24:25], 0, v[196:197]
	s_mov_b32 m0, s26
	s_nop 0
	global_load_lds_dwordx4 v[130:131], off
	v_lshl_add_u64 v[130:131], s[24:25], 0, v[198:199]
	s_add_i32 m0, s26, 0x2000
	s_nop 0
	global_load_lds_dwordx4 v[130:131], off
	s_waitcnt vmcnt(6)
	s_barrier
	v_mfma_f32_16x16x32_bf16 v[30:33], v[178:181], v[146:149], v[30:33]
	v_mfma_f32_16x16x32_bf16 v[14:17], v[192:195], v[146:149], v[14:17]
	v_mfma_f32_16x16x32_bf16 v[26:29], v[178:181], v[154:157], v[26:29]
	v_mfma_f32_16x16x32_bf16 v[10:13], v[192:195], v[154:157], v[10:13]
	v_mfma_f32_16x16x32_bf16 v[22:25], v[178:181], v[162:165], v[22:25]
	v_mfma_f32_16x16x32_bf16 v[6:9], v[192:195], v[162:165], v[6:9]
	v_mfma_f32_16x16x32_bf16 v[18:21], v[178:181], v[170:173], v[18:21]
	v_mfma_f32_16x16x32_bf16 v[2:5], v[192:195], v[170:173], v[2:5]
	v_mfma_f32_16x16x32_bf16 v[30:33], v[182:185], v[150:153], v[30:33]
	v_mfma_f32_16x16x32_bf16 v[14:17], v[204:207], v[150:153], v[14:17]
	v_mfma_f32_16x16x32_bf16 v[26:29], v[182:185], v[158:161], v[26:29]
	v_mfma_f32_16x16x32_bf16 v[10:13], v[204:207], v[158:161], v[10:13]
	v_mfma_f32_16x16x32_bf16 v[22:25], v[182:185], v[166:169], v[22:25]
	v_mfma_f32_16x16x32_bf16 v[6:9], v[204:207], v[166:169], v[6:9]
	v_mfma_f32_16x16x32_bf16 v[18:21], v[182:185], v[174:177], v[18:21]
	v_mfma_f32_16x16x32_bf16 v[2:5], v[204:207], v[174:177], v[2:5]
	s_add_i32 s67, s67, 2
	s_add_u32 s65, s65, 0x100
	s_addc_u32 s66, s66, 0
	s_cmpk_gt_u32 s67, 0x55
	s_mov_b64 s[24:25], s[2:3]
	s_barrier
	s_cbranch_scc0 .LBB0_674
	v_lshl_add_u32 v212, s62, 8, v249
	v_cndmask_b32_e64 v1, 0, 1, s[20:21]
	v_mov_b32_e32 v216, 1.0
	v_cmp_ne_u32_e64 s[2:3], 1, v1
	s_andn2_b64 vcc, exec, s[20:21]
	v_ashrrev_i32_e32 v213, 31, v212
	s_cbranch_vccnz .LBB0_677
	v_lshl_add_u64 v[130:131], v[212:213], 3, s[18:19]
	global_load_dwordx2 v[134:135], v[130:131], off
	s_branch .LBB0_678

; __device__ __forceinline__ int otid(int wv) { int t = (wv << 6) | (int)__builtin_amdgcn_mbcnt_hi(~0u, __builtin_amdgcn_mbcnt_lo(~0u, 0u)); asm volatile("" : "+v"(t)); return t; }
; __device__ __forceinline__ void grid_bar(unsigned* ctr, unsigned& target, int G, int wv) {
;     asm volatile("s_waitcnt vmcnt(0) lgkmcnt(0)" ::: "memory");
;     __syncthreads();
;     target = (unsigned)__builtin_amdgcn_readfirstlane((int)(target + (unsigned)G));
;     if (otid(wv) == 0) {
;         __builtin_amdgcn_fence(__ATOMIC_RELEASE, "agent");
;         asm volatile("s_waitcnt vmcnt(0)" ::: "memory");
;         __hip_atomic_fetch_add(ctr, 1u, __ATOMIC_RELAXED, __HIP_MEMORY_SCOPE_AGENT);
;         while (__hip_atomic_load(ctr, __ATOMIC_RELAXED, __HIP_MEMORY_SCOPE_AGENT) < target) __builtin_amdgcn_s_sleep(1);
;         __builtin_amdgcn_fence(__ATOMIC_ACQUIRE, "agent");
;         asm volatile("s_waitcnt vmcnt(0)" ::: "memory");
;     }
;     __syncthreads();
; }
.LBB0_713:
	s_setprio 0
	s_waitcnt vmcnt(0) lgkmcnt(0)
	v_mov_b32_e32 v1, v236
	s_waitcnt lgkmcnt(0)
	s_barrier
	s_add_i32 s22, s10, s33
	s_nop 0
	v_cmp_eq_u32_e32 vcc, 0, v1
	s_and_saveexec_b64 s[0:1], vcc
	s_cbranch_execz .LBB0_719
	s_mov_b64 s[2:3], exec
	buffer_wbl2 sc1
	s_waitcnt vmcnt(0)
	s_waitcnt vmcnt(0)
	v_mbcnt_lo_u32_b32 v1, s2, 0
	v_mbcnt_hi_u32_b32 v1, s3, v1
	v_cmp_eq_u32_e32 vcc, 0, v1
	s_and_saveexec_b64 s[4:5], vcc
	s_cbranch_execz .LBB0_716
	s_bcnt1_i32_b64 s2, s[2:3]
	v_mov_b32_e32 v1, s2
	v_readlane_b32 s2, v254, 30
	v_readlane_b32 s3, v254, 31
	s_nop 4
	global_atomic_add v0, v1, s[2:3]

; __device__ __forceinline__ int otid(int wv) { int t = (wv << 6) | (int)__builtin_amdgcn_mbcnt_hi(~0u, __builtin_amdgcn_mbcnt_lo(~0u, 0u)); asm volatile("" : "+v"(t)); return t; }
; #define SEAM() do { if (ph == 0) { asm volatile("s_waitcnt vmcnt(0) lgkmcnt(0)" ::: "memory"); grid.sync(); } else grid_bar(bar_ctr, bar_target, G, wv); } while (0)
; #define SEAM() do { } while (0)
; __device__ __forceinline__ void grid_bar(unsigned* ctr, unsigned& target, int G, int wv) {
;     asm volatile("s_waitcnt vmcnt(0) lgkmcnt(0)" ::: "memory");
;     __syncthreads();
;     target = (unsigned)__builtin_amdgcn_readfirstlane((int)(target + (unsigned)G));
;     if (otid(wv) == 0) {
;         __builtin_amdgcn_fence(__ATOMIC_RELEASE, "agent");
;         asm volatile("s_waitcnt vmcnt(0)" ::: "memory");
;         __hip_atomic_fetch_add(ctr, 1u, __ATOMIC_RELAXED, __HIP_MEMORY_SCOPE_AGENT);
;         while (__hip_atomic_load(ctr, __ATOMIC_RELAXED, __HIP_MEMORY_SCOPE_AGENT) < target) __builtin_amdgcn_s_sleep(1);
;         __builtin_amdgcn_fence(__ATOMIC_ACQUIRE, "agent");
;         asm volatile("s_waitcnt vmcnt(0)" ::: "memory");
;     }
;     __syncthreads();
; }
; __global__ void __launch_bounds__(NTHR, 2) fwd_kernel(Params p) {
;     ...
;         if (l + 1 < DEPTH) SEAM();
.LBB0_887:
	v_readlane_b32 s0, v255, 25
	v_readlane_b32 s1, v255, 26
	s_andn2_b64 vcc, exec, s[0:1]
	s_cbranch_vccnz .LBB0_186
	s_setprio 0
	s_waitcnt vmcnt(0) lgkmcnt(0)
	v_mov_b32_e32 v1, v236
	s_barrier
	s_add_i32 s22, s22, s33
	s_nop 0
	v_cmp_eq_u32_e32 vcc, 0, v1
	s_and_saveexec_b64 s[0:1], vcc
	s_cbranch_execz .LBB0_185
	s_mov_b64 s[2:3], exec
	buffer_wbl2 sc1
	s_waitcnt vmcnt(0)
	s_waitcnt vmcnt(0)
	v_mbcnt_lo_u32_b32 v1, s2, 0
	v_mbcnt_hi_u32_b32 v1, s3, v1
	v_cmp_eq_u32_e32 vcc, 0, v1
	s_and_saveexec_b64 s[4:5], vcc
	s_cbranch_execz .LBB0_891
	s_bcnt1_i32_b64 s2, s[2:3]
	v_mov_b32_e32 v1, s2
	v_readlane_b32 s2, v254, 30
	v_readlane_b32 s3, v254, 31
	s_nop 4
	global_atomic_add v0, v1, s[2:3]
